# all GEMM epilogues: wave halves re-aligned (extra barrier for wr=0 at epilogue entry, for wr=1 at exit) so both halves run their epilogue concurrently
# speedup vs baseline: 1.0836x; 1.0072x over previous
.LBB0_295:
	v_readfirstlane_b32 s98, v191
	s_cmpk_lt_u32 s98, 0x100
	s_cbranch_scc1 .Lrl_e1_307
	s_barrier

.LBB0_307:
	v_add_u32_e32 v142, s63, v242
	ds_read_b128 v[130:133], v142
	ds_read_b128 v[134:137], v142 offset:1024
	ds_read_b128 v[138:141], v142 offset:2048
	ds_read_b128 v[142:145], v142 offset:3072
	s_add_i32 s19, s18, 2
	s_add_u32 s20, s14, 0x100
	s_addc_u32 s21, s15, 0
	s_cmp_eq_u32 s24, s18
	s_cselect_b32 s45, s67, s21
	s_cselect_b32 s44, s66, s20
	s_cselect_b32 s35, s71, s26
	s_cselect_b32 s34, s70, s25
	v_lshl_add_u64 v[178:179], s[14:15], 0, v[210:211]
	s_add_i32 m0, s75, 0xc000
	ds_read_b128 v[146:149], v247
	ds_read_b128 v[150:153], v247 offset:1024
	ds_read_b128 v[154:157], v247 offset:2048
	ds_read_b128 v[158:161], v247 offset:3072
	ds_read_b128 v[162:165], v247 offset:4096
	ds_read_b128 v[166:169], v247 offset:5120
	ds_read_b128 v[170:173], v247 offset:6144
	ds_read_b128 v[174:177], v247 offset:7168
	global_load_lds_dwordx4 v[178:179], off
	v_lshl_add_u64 v[178:179], s[14:15], 0, v[212:213]
	s_add_i32 m0, s75, 0xe000
	s_nop 0
	global_load_lds_dwordx4 v[178:179], off
	s_waitcnt lgkmcnt(8)
	s_barrier
	s_waitcnt lgkmcnt(0)
	s_setprio 1
	s_waitcnt lgkmcnt(0)
	v_mfma_f32_16x16x32_bf16 v[126:129], v[130:133], v[146:149], v[126:129]
	v_mfma_f32_16x16x32_bf16 v[122:125], v[138:141], v[146:149], v[122:125]
	v_mfma_f32_16x16x32_bf16 v[118:121], v[130:133], v[154:157], v[118:121]
	v_mfma_f32_16x16x32_bf16 v[114:117], v[138:141], v[154:157], v[114:117]
	v_mfma_f32_16x16x32_bf16 v[110:113], v[130:133], v[162:165], v[110:113]
	v_mfma_f32_16x16x32_bf16 v[106:109], v[138:141], v[162:165], v[106:109]
	v_mfma_f32_16x16x32_bf16 v[102:105], v[130:133], v[170:173], v[102:105]
	v_mfma_f32_16x16x32_bf16 v[98:101], v[138:141], v[170:173], v[98:101]
	v_mfma_f32_16x16x32_bf16 v[126:129], v[134:137], v[150:153], v[126:129]
	v_mfma_f32_16x16x32_bf16 v[122:125], v[142:145], v[150:153], v[122:125]
	v_mfma_f32_16x16x32_bf16 v[118:121], v[134:137], v[158:161], v[118:121]
	v_mfma_f32_16x16x32_bf16 v[114:117], v[142:145], v[158:161], v[114:117]
	v_mfma_f32_16x16x32_bf16 v[110:113], v[134:137], v[166:169], v[110:113]
	v_mfma_f32_16x16x32_bf16 v[106:109], v[142:145], v[166:169], v[106:109]
	v_mfma_f32_16x16x32_bf16 v[102:105], v[134:137], v[174:177], v[102:105]
	v_mfma_f32_16x16x32_bf16 v[98:101], v[142:145], v[174:177], v[98:101]
	s_setprio 0
	s_barrier
	s_mov_b32 m0, s73
	v_add_u32_e32 v194, s77, v242
	v_lshl_add_u64 v[214:215], s[34:35], 0, v[0:1]
	ds_read_b128 v[178:181], v194
	ds_read_b128 v[182:185], v194 offset:1024
	ds_read_b128 v[186:189], v194 offset:2048
	ds_read_b128 v[194:197], v194 offset:3072
	global_load_lds_dwordx4 v[214:215], off
	v_lshl_add_u64 v[216:217], s[34:35], 0, v[204:205]
	s_mov_b32 m0, s74
	s_nop 0
	global_load_lds_dwordx4 v[216:217], off
	s_barrier
	s_waitcnt lgkmcnt(0)
	s_setprio 1
	s_waitcnt lgkmcnt(0)
	v_mfma_f32_16x16x32_bf16 v[94:97], v[178:181], v[146:149], v[94:97]
	v_mfma_f32_16x16x32_bf16 v[90:93], v[186:189], v[146:149], v[90:93]
	v_mfma_f32_16x16x32_bf16 v[86:89], v[178:181], v[154:157], v[86:89]
	v_mfma_f32_16x16x32_bf16 v[82:85], v[186:189], v[154:157], v[82:85]
	v_mfma_f32_16x16x32_bf16 v[78:81], v[178:181], v[162:165], v[78:81]
	v_mfma_f32_16x16x32_bf16 v[74:77], v[186:189], v[162:165], v[74:77]
	v_mfma_f32_16x16x32_bf16 v[70:73], v[178:181], v[170:173], v[70:73]
	v_mfma_f32_16x16x32_bf16 v[66:69], v[186:189], v[170:173], v[66:69]
	v_mfma_f32_16x16x32_bf16 v[94:97], v[182:185], v[150:153], v[94:97]
	v_mfma_f32_16x16x32_bf16 v[90:93], v[194:197], v[150:153], v[90:93]
	v_mfma_f32_16x16x32_bf16 v[86:89], v[182:185], v[158:161], v[86:89]
	v_mfma_f32_16x16x32_bf16 v[82:85], v[194:197], v[158:161], v[82:85]
	v_mfma_f32_16x16x32_bf16 v[78:81], v[182:185], v[166:169], v[78:81]
	v_mfma_f32_16x16x32_bf16 v[74:77], v[194:197], v[166:169], v[74:77]
	v_mfma_f32_16x16x32_bf16 v[70:73], v[182:185], v[174:177], v[70:73]
	v_mfma_f32_16x16x32_bf16 v[66:69], v[194:197], v[174:177], v[66:69]
	s_setprio 0
	s_mov_b32 m0, s75
	v_lshl_add_u64 v[218:219], s[44:45], 0, v[0:1]
	s_barrier
	ds_read_b128 v[146:149], v247 offset:16384
	ds_read_b128 v[150:153], v247 offset:17408
	ds_read_b128 v[154:157], v247 offset:18432
	ds_read_b128 v[158:161], v247 offset:19456
	ds_read_b128 v[162:165], v247 offset:20480
	ds_read_b128 v[166:169], v247 offset:21504
	ds_read_b128 v[170:173], v247 offset:22528
	ds_read_b128 v[174:177], v247 offset:23552
	global_load_lds_dwordx4 v[218:219], off
	v_lshl_add_u64 v[220:221], s[44:45], 0, v[204:205]
	s_mov_b32 m0, s76
	s_nop 0
	global_load_lds_dwordx4 v[220:221], off
	s_barrier
	s_waitcnt lgkmcnt(0)
	s_setprio 1
	s_waitcnt lgkmcnt(0)
	v_mfma_f32_16x16x32_bf16 v[62:65], v[130:133], v[146:149], v[62:65]
	v_mfma_f32_16x16x32_bf16 v[58:61], v[138:141], v[146:149], v[58:61]
	v_mfma_f32_16x16x32_bf16 v[54:57], v[130:133], v[154:157], v[54:57]
	v_mfma_f32_16x16x32_bf16 v[50:53], v[138:141], v[154:157], v[50:53]
	v_mfma_f32_16x16x32_bf16 v[46:49], v[130:133], v[162:165], v[46:49]
	v_mfma_f32_16x16x32_bf16 v[42:45], v[138:141], v[162:165], v[42:45]
	v_mfma_f32_16x16x32_bf16 v[38:41], v[130:133], v[170:173], v[38:41]
	v_mfma_f32_16x16x32_bf16 v[34:37], v[138:141], v[170:173], v[34:37]
	v_mfma_f32_16x16x32_bf16 v[62:65], v[134:137], v[150:153], v[62:65]
	v_mfma_f32_16x16x32_bf16 v[58:61], v[142:145], v[150:153], v[58:61]
	v_mfma_f32_16x16x32_bf16 v[54:57], v[134:137], v[158:161], v[54:57]
	v_mfma_f32_16x16x32_bf16 v[50:53], v[142:145], v[158:161], v[50:53]
	v_mfma_f32_16x16x32_bf16 v[46:49], v[134:137], v[166:169], v[46:49]
	v_mfma_f32_16x16x32_bf16 v[42:45], v[142:145], v[166:169], v[42:45]
	v_mfma_f32_16x16x32_bf16 v[38:41], v[134:137], v[174:177], v[38:41]
	v_mfma_f32_16x16x32_bf16 v[34:37], v[142:145], v[174:177], v[34:37]
	s_setprio 0
	s_barrier
	s_add_u32 s0, s34, 0xb0000
	s_addc_u32 s1, s35, 0
	s_mov_b32 m0, s78
	v_lshl_add_u64 v[130:131], s[0:1], 0, v[0:1]
	global_load_lds_dwordx4 v[130:131], off
	v_lshl_add_u64 v[130:131], s[0:1], 0, v[204:205]
	s_mov_b32 m0, s79
	s_nop 0
	global_load_lds_dwordx4 v[130:131], off
	s_waitcnt vmcnt(6)
	s_barrier
	s_setprio 1
	v_mfma_f32_16x16x32_bf16 v[30:33], v[178:181], v[146:149], v[30:33]
	v_mfma_f32_16x16x32_bf16 v[26:29], v[186:189], v[146:149], v[26:29]
	v_mfma_f32_16x16x32_bf16 v[22:25], v[178:181], v[154:157], v[22:25]
	v_mfma_f32_16x16x32_bf16 v[18:21], v[186:189], v[154:157], v[18:21]
	v_mfma_f32_16x16x32_bf16 v[14:17], v[178:181], v[162:165], v[14:17]
	v_mfma_f32_16x16x32_bf16 v[10:13], v[186:189], v[162:165], v[10:13]
	v_mfma_f32_16x16x32_bf16 v[6:9], v[178:181], v[170:173], v[6:9]
	v_mfma_f32_16x16x32_bf16 v[2:5], v[186:189], v[170:173], v[2:5]
	v_mfma_f32_16x16x32_bf16 v[30:33], v[182:185], v[150:153], v[30:33]
	v_mfma_f32_16x16x32_bf16 v[26:29], v[194:197], v[150:153], v[26:29]
	v_mfma_f32_16x16x32_bf16 v[22:25], v[182:185], v[158:161], v[22:25]
	v_mfma_f32_16x16x32_bf16 v[18:21], v[194:197], v[158:161], v[18:21]
	v_mfma_f32_16x16x32_bf16 v[14:17], v[182:185], v[166:169], v[14:17]
	v_mfma_f32_16x16x32_bf16 v[10:13], v[194:197], v[166:169], v[10:13]
	v_mfma_f32_16x16x32_bf16 v[6:9], v[182:185], v[174:177], v[6:9]
	v_mfma_f32_16x16x32_bf16 v[2:5], v[194:197], v[174:177], v[2:5]
	s_setprio 0
	v_add_u32_e32 v142, s94, v242
	s_barrier
	ds_read_b128 v[130:133], v142
	ds_read_b128 v[134:137], v142 offset:1024
	ds_read_b128 v[138:141], v142 offset:2048
	ds_read_b128 v[142:145], v142 offset:3072
	s_add_u32 s0, s44, 0xb0000
	s_addc_u32 s1, s45, 0
	s_mov_b32 m0, s80
	v_lshl_add_u64 v[178:179], s[0:1], 0, v[0:1]
	ds_read_b128 v[146:149], v247 offset:32768
	ds_read_b128 v[150:153], v247 offset:33792
	ds_read_b128 v[154:157], v247 offset:34816
	ds_read_b128 v[158:161], v247 offset:35840
	ds_read_b128 v[162:165], v247 offset:36864
	ds_read_b128 v[166:169], v247 offset:37888
	ds_read_b128 v[170:173], v247 offset:38912
	ds_read_b128 v[174:177], v247 offset:39936
	global_load_lds_dwordx4 v[178:179], off
	v_lshl_add_u64 v[178:179], s[0:1], 0, v[204:205]
	s_mov_b32 m0, s81
	s_nop 0
	global_load_lds_dwordx4 v[178:179], off
	s_waitcnt lgkmcnt(8)
	s_barrier
	s_waitcnt lgkmcnt(0)
	s_setprio 1
	s_waitcnt lgkmcnt(0)
	v_mfma_f32_16x16x32_bf16 v[126:129], v[130:133], v[146:149], v[126:129]
	v_mfma_f32_16x16x32_bf16 v[122:125], v[138:141], v[146:149], v[122:125]
	v_mfma_f32_16x16x32_bf16 v[118:121], v[130:133], v[154:157], v[118:121]
	v_mfma_f32_16x16x32_bf16 v[114:117], v[138:141], v[154:157], v[114:117]
	v_mfma_f32_16x16x32_bf16 v[110:113], v[130:133], v[162:165], v[110:113]
	v_mfma_f32_16x16x32_bf16 v[106:109], v[138:141], v[162:165], v[106:109]
	v_mfma_f32_16x16x32_bf16 v[102:105], v[130:133], v[170:173], v[102:105]
	v_mfma_f32_16x16x32_bf16 v[98:101], v[138:141], v[170:173], v[98:101]
	v_mfma_f32_16x16x32_bf16 v[126:129], v[134:137], v[150:153], v[126:129]
	v_mfma_f32_16x16x32_bf16 v[122:125], v[142:145], v[150:153], v[122:125]
	v_mfma_f32_16x16x32_bf16 v[118:121], v[134:137], v[158:161], v[118:121]
	v_mfma_f32_16x16x32_bf16 v[114:117], v[142:145], v[158:161], v[114:117]
	v_mfma_f32_16x16x32_bf16 v[110:113], v[134:137], v[166:169], v[110:113]
	v_mfma_f32_16x16x32_bf16 v[106:109], v[142:145], v[166:169], v[106:109]
	v_mfma_f32_16x16x32_bf16 v[102:105], v[134:137], v[174:177], v[102:105]
	v_mfma_f32_16x16x32_bf16 v[98:101], v[142:145], v[174:177], v[98:101]
	s_setprio 0
	s_barrier
	s_mov_b32 m0, s95
	v_add_u32_e32 v194, s37, v242
	v_lshl_add_u64 v[214:215], v[214:215], 0, s[88:89]
	ds_read_b128 v[178:181], v194
	ds_read_b128 v[182:185], v194 offset:1024
	ds_read_b128 v[186:189], v194 offset:2048
	ds_read_b128 v[194:197], v194 offset:3072
	global_load_lds_dwordx4 v[214:215], off
	v_lshl_add_u64 v[214:215], v[216:217], 0, s[88:89]
	s_mov_b32 m0, s16
	s_nop 0
	global_load_lds_dwordx4 v[214:215], off
	s_barrier
	s_waitcnt lgkmcnt(0)
	s_setprio 1
	s_waitcnt lgkmcnt(0)
	v_mfma_f32_16x16x32_bf16 v[94:97], v[178:181], v[146:149], v[94:97]
	v_mfma_f32_16x16x32_bf16 v[90:93], v[186:189], v[146:149], v[90:93]
	v_mfma_f32_16x16x32_bf16 v[86:89], v[178:181], v[154:157], v[86:89]
	v_mfma_f32_16x16x32_bf16 v[82:85], v[186:189], v[154:157], v[82:85]
	v_mfma_f32_16x16x32_bf16 v[78:81], v[178:181], v[162:165], v[78:81]
	v_mfma_f32_16x16x32_bf16 v[74:77], v[186:189], v[162:165], v[74:77]
	v_mfma_f32_16x16x32_bf16 v[70:73], v[178:181], v[170:173], v[70:73]
	v_mfma_f32_16x16x32_bf16 v[66:69], v[186:189], v[170:173], v[66:69]
	v_mfma_f32_16x16x32_bf16 v[94:97], v[182:185], v[150:153], v[94:97]
	v_mfma_f32_16x16x32_bf16 v[90:93], v[194:197], v[150:153], v[90:93]
	v_mfma_f32_16x16x32_bf16 v[86:89], v[182:185], v[158:161], v[86:89]
	v_mfma_f32_16x16x32_bf16 v[82:85], v[194:197], v[158:161], v[82:85]
	v_mfma_f32_16x16x32_bf16 v[78:81], v[182:185], v[166:169], v[78:81]
	v_mfma_f32_16x16x32_bf16 v[74:77], v[194:197], v[166:169], v[74:77]
	v_mfma_f32_16x16x32_bf16 v[70:73], v[182:185], v[174:177], v[70:73]
	v_mfma_f32_16x16x32_bf16 v[66:69], v[194:197], v[174:177], v[66:69]
	s_setprio 0
	s_mov_b32 m0, s17
	v_lshl_add_u64 v[214:215], v[218:219], 0, s[88:89]
	s_barrier
	ds_read_b128 v[146:149], v247 offset:49152
	ds_read_b128 v[150:153], v247 offset:50176
	ds_read_b128 v[154:157], v247 offset:51200
	ds_read_b128 v[158:161], v247 offset:52224
	ds_read_b128 v[162:165], v247 offset:53248
	ds_read_b128 v[166:169], v247 offset:54272
	ds_read_b128 v[170:173], v247 offset:55296
	ds_read_b128 v[174:177], v247 offset:56320
	global_load_lds_dwordx4 v[214:215], off
	v_lshl_add_u64 v[214:215], v[220:221], 0, s[88:89]
	s_mov_b32 m0, s60
	s_nop 0
	global_load_lds_dwordx4 v[214:215], off
	s_barrier
	s_waitcnt lgkmcnt(0)
	s_setprio 1
	s_waitcnt lgkmcnt(0)
	v_mfma_f32_16x16x32_bf16 v[62:65], v[130:133], v[146:149], v[62:65]
	v_mfma_f32_16x16x32_bf16 v[58:61], v[138:141], v[146:149], v[58:61]
	v_mfma_f32_16x16x32_bf16 v[54:57], v[130:133], v[154:157], v[54:57]
	v_mfma_f32_16x16x32_bf16 v[50:53], v[138:141], v[154:157], v[50:53]
	v_mfma_f32_16x16x32_bf16 v[46:49], v[130:133], v[162:165], v[46:49]
	v_mfma_f32_16x16x32_bf16 v[42:45], v[138:141], v[162:165], v[42:45]
	v_mfma_f32_16x16x32_bf16 v[38:41], v[130:133], v[170:173], v[38:41]
	v_mfma_f32_16x16x32_bf16 v[34:37], v[138:141], v[170:173], v[34:37]
	v_mfma_f32_16x16x32_bf16 v[62:65], v[134:137], v[150:153], v[62:65]
	v_mfma_f32_16x16x32_bf16 v[58:61], v[142:145], v[150:153], v[58:61]
	v_mfma_f32_16x16x32_bf16 v[54:57], v[134:137], v[158:161], v[54:57]
	v_mfma_f32_16x16x32_bf16 v[50:53], v[142:145], v[158:161], v[50:53]
	v_mfma_f32_16x16x32_bf16 v[46:49], v[134:137], v[166:169], v[46:49]
	v_mfma_f32_16x16x32_bf16 v[42:45], v[142:145], v[166:169], v[42:45]
	v_mfma_f32_16x16x32_bf16 v[38:41], v[134:137], v[174:177], v[38:41]
	v_mfma_f32_16x16x32_bf16 v[34:37], v[142:145], v[174:177], v[34:37]
	s_setprio 0
	s_barrier
	s_add_u32 s0, s34, 0xb0080
	s_addc_u32 s1, s35, 0
	s_mov_b32 m0, s2
	v_lshl_add_u64 v[130:131], s[0:1], 0, v[0:1]
	global_load_lds_dwordx4 v[130:131], off
	v_lshl_add_u64 v[130:131], s[0:1], 0, v[204:205]
	s_mov_b32 m0, s3
	s_nop 0
	global_load_lds_dwordx4 v[130:131], off
	s_waitcnt vmcnt(6)
	s_barrier
	s_setprio 1
	v_mfma_f32_16x16x32_bf16 v[30:33], v[178:181], v[146:149], v[30:33]
	v_mfma_f32_16x16x32_bf16 v[26:29], v[186:189], v[146:149], v[26:29]
	v_mfma_f32_16x16x32_bf16 v[22:25], v[178:181], v[154:157], v[22:25]
	v_mfma_f32_16x16x32_bf16 v[18:21], v[186:189], v[154:157], v[18:21]
	v_mfma_f32_16x16x32_bf16 v[14:17], v[178:181], v[162:165], v[14:17]
	v_mfma_f32_16x16x32_bf16 v[10:13], v[186:189], v[162:165], v[10:13]
	v_mfma_f32_16x16x32_bf16 v[6:9], v[178:181], v[170:173], v[6:9]
	v_mfma_f32_16x16x32_bf16 v[2:5], v[186:189], v[170:173], v[2:5]
	v_mfma_f32_16x16x32_bf16 v[30:33], v[182:185], v[150:153], v[30:33]
	v_mfma_f32_16x16x32_bf16 v[26:29], v[194:197], v[150:153], v[26:29]
	v_mfma_f32_16x16x32_bf16 v[22:25], v[182:185], v[158:161], v[22:25]
	v_mfma_f32_16x16x32_bf16 v[18:21], v[194:197], v[158:161], v[18:21]
	v_mfma_f32_16x16x32_bf16 v[14:17], v[182:185], v[166:169], v[14:17]
	v_mfma_f32_16x16x32_bf16 v[10:13], v[194:197], v[166:169], v[10:13]
	v_mfma_f32_16x16x32_bf16 v[6:9], v[182:185], v[174:177], v[6:9]
	v_mfma_f32_16x16x32_bf16 v[2:5], v[194:197], v[174:177], v[2:5]
	s_setprio 0
	s_add_u32 s25, s25, 0x100
	s_addc_u32 s26, s26, 0
	s_cmp_ge_i32 s19, s11
	s_mov_b64 s[14:15], s[20:21]
	s_mov_b32 s18, s19
	s_barrier
	s_cbranch_scc0 .LBB0_307
	v_readfirstlane_b32 s98, v191
	s_cmpk_gt_u32 s98, 0xff
	s_cbranch_scc1 .Lrl_e0_307
	s_barrier
.Lrl_e0_307:
	s_cmp_lg_u32 s10, 1
	s_mov_b64 s[14:15], -1
	s_cbranch_scc0 .LBB0_354
	s_cmp_eq_u32 s10, 2
	s_cselect_b64 s[14:15], -1, 0
	s_cmp_lg_u32 s10, 2
	s_cbranch_scc1 .LBB0_321
	s_lshl_b32 s0, s50, 3
	s_ashr_i32 s1, s0, 31
	s_lshl_b64 s[0:1], s[0:1], 2
	v_readlane_b32 s10, v254, 24
	s_add_u32 s20, s10, s0
	v_readlane_b32 s0, v254, 30
	s_addc_u32 s21, s0, s1
	s_mov_b32 s10, 0x400001
	s_branch .LBB0_312

.LBB0_780:
	v_add_u32_e32 v30, s15, v202
	ds_read_b128 v[18:21], v30
	ds_read_b128 v[22:25], v30 offset:1024
	ds_read_b128 v[26:29], v30 offset:2048
	ds_read_b128 v[30:33], v30 offset:3072
	s_add_u32 s0, s20, 0xfffc0080
	s_addc_u32 s1, s21, -1
	s_cmp_eq_u32 s28, 12
	s_cselect_b32 s51, s8, s1
	s_cselect_b32 s50, s10, s0
	s_cselect_b32 s35, s11, s26
	s_cselect_b32 s34, s24, s25
	v_lshl_add_u64 v[184:185], s[20:21], 0, v[180:181]
	s_add_i32 m0, s61, 0xc000
	ds_read_b128 v[34:37], v204
	ds_read_b128 v[38:41], v204 offset:1024
	ds_read_b128 v[58:61], v204 offset:2048
	ds_read_b128 v[62:65], v204 offset:3072
	ds_read_b128 v[66:69], v204 offset:4096
	ds_read_b128 v[70:73], v204 offset:5120
	ds_read_b128 v[74:77], v204 offset:6144
	ds_read_b128 v[78:81], v204 offset:7168
	global_load_lds_dwordx4 v[184:185], off
	v_lshl_add_u64 v[184:185], s[20:21], 0, v[182:183]
	s_add_i32 m0, s61, 0xe000
	s_nop 0
	global_load_lds_dwordx4 v[184:185], off
	s_waitcnt lgkmcnt(8)
	s_barrier
	s_waitcnt lgkmcnt(0)
	s_setprio 1
	s_waitcnt lgkmcnt(0)
	v_mfma_f32_16x16x32_bf16 v[174:177], v[18:21], v[34:37], v[174:177]
	v_mfma_f32_16x16x32_bf16 v[170:173], v[26:29], v[34:37], v[170:173]
	v_mfma_f32_16x16x32_bf16 v[158:161], v[18:21], v[58:61], v[158:161]
	v_mfma_f32_16x16x32_bf16 v[154:157], v[26:29], v[58:61], v[154:157]
	v_mfma_f32_16x16x32_bf16 v[142:145], v[18:21], v[66:69], v[142:145]
	v_mfma_f32_16x16x32_bf16 v[138:141], v[26:29], v[66:69], v[138:141]
	v_mfma_f32_16x16x32_bf16 v[126:129], v[18:21], v[74:77], v[126:129]
	v_mfma_f32_16x16x32_bf16 v[122:125], v[26:29], v[74:77], v[122:125]
	v_mfma_f32_16x16x32_bf16 v[174:177], v[22:25], v[38:41], v[174:177]
	v_mfma_f32_16x16x32_bf16 v[170:173], v[30:33], v[38:41], v[170:173]
	v_mfma_f32_16x16x32_bf16 v[158:161], v[22:25], v[62:65], v[158:161]
	v_mfma_f32_16x16x32_bf16 v[154:157], v[30:33], v[62:65], v[154:157]
	v_mfma_f32_16x16x32_bf16 v[142:145], v[22:25], v[70:73], v[142:145]
	v_mfma_f32_16x16x32_bf16 v[138:141], v[30:33], v[70:73], v[138:141]
	v_mfma_f32_16x16x32_bf16 v[126:129], v[22:25], v[78:81], v[126:129]
	v_mfma_f32_16x16x32_bf16 v[122:125], v[30:33], v[78:81], v[122:125]
	s_setprio 0
	s_barrier
	v_add_u32_e32 v188, s63, v202
	s_mov_b32 m0, s55
	ds_read_b128 v[184:187], v188
	ds_read_b128 v[206:209], v188 offset:1024
	ds_read_b128 v[210:213], v188 offset:2048
	ds_read_b128 v[214:217], v188 offset:3072
	v_lshl_add_u64 v[188:189], s[34:35], 0, v[0:1]
	global_load_lds_dwordx4 v[188:189], off
	v_lshl_add_u64 v[222:223], s[34:35], 0, v[178:179]
	s_mov_b32 m0, s60
	s_nop 0
	global_load_lds_dwordx4 v[222:223], off
	s_barrier
	s_waitcnt lgkmcnt(0)
	s_setprio 1
	s_waitcnt lgkmcnt(0)
	v_mfma_f32_16x16x32_bf16 v[166:169], v[184:187], v[34:37], v[166:169]
	v_mfma_f32_16x16x32_bf16 v[34:37], v[210:213], v[34:37], v[162:165]
	v_mfma_f32_16x16x32_bf16 v[166:169], v[206:209], v[38:41], v[166:169]
	v_mfma_f32_16x16x32_bf16 v[34:37], v[214:217], v[38:41], v[34:37]
	v_mfma_f32_16x16x32_bf16 v[38:41], v[184:187], v[58:61], v[150:153]
	v_mfma_f32_16x16x32_bf16 v[58:61], v[210:213], v[58:61], v[146:149]
	v_mfma_f32_16x16x32_bf16 v[38:41], v[206:209], v[62:65], v[38:41]
	v_mfma_f32_16x16x32_bf16 v[58:61], v[214:217], v[62:65], v[58:61]
	v_mfma_f32_16x16x32_bf16 v[62:65], v[184:187], v[66:69], v[134:137]
	v_mfma_f32_16x16x32_bf16 v[66:69], v[210:213], v[66:69], v[130:133]
	v_mfma_f32_16x16x32_bf16 v[62:65], v[206:209], v[70:73], v[62:65]
	v_mfma_f32_16x16x32_bf16 v[66:69], v[214:217], v[70:73], v[66:69]
	v_mfma_f32_16x16x32_bf16 v[70:73], v[184:187], v[74:77], v[118:121]
	v_mfma_f32_16x16x32_bf16 v[74:77], v[210:213], v[74:77], v[114:117]
	v_mfma_f32_16x16x32_bf16 v[70:73], v[206:209], v[78:81], v[70:73]
	v_mfma_f32_16x16x32_bf16 v[74:77], v[214:217], v[78:81], v[74:77]
	s_setprio 0
	s_mov_b32 m0, s61
	v_lshl_add_u64 v[250:251], s[50:51], 0, v[0:1]
	s_barrier
	ds_read_b128 v[78:81], v204 offset:16384
	ds_read_b128 v[114:117], v204 offset:17408
	ds_read_b128 v[118:121], v204 offset:18432
	ds_read_b128 v[130:133], v204 offset:19456
	ds_read_b128 v[134:137], v204 offset:20480
	ds_read_b128 v[146:149], v204 offset:21504
	ds_read_b128 v[150:153], v204 offset:22528
	ds_read_b128 v[162:165], v204 offset:23552
	global_load_lds_dwordx4 v[250:251], off
	v_lshl_add_u64 v[232:233], s[50:51], 0, v[178:179]
	s_mov_b32 m0, s62
	s_nop 0
	global_load_lds_dwordx4 v[232:233], off
	s_barrier
	s_waitcnt lgkmcnt(0)
	s_setprio 1
	s_waitcnt lgkmcnt(0)
	v_mfma_f32_16x16x32_bf16 v[110:113], v[18:21], v[78:81], v[110:113]
	v_mfma_f32_16x16x32_bf16 v[106:109], v[26:29], v[78:81], v[106:109]
	v_mfma_f32_16x16x32_bf16 v[94:97], v[18:21], v[118:121], v[94:97]
	v_mfma_f32_16x16x32_bf16 v[90:93], v[26:29], v[118:121], v[90:93]
	v_mfma_f32_16x16x32_bf16 v[54:57], v[18:21], v[134:137], v[54:57]
	v_mfma_f32_16x16x32_bf16 v[50:53], v[26:29], v[134:137], v[50:53]
	v_mfma_f32_16x16x32_bf16 v[14:17], v[18:21], v[150:153], v[14:17]
	v_mfma_f32_16x16x32_bf16 v[10:13], v[26:29], v[150:153], v[10:13]
	v_mfma_f32_16x16x32_bf16 v[110:113], v[22:25], v[114:117], v[110:113]
	v_mfma_f32_16x16x32_bf16 v[106:109], v[30:33], v[114:117], v[106:109]
	v_mfma_f32_16x16x32_bf16 v[94:97], v[22:25], v[130:133], v[94:97]
	v_mfma_f32_16x16x32_bf16 v[90:93], v[30:33], v[130:133], v[90:93]
	v_mfma_f32_16x16x32_bf16 v[54:57], v[22:25], v[146:149], v[54:57]
	v_mfma_f32_16x16x32_bf16 v[50:53], v[30:33], v[146:149], v[50:53]
	v_mfma_f32_16x16x32_bf16 v[14:17], v[22:25], v[162:165], v[14:17]
	v_mfma_f32_16x16x32_bf16 v[10:13], v[30:33], v[162:165], v[10:13]
	s_setprio 0
	s_barrier
	s_add_u32 s0, s34, 0x40000
	s_addc_u32 s1, s35, 0
	s_mov_b32 m0, s66
	v_lshl_add_u64 v[18:19], s[0:1], 0, v[0:1]
	global_load_lds_dwordx4 v[18:19], off
	v_lshl_add_u64 v[18:19], s[0:1], 0, v[178:179]
	s_mov_b32 m0, s67
	s_nop 0
	global_load_lds_dwordx4 v[18:19], off
	s_waitcnt vmcnt(6)
	s_barrier
	s_setprio 1
	v_mfma_f32_16x16x32_bf16 v[46:49], v[184:187], v[134:137], v[46:49]
	v_mfma_f32_16x16x32_bf16 v[42:45], v[210:213], v[134:137], v[42:45]
	v_mfma_f32_16x16x32_bf16 v[6:9], v[184:187], v[150:153], v[6:9]
	v_mfma_f32_16x16x32_bf16 v[2:5], v[210:213], v[150:153], v[2:5]
	v_mfma_f32_16x16x32_bf16 v[18:21], v[184:187], v[78:81], v[102:105]
	v_mfma_f32_16x16x32_bf16 v[22:25], v[210:213], v[78:81], v[98:101]
	v_mfma_f32_16x16x32_bf16 v[26:29], v[184:187], v[118:121], v[86:89]
	v_mfma_f32_16x16x32_bf16 v[30:33], v[210:213], v[118:121], v[82:85]
	v_mfma_f32_16x16x32_bf16 v[46:49], v[206:209], v[146:149], v[46:49]
	v_mfma_f32_16x16x32_bf16 v[42:45], v[214:217], v[146:149], v[42:45]
	v_mfma_f32_16x16x32_bf16 v[6:9], v[206:209], v[162:165], v[6:9]
	v_mfma_f32_16x16x32_bf16 v[2:5], v[214:217], v[162:165], v[2:5]
	v_mfma_f32_16x16x32_bf16 v[18:21], v[206:209], v[114:117], v[18:21]
	v_mfma_f32_16x16x32_bf16 v[22:25], v[214:217], v[114:117], v[22:25]
	v_mfma_f32_16x16x32_bf16 v[26:29], v[206:209], v[130:133], v[26:29]
	v_mfma_f32_16x16x32_bf16 v[30:33], v[214:217], v[130:133], v[30:33]
	s_setprio 0
	v_add_u32_e32 v98, s72, v202
	s_barrier
	ds_read_b128 v[78:81], v98
	ds_read_b128 v[82:85], v98 offset:1024
	ds_read_b128 v[86:89], v98 offset:2048
	ds_read_b128 v[98:101], v98 offset:3072
	s_add_u32 s0, s50, 0x40000
	s_addc_u32 s1, s51, 0
	s_mov_b32 m0, s68
	v_lshl_add_u64 v[134:135], s[0:1], 0, v[0:1]
	ds_read_b128 v[102:105], v204 offset:32768
	ds_read_b128 v[114:117], v204 offset:33792
	ds_read_b128 v[118:121], v204 offset:34816
	ds_read_b128 v[130:133], v204 offset:35840
	ds_read_b128 v[184:187], v204 offset:36864
	ds_read_b128 v[206:209], v204 offset:37888
	ds_read_b128 v[210:213], v204 offset:38912
	ds_read_b128 v[214:217], v204 offset:39936
	global_load_lds_dwordx4 v[134:135], off
	v_lshl_add_u64 v[134:135], s[0:1], 0, v[178:179]
	s_mov_b32 m0, s69
	s_nop 0
	global_load_lds_dwordx4 v[134:135], off
	s_waitcnt lgkmcnt(8)
	s_barrier
	s_waitcnt lgkmcnt(0)
	s_setprio 1
	s_waitcnt lgkmcnt(0)
	v_mfma_f32_16x16x32_bf16 v[134:137], v[78:81], v[102:105], v[174:177]
	v_mfma_f32_16x16x32_bf16 v[174:177], v[82:85], v[114:117], v[134:137]
	v_mfma_f32_16x16x32_bf16 v[134:137], v[86:89], v[102:105], v[170:173]
	v_mfma_f32_16x16x32_bf16 v[170:173], v[98:101], v[114:117], v[134:137]
	v_mfma_f32_16x16x32_bf16 v[134:137], v[78:81], v[118:121], v[158:161]
	v_mfma_f32_16x16x32_bf16 v[158:161], v[82:85], v[130:133], v[134:137]
	v_mfma_f32_16x16x32_bf16 v[134:137], v[86:89], v[118:121], v[154:157]
	v_mfma_f32_16x16x32_bf16 v[154:157], v[98:101], v[130:133], v[134:137]
	v_mfma_f32_16x16x32_bf16 v[134:137], v[78:81], v[184:187], v[142:145]
	v_mfma_f32_16x16x32_bf16 v[142:145], v[82:85], v[206:209], v[134:137]
	v_mfma_f32_16x16x32_bf16 v[134:137], v[86:89], v[184:187], v[138:141]
	v_mfma_f32_16x16x32_bf16 v[126:129], v[78:81], v[210:213], v[126:129]
	v_mfma_f32_16x16x32_bf16 v[122:125], v[86:89], v[210:213], v[122:125]
	v_mfma_f32_16x16x32_bf16 v[138:141], v[98:101], v[206:209], v[134:137]
	v_mfma_f32_16x16x32_bf16 v[126:129], v[82:85], v[214:217], v[126:129]
	v_mfma_f32_16x16x32_bf16 v[122:125], v[98:101], v[214:217], v[122:125]
	s_setprio 0
	s_barrier
	s_nop 0
	v_add_u32_e32 v134, s77, v202
	s_mov_b32 m0, s73
	ds_read_b128 v[218:221], v134
	ds_read_b128 v[242:245], v134 offset:1024
	ds_read_b128 v[246:249], v134 offset:2048
	ds_read_b128 v[194:197], v134 offset:3072
	v_lshl_add_u64 v[134:135], v[188:189], 0, s[88:89]
	global_load_lds_dwordx4 v[134:135], off
	v_lshl_add_u64 v[134:135], v[222:223], 0, s[88:89]
	s_mov_b32 m0, s74
	s_nop 0
	global_load_lds_dwordx4 v[134:135], off
	s_barrier
	s_waitcnt lgkmcnt(0)
	s_setprio 1
	s_waitcnt lgkmcnt(0)
	v_mfma_f32_16x16x32_bf16 v[34:37], v[246:249], v[102:105], v[34:37]
	v_mfma_f32_16x16x32_bf16 v[162:165], v[194:197], v[114:117], v[34:37]
	v_mfma_f32_16x16x32_bf16 v[34:37], v[218:221], v[118:121], v[38:41]
	v_mfma_f32_16x16x32_bf16 v[150:153], v[242:245], v[130:133], v[34:37]
	v_mfma_f32_16x16x32_bf16 v[34:37], v[246:249], v[118:121], v[58:61]
	v_mfma_f32_16x16x32_bf16 v[134:137], v[218:221], v[102:105], v[166:169]
	v_mfma_f32_16x16x32_bf16 v[146:149], v[194:197], v[130:133], v[34:37]
	v_mfma_f32_16x16x32_bf16 v[34:37], v[218:221], v[184:187], v[62:65]
	v_mfma_f32_16x16x32_bf16 v[166:169], v[242:245], v[114:117], v[134:137]
	v_mfma_f32_16x16x32_bf16 v[134:137], v[242:245], v[206:209], v[34:37]
	v_mfma_f32_16x16x32_bf16 v[34:37], v[246:249], v[184:187], v[66:69]
	v_mfma_f32_16x16x32_bf16 v[130:133], v[194:197], v[206:209], v[34:37]
	v_mfma_f32_16x16x32_bf16 v[34:37], v[218:221], v[210:213], v[70:73]
	v_mfma_f32_16x16x32_bf16 v[118:121], v[242:245], v[214:217], v[34:37]
	v_mfma_f32_16x16x32_bf16 v[34:37], v[246:249], v[210:213], v[74:77]
	v_mfma_f32_16x16x32_bf16 v[114:117], v[194:197], v[214:217], v[34:37]
	s_setprio 0
	s_mov_b32 m0, s75
	v_lshl_add_u64 v[102:103], v[250:251], 0, s[88:89]
	s_barrier
	s_nop 2
	ds_read_b128 v[34:37], v204 offset:49152
	ds_read_b128 v[38:41], v204 offset:50176
	ds_read_b128 v[58:61], v204 offset:51200
	ds_read_b128 v[62:65], v204 offset:52224
	ds_read_b128 v[66:69], v204 offset:53248
	ds_read_b128 v[70:73], v204 offset:54272
	ds_read_b128 v[74:77], v204 offset:55296
	ds_read_b128 v[184:187], v204 offset:56320
	global_load_lds_dwordx4 v[102:103], off
	v_lshl_add_u64 v[102:103], v[232:233], 0, s[88:89]
	s_mov_b32 m0, s76
	s_nop 0
	global_load_lds_dwordx4 v[102:103], off
	s_barrier
	s_waitcnt lgkmcnt(0)
	s_setprio 1
	s_waitcnt lgkmcnt(0)
	v_mfma_f32_16x16x32_bf16 v[102:105], v[78:81], v[34:37], v[110:113]
	v_mfma_f32_16x16x32_bf16 v[110:113], v[82:85], v[38:41], v[102:105]
	v_mfma_f32_16x16x32_bf16 v[102:105], v[86:89], v[34:37], v[106:109]
	v_mfma_f32_16x16x32_bf16 v[94:97], v[78:81], v[58:61], v[94:97]
	v_mfma_f32_16x16x32_bf16 v[90:93], v[86:89], v[58:61], v[90:93]
	v_mfma_f32_16x16x32_bf16 v[54:57], v[78:81], v[66:69], v[54:57]
	v_mfma_f32_16x16x32_bf16 v[50:53], v[86:89], v[66:69], v[50:53]
	v_mfma_f32_16x16x32_bf16 v[14:17], v[78:81], v[74:77], v[14:17]
	v_mfma_f32_16x16x32_bf16 v[10:13], v[86:89], v[74:77], v[10:13]
	v_mfma_f32_16x16x32_bf16 v[106:109], v[98:101], v[38:41], v[102:105]
	v_mfma_f32_16x16x32_bf16 v[94:97], v[82:85], v[62:65], v[94:97]
	v_mfma_f32_16x16x32_bf16 v[90:93], v[98:101], v[62:65], v[90:93]
	v_mfma_f32_16x16x32_bf16 v[54:57], v[82:85], v[70:73], v[54:57]
	v_mfma_f32_16x16x32_bf16 v[50:53], v[98:101], v[70:73], v[50:53]
	v_mfma_f32_16x16x32_bf16 v[14:17], v[82:85], v[184:187], v[14:17]
	v_mfma_f32_16x16x32_bf16 v[10:13], v[98:101], v[184:187], v[10:13]
	s_setprio 0
	s_barrier
	s_add_u32 s0, s34, 0x40080
	s_addc_u32 s1, s35, 0
	s_mov_b32 m0, s78
	v_lshl_add_u64 v[78:79], s[0:1], 0, v[0:1]
	global_load_lds_dwordx4 v[78:79], off
	v_lshl_add_u64 v[78:79], s[0:1], 0, v[178:179]
	s_mov_b32 m0, s79
	s_nop 0
	global_load_lds_dwordx4 v[78:79], off
	s_waitcnt vmcnt(6)
	s_barrier
	s_setprio 1
	v_mfma_f32_16x16x32_bf16 v[18:21], v[218:221], v[34:37], v[18:21]
	v_mfma_f32_16x16x32_bf16 v[102:105], v[242:245], v[38:41], v[18:21]
	v_mfma_f32_16x16x32_bf16 v[18:21], v[246:249], v[34:37], v[22:25]
	v_mfma_f32_16x16x32_bf16 v[98:101], v[194:197], v[38:41], v[18:21]
	v_mfma_f32_16x16x32_bf16 v[18:21], v[218:221], v[58:61], v[26:29]
	v_mfma_f32_16x16x32_bf16 v[86:89], v[242:245], v[62:65], v[18:21]
	v_mfma_f32_16x16x32_bf16 v[18:21], v[246:249], v[58:61], v[30:33]
	v_mfma_f32_16x16x32_bf16 v[82:85], v[194:197], v[62:65], v[18:21]
	v_mfma_f32_16x16x32_bf16 v[18:21], v[218:221], v[66:69], v[46:49]
	v_mfma_f32_16x16x32_bf16 v[46:49], v[242:245], v[70:73], v[18:21]
	v_mfma_f32_16x16x32_bf16 v[18:21], v[246:249], v[66:69], v[42:45]
	v_mfma_f32_16x16x32_bf16 v[6:9], v[218:221], v[74:77], v[6:9]
	v_mfma_f32_16x16x32_bf16 v[2:5], v[246:249], v[74:77], v[2:5]
	v_mfma_f32_16x16x32_bf16 v[42:45], v[194:197], v[70:73], v[18:21]
	v_mfma_f32_16x16x32_bf16 v[6:9], v[242:245], v[184:187], v[6:9]
	v_mfma_f32_16x16x32_bf16 v[2:5], v[194:197], v[184:187], v[2:5]
	s_setprio 0
	s_add_i32 s28, s28, 2
	s_add_u32 s20, s20, 0x100
	s_addc_u32 s21, s21, 0
	s_add_u32 s25, s25, 0x100
	s_addc_u32 s26, s26, 0
	s_cmp_gt_u32 s28, 13
	s_barrier
	s_cbranch_scc0 .LBB0_780
	v_readfirstlane_b32 s98, v191
	s_cmpk_gt_u32 s98, 0xff
	s_cbranch_scc1 .Lrl_e0_780
	s_barrier
.Lrl_e0_780:
	v_lshl_or_b32 v184, s4, 8, v203
	s_lshl_b32 s4, s14, 8
	s_add_i32 s0, s4, 0xfffff000
	s_lshr_b32 s0, s0, 11
	s_mulk_i32 s0, 0x1800
	s_addk_i32 s0, 0x1800
	s_cmp_gt_i32 s14, 15
	s_cselect_b32 s86, s0, 0
	v_add_u32_e32 v186, s4, v201
	s_lshl_b64 s[0:1], s[86:87], 2
	v_ashrrev_i32_e32 v187, 31, v186
	s_add_u32 s0, s70, s0
	v_ashrrev_i32_e32 v185, 31, v184
	v_lshlrev_b64 v[188:189], 11, v[186:187]
	s_addc_u32 s1, s71, s1
	v_lshlrev_b64 v[18:19], 2, v[184:185]
	v_lshl_add_u64 v[188:189], s[12:13], 0, v[188:189]
	v_lshlrev_b64 v[184:185], 1, v[184:185]
	v_lshl_add_u64 v[22:23], s[0:1], 0, v[18:19]
	v_lshl_add_u64 v[30:31], s[2:3], 0, v[18:19]
	v_lshl_add_u64 v[38:39], s[16:17], 0, v[18:19]
	v_lshl_add_u64 v[194:195], v[186:187], 3, s[6:7]
	v_lshl_add_u64 v[188:189], v[188:189], 0, v[184:185]
	v_mov_b64_e32 v[184:185], v[188:189]
	global_load_dwordx4 v[58:61], v[22:23], off offset:16
	global_load_dwordx4 v[62:65], v[22:23], off
	global_load_dwordx4 v[66:69], v[30:31], off offset:16
	global_load_dwordx4 v[74:77], v[30:31], off
	global_load_dwordx4 v[70:73], v[38:39], off offset:16
	global_load_dwordx4 v[78:81], v[38:39], off
	global_load_dwordx4 v[18:21], v[22:23], off offset:528
	s_nop 0
	global_load_dwordx4 v[22:25], v[22:23], off offset:512
	s_nop 0
	global_load_dwordx4 v[26:29], v[30:31], off offset:528
	global_load_dwordx4 v[34:37], v[30:31], off offset:512
	s_nop 0
	global_load_dwordx4 v[30:33], v[38:39], off offset:528
	s_nop 0
	global_load_dwordx4 v[38:41], v[38:39], off offset:512
	s_and_b64 vcc, exec, s[40:41]
	global_load_dwordx2 v[232:233], v[194:195], off
	global_load_dwordx4 v[210:213], v[188:189], off
	global_load_dwordx4 v[214:217], v[188:189], off offset:256
	s_mov_b32 s0, 0x8000
	s_mov_b32 s1, 0
	v_lshl_add_u64 v[188:189], v[188:189], 0, s[0:1]
	global_load_dwordx2 v[250:251], v[194:195], off offset:128
	global_load_dwordx4 v[242:245], v[188:189], off
	global_load_dwordx4 v[246:249], v[188:189], off offset:256
	v_lshl_add_u64 v[188:189], v[188:189], 0, s[0:1]
	global_load_dwordx2 v[222:223], v[194:195], off offset:256
	global_load_dwordx4 v[218:221], v[188:189], off
	global_load_dwordx4 v[206:209], v[188:189], off offset:256
	v_lshl_add_u64 v[188:189], v[188:189], 0, s[0:1]
	s_mov_b32 s4, s42
	s_mov_b32 s14, s44
	s_mov_b64 s[34:35], s[48:49]
	s_mov_b64 s[20:21], s[46:47]
	s_waitcnt vmcnt(7)
	v_lshlrev_b32_e32 v196, 16, v210
	v_and_b32_e32 v197, 0xffff0000, v210
	v_lshlrev_b32_e32 v210, 16, v211
	v_and_b32_e32 v211, 0xffff0000, v211
	v_lshlrev_b32_e32 v186, 16, v212
	v_and_b32_e32 v187, 0xffff0000, v212
	v_lshlrev_b32_e32 v212, 16, v213
	v_and_b32_e32 v213, 0xffff0000, v213
	v_sub_f32_e32 v211, v211, v232
	v_sub_f32_e32 v210, v210, v232
	v_sub_f32_e32 v197, v197, v232
	v_sub_f32_e32 v196, v196, v232
	v_pk_mul_f32 v[196:197], v[232:233], v[196:197] op_sel:[1,0]
	v_pk_mul_f32 v[210:211], v[232:233], v[210:211] op_sel:[1,0]
	v_sub_f32_e32 v213, v213, v232
	v_sub_f32_e32 v212, v212, v232
	v_sub_f32_e32 v187, v187, v232
	v_sub_f32_e32 v186, v186, v232
	v_pk_fma_f32 v[210:211], v[76:77], v[210:211], v[80:81]
	v_pk_fma_f32 v[196:197], v[74:75], v[196:197], v[78:79]
	v_pk_mul_f32 v[186:187], v[232:233], v[186:187] op_sel:[1,0]
	v_pk_mul_f32 v[212:213], v[232:233], v[212:213] op_sel:[1,0]
	v_pk_fma_f32 v[186:187], v[66:67], v[186:187], v[70:71]
	v_pk_fma_f32 v[212:213], v[68:69], v[212:213], v[72:73]
	v_pk_mul_f32 v[210:211], v[210:211], s[56:57] op_sel_hi:[1,0]
	v_pk_mul_f32 v[196:197], v[196:197], s[56:57] op_sel_hi:[1,0]
	v_pk_mul_f32 v[212:213], v[212:213], s[56:57] op_sel_hi:[1,0]
	v_pk_mul_f32 v[186:187], v[186:187], s[56:57] op_sel_hi:[1,0]
	v_pk_fma_f32 v[176:177], v[176:177], v[64:65], v[210:211]
	v_pk_fma_f32 v[174:175], v[174:175], v[62:63], v[196:197]
	v_pk_fma_f32 v[172:173], v[172:173], v[60:61], v[212:213]
	v_pk_fma_f32 v[170:171], v[170:171], v[58:59], v[186:187]
	v_cvt_pk_bf16_f32 v174, v174, v175
	v_cvt_pk_bf16_f32 v175, v176, v177
	v_cvt_pk_bf16_f32 v176, v170, v171
	v_cvt_pk_bf16_f32 v177, v172, v173
	global_store_dwordx4 v[184:185], v[174:177], off
	s_waitcnt vmcnt(7)
	v_lshlrev_b32_e32 v196, 16, v214
	v_and_b32_e32 v197, 0xffff0000, v214
	v_lshlrev_b32_e32 v214, 16, v215
	v_and_b32_e32 v215, 0xffff0000, v215
	v_lshlrev_b32_e32 v186, 16, v216
	v_and_b32_e32 v187, 0xffff0000, v216
	v_lshlrev_b32_e32 v216, 16, v217
	v_and_b32_e32 v217, 0xffff0000, v217
	v_sub_f32_e32 v215, v215, v232
	v_sub_f32_e32 v214, v214, v232
	v_sub_f32_e32 v197, v197, v232
	v_sub_f32_e32 v196, v196, v232
	v_pk_mul_f32 v[196:197], v[232:233], v[196:197] op_sel:[1,0]
	v_pk_mul_f32 v[214:215], v[232:233], v[214:215] op_sel:[1,0]
	v_sub_f32_e32 v217, v217, v232
	v_sub_f32_e32 v216, v216, v232
	v_sub_f32_e32 v187, v187, v232
	v_sub_f32_e32 v186, v186, v232
	v_pk_fma_f32 v[214:215], v[36:37], v[214:215], v[40:41]
	v_pk_fma_f32 v[196:197], v[34:35], v[196:197], v[38:39]
	v_pk_mul_f32 v[186:187], v[232:233], v[186:187] op_sel:[1,0]
	v_pk_mul_f32 v[216:217], v[232:233], v[216:217] op_sel:[1,0]
	v_pk_fma_f32 v[186:187], v[26:27], v[186:187], v[30:31]
	v_pk_fma_f32 v[216:217], v[28:29], v[216:217], v[32:33]
	v_pk_mul_f32 v[214:215], v[214:215], s[56:57] op_sel_hi:[1,0]
	v_pk_mul_f32 v[196:197], v[196:197], s[56:57] op_sel_hi:[1,0]
	v_pk_mul_f32 v[216:217], v[216:217], s[56:57] op_sel_hi:[1,0]
	v_pk_mul_f32 v[186:187], v[186:187], s[56:57] op_sel_hi:[1,0]
	v_pk_fma_f32 v[168:169], v[168:169], v[24:25], v[214:215]
	v_pk_fma_f32 v[166:167], v[166:167], v[22:23], v[196:197]
	v_pk_fma_f32 v[164:165], v[164:165], v[20:21], v[216:217]
	v_pk_fma_f32 v[162:163], v[162:163], v[18:19], v[186:187]
	v_cvt_pk_bf16_f32 v166, v166, v167
	v_cvt_pk_bf16_f32 v167, v168, v169
	v_cvt_pk_bf16_f32 v168, v162, v163
	v_cvt_pk_bf16_f32 v169, v164, v165
	global_store_dwordx4 v[184:185], v[166:169], off offset:256
	v_lshl_add_u64 v[184:185], v[184:185], 0, s[0:1]
	global_load_dwordx2 v[232:233], v[194:195], off offset:384
	global_load_dwordx4 v[210:213], v[188:189], off
	global_load_dwordx4 v[214:217], v[188:189], off offset:256
	s_mov_b32 s0, 0x28000
	v_lshl_add_u64 v[188:189], v[188:189], 0, s[0:1]
	s_waitcnt vmcnt(9)
	v_lshlrev_b32_e32 v196, 16, v242
	v_and_b32_e32 v197, 0xffff0000, v242
	v_lshlrev_b32_e32 v242, 16, v243
	v_and_b32_e32 v243, 0xffff0000, v243
	v_lshlrev_b32_e32 v186, 16, v244
	v_and_b32_e32 v187, 0xffff0000, v244
	v_lshlrev_b32_e32 v244, 16, v245
	v_and_b32_e32 v245, 0xffff0000, v245
	v_sub_f32_e32 v243, v243, v250
	v_sub_f32_e32 v242, v242, v250
	v_sub_f32_e32 v197, v197, v250
	v_sub_f32_e32 v196, v196, v250
	v_pk_mul_f32 v[196:197], v[250:251], v[196:197] op_sel:[1,0]
	v_pk_mul_f32 v[242:243], v[250:251], v[242:243] op_sel:[1,0]
	v_sub_f32_e32 v245, v245, v250
	v_sub_f32_e32 v244, v244, v250
	v_sub_f32_e32 v187, v187, v250
	v_sub_f32_e32 v186, v186, v250
	v_pk_fma_f32 v[242:243], v[76:77], v[242:243], v[80:81]
	v_pk_fma_f32 v[196:197], v[74:75], v[196:197], v[78:79]
	v_pk_mul_f32 v[186:187], v[250:251], v[186:187] op_sel:[1,0]
	v_pk_mul_f32 v[244:245], v[250:251], v[244:245] op_sel:[1,0]
	v_pk_fma_f32 v[186:187], v[66:67], v[186:187], v[70:71]
	v_pk_fma_f32 v[244:245], v[68:69], v[244:245], v[72:73]
	v_pk_mul_f32 v[242:243], v[242:243], s[56:57] op_sel_hi:[1,0]
	v_pk_mul_f32 v[196:197], v[196:197], s[56:57] op_sel_hi:[1,0]
	v_pk_mul_f32 v[244:245], v[244:245], s[56:57] op_sel_hi:[1,0]
	v_pk_mul_f32 v[186:187], v[186:187], s[56:57] op_sel_hi:[1,0]
	v_pk_fma_f32 v[160:161], v[160:161], v[64:65], v[242:243]
	v_pk_fma_f32 v[158:159], v[158:159], v[62:63], v[196:197]
	v_pk_fma_f32 v[156:157], v[156:157], v[60:61], v[244:245]
	v_pk_fma_f32 v[154:155], v[154:155], v[58:59], v[186:187]
	v_cvt_pk_bf16_f32 v158, v158, v159
	v_cvt_pk_bf16_f32 v159, v160, v161
	v_cvt_pk_bf16_f32 v160, v154, v155
	v_cvt_pk_bf16_f32 v161, v156, v157
	global_store_dwordx4 v[184:185], v[158:161], off
	s_waitcnt vmcnt(9)
	v_lshlrev_b32_e32 v196, 16, v246
	v_and_b32_e32 v197, 0xffff0000, v246
	v_lshlrev_b32_e32 v246, 16, v247
	v_and_b32_e32 v247, 0xffff0000, v247
	v_lshlrev_b32_e32 v186, 16, v248
	v_and_b32_e32 v187, 0xffff0000, v248
	v_lshlrev_b32_e32 v248, 16, v249
	v_and_b32_e32 v249, 0xffff0000, v249
	v_sub_f32_e32 v247, v247, v250
	v_sub_f32_e32 v246, v246, v250
	v_sub_f32_e32 v197, v197, v250
	v_sub_f32_e32 v196, v196, v250
	v_pk_mul_f32 v[196:197], v[250:251], v[196:197] op_sel:[1,0]
	v_pk_mul_f32 v[246:247], v[250:251], v[246:247] op_sel:[1,0]
	v_sub_f32_e32 v249, v249, v250
	v_sub_f32_e32 v248, v248, v250
	v_sub_f32_e32 v187, v187, v250
	v_sub_f32_e32 v186, v186, v250
	v_pk_fma_f32 v[246:247], v[36:37], v[246:247], v[40:41]
	v_pk_fma_f32 v[196:197], v[34:35], v[196:197], v[38:39]
	v_pk_mul_f32 v[186:187], v[250:251], v[186:187] op_sel:[1,0]
	v_pk_mul_f32 v[248:249], v[250:251], v[248:249] op_sel:[1,0]
	v_pk_fma_f32 v[186:187], v[26:27], v[186:187], v[30:31]
	v_pk_fma_f32 v[248:249], v[28:29], v[248:249], v[32:33]
	v_pk_mul_f32 v[246:247], v[246:247], s[56:57] op_sel_hi:[1,0]
	v_pk_mul_f32 v[196:197], v[196:197], s[56:57] op_sel_hi:[1,0]
	v_pk_mul_f32 v[248:249], v[248:249], s[56:57] op_sel_hi:[1,0]
	v_pk_mul_f32 v[186:187], v[186:187], s[56:57] op_sel_hi:[1,0]
	v_pk_fma_f32 v[152:153], v[152:153], v[24:25], v[246:247]
	v_pk_fma_f32 v[150:151], v[150:151], v[22:23], v[196:197]
	v_pk_fma_f32 v[148:149], v[148:149], v[20:21], v[248:249]
	v_pk_fma_f32 v[146:147], v[146:147], v[18:19], v[186:187]
	v_cvt_pk_bf16_f32 v150, v150, v151
	v_cvt_pk_bf16_f32 v151, v152, v153
	v_cvt_pk_bf16_f32 v152, v146, v147
	v_cvt_pk_bf16_f32 v153, v148, v149
	global_store_dwordx4 v[184:185], v[150:153], off offset:256
	s_mov_b32 s0, 0x8000
	v_lshl_add_u64 v[184:185], v[184:185], 0, s[0:1]
	global_load_dwordx2 v[250:251], v[194:195], off offset:1024
	global_load_dwordx4 v[242:245], v[188:189], off
	global_load_dwordx4 v[246:249], v[188:189], off offset:256
	v_lshl_add_u64 v[188:189], v[188:189], 0, s[0:1]
	s_waitcnt vmcnt(11)
	v_lshlrev_b32_e32 v196, 16, v218
	v_and_b32_e32 v197, 0xffff0000, v218
	v_lshlrev_b32_e32 v218, 16, v219
	v_and_b32_e32 v219, 0xffff0000, v219
	v_lshlrev_b32_e32 v186, 16, v220
	v_and_b32_e32 v187, 0xffff0000, v220
	v_lshlrev_b32_e32 v220, 16, v221
	v_and_b32_e32 v221, 0xffff0000, v221
	v_sub_f32_e32 v219, v219, v222
	v_sub_f32_e32 v218, v218, v222
	v_sub_f32_e32 v197, v197, v222
	v_sub_f32_e32 v196, v196, v222
	v_pk_mul_f32 v[196:197], v[222:223], v[196:197] op_sel:[1,0]
	v_pk_mul_f32 v[218:219], v[222:223], v[218:219] op_sel:[1,0]
	v_sub_f32_e32 v221, v221, v222
	v_sub_f32_e32 v220, v220, v222
	v_sub_f32_e32 v187, v187, v222
	v_sub_f32_e32 v186, v186, v222
	v_pk_fma_f32 v[218:219], v[76:77], v[218:219], v[80:81]
	v_pk_fma_f32 v[196:197], v[74:75], v[196:197], v[78:79]
	v_pk_mul_f32 v[186:187], v[222:223], v[186:187] op_sel:[1,0]
	v_pk_mul_f32 v[220:221], v[222:223], v[220:221] op_sel:[1,0]
	v_pk_fma_f32 v[186:187], v[66:67], v[186:187], v[70:71]
	v_pk_fma_f32 v[220:221], v[68:69], v[220:221], v[72:73]
	v_pk_mul_f32 v[218:219], v[218:219], s[56:57] op_sel_hi:[1,0]
	v_pk_mul_f32 v[196:197], v[196:197], s[56:57] op_sel_hi:[1,0]
	v_pk_mul_f32 v[220:221], v[220:221], s[56:57] op_sel_hi:[1,0]
	v_pk_mul_f32 v[186:187], v[186:187], s[56:57] op_sel_hi:[1,0]
	v_pk_fma_f32 v[144:145], v[144:145], v[64:65], v[218:219]
	v_pk_fma_f32 v[142:143], v[142:143], v[62:63], v[196:197]
	v_pk_fma_f32 v[140:141], v[140:141], v[60:61], v[220:221]
	v_pk_fma_f32 v[138:139], v[138:139], v[58:59], v[186:187]
	v_cvt_pk_bf16_f32 v142, v142, v143
	v_cvt_pk_bf16_f32 v143, v144, v145
	v_cvt_pk_bf16_f32 v144, v138, v139
	v_cvt_pk_bf16_f32 v145, v140, v141
	global_store_dwordx4 v[184:185], v[142:145], off
	s_waitcnt vmcnt(11)
	v_lshlrev_b32_e32 v196, 16, v206
	v_and_b32_e32 v197, 0xffff0000, v206
	v_lshlrev_b32_e32 v206, 16, v207
	v_and_b32_e32 v207, 0xffff0000, v207
	v_lshlrev_b32_e32 v186, 16, v208
	v_and_b32_e32 v187, 0xffff0000, v208
	v_lshlrev_b32_e32 v208, 16, v209
	v_and_b32_e32 v209, 0xffff0000, v209
	v_sub_f32_e32 v207, v207, v222
	v_sub_f32_e32 v206, v206, v222
	v_sub_f32_e32 v197, v197, v222
	v_sub_f32_e32 v196, v196, v222
	v_pk_mul_f32 v[196:197], v[222:223], v[196:197] op_sel:[1,0]
	v_pk_mul_f32 v[206:207], v[222:223], v[206:207] op_sel:[1,0]
	v_sub_f32_e32 v209, v209, v222
	v_sub_f32_e32 v208, v208, v222
	v_sub_f32_e32 v187, v187, v222
	v_sub_f32_e32 v186, v186, v222
	v_pk_fma_f32 v[206:207], v[36:37], v[206:207], v[40:41]
	v_pk_fma_f32 v[196:197], v[34:35], v[196:197], v[38:39]
	v_pk_mul_f32 v[186:187], v[222:223], v[186:187] op_sel:[1,0]
	v_pk_mul_f32 v[208:209], v[222:223], v[208:209] op_sel:[1,0]
	v_pk_fma_f32 v[186:187], v[26:27], v[186:187], v[30:31]
	v_pk_fma_f32 v[208:209], v[28:29], v[208:209], v[32:33]
	v_pk_mul_f32 v[206:207], v[206:207], s[56:57] op_sel_hi:[1,0]
	v_pk_mul_f32 v[196:197], v[196:197], s[56:57] op_sel_hi:[1,0]
	v_pk_mul_f32 v[208:209], v[208:209], s[56:57] op_sel_hi:[1,0]
	v_pk_mul_f32 v[186:187], v[186:187], s[56:57] op_sel_hi:[1,0]
	v_pk_fma_f32 v[136:137], v[136:137], v[24:25], v[206:207]
	v_pk_fma_f32 v[134:135], v[134:135], v[22:23], v[196:197]
	v_pk_fma_f32 v[132:133], v[132:133], v[20:21], v[208:209]
	v_pk_fma_f32 v[130:131], v[130:131], v[18:19], v[186:187]
	v_cvt_pk_bf16_f32 v134, v134, v135
	v_cvt_pk_bf16_f32 v135, v136, v137
	v_cvt_pk_bf16_f32 v136, v130, v131
	v_cvt_pk_bf16_f32 v137, v132, v133
	global_store_dwordx4 v[184:185], v[134:137], off offset:256
	v_lshl_add_u64 v[184:185], v[184:185], 0, s[0:1]
	global_load_dwordx2 v[222:223], v[194:195], off offset:1152
	global_load_dwordx4 v[218:221], v[188:189], off
	global_load_dwordx4 v[206:209], v[188:189], off offset:256
	v_lshl_add_u64 v[188:189], v[188:189], 0, s[0:1]
	s_waitcnt vmcnt(11)
	v_lshlrev_b32_e32 v196, 16, v210
	v_and_b32_e32 v197, 0xffff0000, v210
	v_lshlrev_b32_e32 v210, 16, v211
	v_and_b32_e32 v211, 0xffff0000, v211
	v_lshlrev_b32_e32 v186, 16, v212
	v_and_b32_e32 v187, 0xffff0000, v212
	v_lshlrev_b32_e32 v212, 16, v213
	v_and_b32_e32 v213, 0xffff0000, v213
	v_sub_f32_e32 v211, v211, v232
	v_sub_f32_e32 v210, v210, v232
	v_sub_f32_e32 v197, v197, v232
	v_sub_f32_e32 v196, v196, v232
	v_pk_mul_f32 v[196:197], v[232:233], v[196:197] op_sel:[1,0]
	v_pk_mul_f32 v[210:211], v[232:233], v[210:211] op_sel:[1,0]
	v_sub_f32_e32 v213, v213, v232
	v_sub_f32_e32 v212, v212, v232
	v_sub_f32_e32 v187, v187, v232
	v_sub_f32_e32 v186, v186, v232
	v_pk_fma_f32 v[210:211], v[76:77], v[210:211], v[80:81]
	v_pk_fma_f32 v[196:197], v[74:75], v[196:197], v[78:79]
	v_pk_mul_f32 v[186:187], v[232:233], v[186:187] op_sel:[1,0]
	v_pk_mul_f32 v[212:213], v[232:233], v[212:213] op_sel:[1,0]
	v_pk_fma_f32 v[186:187], v[66:67], v[186:187], v[70:71]
	v_pk_fma_f32 v[212:213], v[68:69], v[212:213], v[72:73]
	v_pk_mul_f32 v[210:211], v[210:211], s[56:57] op_sel_hi:[1,0]
	v_pk_mul_f32 v[196:197], v[196:197], s[56:57] op_sel_hi:[1,0]
	v_pk_mul_f32 v[212:213], v[212:213], s[56:57] op_sel_hi:[1,0]
	v_pk_mul_f32 v[186:187], v[186:187], s[56:57] op_sel_hi:[1,0]
	v_pk_fma_f32 v[128:129], v[128:129], v[64:65], v[210:211]
	v_pk_fma_f32 v[126:127], v[126:127], v[62:63], v[196:197]
	v_pk_fma_f32 v[124:125], v[124:125], v[60:61], v[212:213]
	v_pk_fma_f32 v[122:123], v[122:123], v[58:59], v[186:187]
	v_cvt_pk_bf16_f32 v126, v126, v127
	v_cvt_pk_bf16_f32 v127, v128, v129
	v_cvt_pk_bf16_f32 v128, v122, v123
	v_cvt_pk_bf16_f32 v129, v124, v125
	global_store_dwordx4 v[184:185], v[126:129], off
	s_waitcnt vmcnt(11)
	v_lshlrev_b32_e32 v196, 16, v214
	v_and_b32_e32 v197, 0xffff0000, v214
	v_lshlrev_b32_e32 v214, 16, v215
	v_and_b32_e32 v215, 0xffff0000, v215
	v_lshlrev_b32_e32 v186, 16, v216
	v_and_b32_e32 v187, 0xffff0000, v216
	v_lshlrev_b32_e32 v216, 16, v217
	v_and_b32_e32 v217, 0xffff0000, v217
	v_sub_f32_e32 v215, v215, v232
	v_sub_f32_e32 v214, v214, v232
	v_sub_f32_e32 v197, v197, v232
	v_sub_f32_e32 v196, v196, v232
	v_pk_mul_f32 v[196:197], v[232:233], v[196:197] op_sel:[1,0]
	v_pk_mul_f32 v[214:215], v[232:233], v[214:215] op_sel:[1,0]
	v_sub_f32_e32 v217, v217, v232
	v_sub_f32_e32 v216, v216, v232
	v_sub_f32_e32 v187, v187, v232
	v_sub_f32_e32 v186, v186, v232
	v_pk_fma_f32 v[214:215], v[36:37], v[214:215], v[40:41]
	v_pk_fma_f32 v[196:197], v[34:35], v[196:197], v[38:39]
	v_pk_mul_f32 v[186:187], v[232:233], v[186:187] op_sel:[1,0]
	v_pk_mul_f32 v[216:217], v[232:233], v[216:217] op_sel:[1,0]
	v_pk_fma_f32 v[186:187], v[26:27], v[186:187], v[30:31]
	v_pk_fma_f32 v[216:217], v[28:29], v[216:217], v[32:33]
	v_pk_mul_f32 v[214:215], v[214:215], s[56:57] op_sel_hi:[1,0]
	v_pk_mul_f32 v[196:197], v[196:197], s[56:57] op_sel_hi:[1,0]
	v_pk_mul_f32 v[216:217], v[216:217], s[56:57] op_sel_hi:[1,0]
	v_pk_mul_f32 v[186:187], v[186:187], s[56:57] op_sel_hi:[1,0]
	v_pk_fma_f32 v[120:121], v[120:121], v[24:25], v[214:215]
	v_pk_fma_f32 v[118:119], v[118:119], v[22:23], v[196:197]
	v_pk_fma_f32 v[116:117], v[116:117], v[20:21], v[216:217]
	v_pk_fma_f32 v[114:115], v[114:115], v[18:19], v[186:187]
	v_cvt_pk_bf16_f32 v118, v118, v119
	v_cvt_pk_bf16_f32 v119, v120, v121
	v_cvt_pk_bf16_f32 v120, v114, v115
	v_cvt_pk_bf16_f32 v121, v116, v117
	global_store_dwordx4 v[184:185], v[118:121], off offset:256
	s_mov_b32 s0, 0x28000
	v_lshl_add_u64 v[184:185], v[184:185], 0, s[0:1]
	global_load_dwordx2 v[232:233], v[194:195], off offset:1280
	global_load_dwordx4 v[210:213], v[188:189], off
	global_load_dwordx4 v[214:217], v[188:189], off offset:256
	s_mov_b32 s0, 0x8000
	v_lshl_add_u64 v[188:189], v[188:189], 0, s[0:1]
	s_waitcnt vmcnt(11)
	v_lshlrev_b32_e32 v196, 16, v242
	v_and_b32_e32 v197, 0xffff0000, v242
	v_lshlrev_b32_e32 v242, 16, v243
	v_and_b32_e32 v243, 0xffff0000, v243
	v_lshlrev_b32_e32 v186, 16, v244
	v_and_b32_e32 v187, 0xffff0000, v244
	v_lshlrev_b32_e32 v244, 16, v245
	v_and_b32_e32 v245, 0xffff0000, v245
	v_sub_f32_e32 v243, v243, v250
	v_sub_f32_e32 v242, v242, v250
	v_sub_f32_e32 v197, v197, v250
	v_sub_f32_e32 v196, v196, v250
	v_pk_mul_f32 v[196:197], v[250:251], v[196:197] op_sel:[1,0]
	v_pk_mul_f32 v[242:243], v[250:251], v[242:243] op_sel:[1,0]
	v_sub_f32_e32 v245, v245, v250
	v_sub_f32_e32 v244, v244, v250
	v_sub_f32_e32 v187, v187, v250
	v_sub_f32_e32 v186, v186, v250
	v_pk_fma_f32 v[242:243], v[76:77], v[242:243], v[80:81]
	v_pk_fma_f32 v[196:197], v[74:75], v[196:197], v[78:79]
	v_pk_mul_f32 v[186:187], v[250:251], v[186:187] op_sel:[1,0]
	v_pk_mul_f32 v[244:245], v[250:251], v[244:245] op_sel:[1,0]
	v_pk_fma_f32 v[186:187], v[66:67], v[186:187], v[70:71]
	v_pk_fma_f32 v[244:245], v[68:69], v[244:245], v[72:73]
	v_pk_mul_f32 v[242:243], v[242:243], s[56:57] op_sel_hi:[1,0]
	v_pk_mul_f32 v[196:197], v[196:197], s[56:57] op_sel_hi:[1,0]
	v_pk_mul_f32 v[244:245], v[244:245], s[56:57] op_sel_hi:[1,0]
	v_pk_mul_f32 v[186:187], v[186:187], s[56:57] op_sel_hi:[1,0]
	v_pk_fma_f32 v[112:113], v[112:113], v[64:65], v[242:243]
	v_pk_fma_f32 v[110:111], v[110:111], v[62:63], v[196:197]
	v_pk_fma_f32 v[108:109], v[108:109], v[60:61], v[244:245]
	v_pk_fma_f32 v[106:107], v[106:107], v[58:59], v[186:187]
	v_cvt_pk_bf16_f32 v110, v110, v111
	v_cvt_pk_bf16_f32 v111, v112, v113
	v_cvt_pk_bf16_f32 v112, v106, v107
	v_cvt_pk_bf16_f32 v113, v108, v109
	global_store_dwordx4 v[184:185], v[110:113], off
	s_waitcnt vmcnt(11)
	v_lshlrev_b32_e32 v196, 16, v246
	v_and_b32_e32 v197, 0xffff0000, v246
	v_lshlrev_b32_e32 v246, 16, v247
	v_and_b32_e32 v247, 0xffff0000, v247
	v_lshlrev_b32_e32 v186, 16, v248
	v_and_b32_e32 v187, 0xffff0000, v248
	v_lshlrev_b32_e32 v248, 16, v249
	v_and_b32_e32 v249, 0xffff0000, v249
	v_sub_f32_e32 v247, v247, v250
	v_sub_f32_e32 v246, v246, v250
	v_sub_f32_e32 v197, v197, v250
	v_sub_f32_e32 v196, v196, v250
	v_pk_mul_f32 v[196:197], v[250:251], v[196:197] op_sel:[1,0]
	v_pk_mul_f32 v[246:247], v[250:251], v[246:247] op_sel:[1,0]
	v_sub_f32_e32 v249, v249, v250
	v_sub_f32_e32 v248, v248, v250
	v_sub_f32_e32 v187, v187, v250
	v_sub_f32_e32 v186, v186, v250
	v_pk_fma_f32 v[246:247], v[36:37], v[246:247], v[40:41]
	v_pk_fma_f32 v[196:197], v[34:35], v[196:197], v[38:39]
	v_pk_mul_f32 v[186:187], v[250:251], v[186:187] op_sel:[1,0]
	v_pk_mul_f32 v[248:249], v[250:251], v[248:249] op_sel:[1,0]
	v_pk_fma_f32 v[186:187], v[26:27], v[186:187], v[30:31]
	v_pk_fma_f32 v[248:249], v[28:29], v[248:249], v[32:33]
	v_pk_mul_f32 v[246:247], v[246:247], s[56:57] op_sel_hi:[1,0]
	v_pk_mul_f32 v[196:197], v[196:197], s[56:57] op_sel_hi:[1,0]
	v_pk_mul_f32 v[248:249], v[248:249], s[56:57] op_sel_hi:[1,0]
	v_pk_mul_f32 v[186:187], v[186:187], s[56:57] op_sel_hi:[1,0]
	v_pk_fma_f32 v[104:105], v[104:105], v[24:25], v[246:247]
	v_pk_fma_f32 v[102:103], v[102:103], v[22:23], v[196:197]
	v_pk_fma_f32 v[100:101], v[100:101], v[20:21], v[248:249]
	v_pk_fma_f32 v[98:99], v[98:99], v[18:19], v[186:187]
	v_cvt_pk_bf16_f32 v102, v102, v103
	v_cvt_pk_bf16_f32 v103, v104, v105
	v_cvt_pk_bf16_f32 v104, v98, v99
	v_cvt_pk_bf16_f32 v105, v100, v101
	global_store_dwordx4 v[184:185], v[102:105], off offset:256
	v_lshl_add_u64 v[184:185], v[184:185], 0, s[0:1]
	global_load_dwordx2 v[250:251], v[194:195], off offset:1408
	global_load_dwordx4 v[242:245], v[188:189], off
	global_load_dwordx4 v[246:249], v[188:189], off offset:256
	s_waitcnt vmcnt(11)
	v_lshlrev_b32_e32 v196, 16, v218
	v_and_b32_e32 v197, 0xffff0000, v218
	v_lshlrev_b32_e32 v218, 16, v219
	v_and_b32_e32 v219, 0xffff0000, v219
	v_lshlrev_b32_e32 v186, 16, v220
	v_and_b32_e32 v187, 0xffff0000, v220
	v_lshlrev_b32_e32 v220, 16, v221
	v_and_b32_e32 v221, 0xffff0000, v221
	v_sub_f32_e32 v219, v219, v222
	v_sub_f32_e32 v218, v218, v222
	v_sub_f32_e32 v197, v197, v222
	v_sub_f32_e32 v196, v196, v222
	v_pk_mul_f32 v[196:197], v[222:223], v[196:197] op_sel:[1,0]
	v_pk_mul_f32 v[218:219], v[222:223], v[218:219] op_sel:[1,0]
	v_sub_f32_e32 v221, v221, v222
	v_sub_f32_e32 v220, v220, v222
	v_sub_f32_e32 v187, v187, v222
	v_sub_f32_e32 v186, v186, v222
	v_pk_fma_f32 v[218:219], v[76:77], v[218:219], v[80:81]
	v_pk_fma_f32 v[196:197], v[74:75], v[196:197], v[78:79]
	v_pk_mul_f32 v[186:187], v[222:223], v[186:187] op_sel:[1,0]
	v_pk_mul_f32 v[220:221], v[222:223], v[220:221] op_sel:[1,0]
	v_pk_fma_f32 v[186:187], v[66:67], v[186:187], v[70:71]
	v_pk_fma_f32 v[220:221], v[68:69], v[220:221], v[72:73]
	v_pk_mul_f32 v[218:219], v[218:219], s[56:57] op_sel_hi:[1,0]
	v_pk_mul_f32 v[196:197], v[196:197], s[56:57] op_sel_hi:[1,0]
	v_pk_mul_f32 v[220:221], v[220:221], s[56:57] op_sel_hi:[1,0]
	v_pk_mul_f32 v[186:187], v[186:187], s[56:57] op_sel_hi:[1,0]
	v_pk_fma_f32 v[96:97], v[96:97], v[64:65], v[218:219]
	v_pk_fma_f32 v[94:95], v[94:95], v[62:63], v[196:197]
	v_pk_fma_f32 v[92:93], v[92:93], v[60:61], v[220:221]
	v_pk_fma_f32 v[90:91], v[90:91], v[58:59], v[186:187]
	v_cvt_pk_bf16_f32 v94, v94, v95
	v_cvt_pk_bf16_f32 v95, v96, v97
	v_cvt_pk_bf16_f32 v96, v90, v91
	v_cvt_pk_bf16_f32 v97, v92, v93
	global_store_dwordx4 v[184:185], v[94:97], off
	s_waitcnt vmcnt(11)
	v_lshlrev_b32_e32 v196, 16, v206
	v_and_b32_e32 v197, 0xffff0000, v206
	v_lshlrev_b32_e32 v206, 16, v207
	v_and_b32_e32 v207, 0xffff0000, v207
	v_lshlrev_b32_e32 v186, 16, v208
	v_and_b32_e32 v187, 0xffff0000, v208
	v_lshlrev_b32_e32 v208, 16, v209
	v_and_b32_e32 v209, 0xffff0000, v209
	v_sub_f32_e32 v207, v207, v222
	v_sub_f32_e32 v206, v206, v222
	v_sub_f32_e32 v197, v197, v222
	v_sub_f32_e32 v196, v196, v222
	v_pk_mul_f32 v[196:197], v[222:223], v[196:197] op_sel:[1,0]
	v_pk_mul_f32 v[206:207], v[222:223], v[206:207] op_sel:[1,0]
	v_sub_f32_e32 v209, v209, v222
	v_sub_f32_e32 v208, v208, v222
	v_sub_f32_e32 v187, v187, v222
	v_sub_f32_e32 v186, v186, v222
	v_pk_fma_f32 v[206:207], v[36:37], v[206:207], v[40:41]
	v_pk_fma_f32 v[196:197], v[34:35], v[196:197], v[38:39]
	v_pk_mul_f32 v[186:187], v[222:223], v[186:187] op_sel:[1,0]
	v_pk_mul_f32 v[208:209], v[222:223], v[208:209] op_sel:[1,0]
	v_pk_fma_f32 v[186:187], v[26:27], v[186:187], v[30:31]
	v_pk_fma_f32 v[208:209], v[28:29], v[208:209], v[32:33]
	v_pk_mul_f32 v[206:207], v[206:207], s[56:57] op_sel_hi:[1,0]
	v_pk_mul_f32 v[196:197], v[196:197], s[56:57] op_sel_hi:[1,0]
	v_pk_mul_f32 v[208:209], v[208:209], s[56:57] op_sel_hi:[1,0]
	v_pk_mul_f32 v[186:187], v[186:187], s[56:57] op_sel_hi:[1,0]
	v_pk_fma_f32 v[88:89], v[88:89], v[24:25], v[206:207]
	v_pk_fma_f32 v[86:87], v[86:87], v[22:23], v[196:197]
	v_pk_fma_f32 v[84:85], v[84:85], v[20:21], v[208:209]
	v_pk_fma_f32 v[82:83], v[82:83], v[18:19], v[186:187]
	v_cvt_pk_bf16_f32 v86, v86, v87
	v_cvt_pk_bf16_f32 v87, v88, v89
	v_cvt_pk_bf16_f32 v88, v82, v83
	v_cvt_pk_bf16_f32 v89, v84, v85
	global_store_dwordx4 v[184:185], v[86:89], off offset:256
	v_lshl_add_u64 v[184:185], v[184:185], 0, s[0:1]
	s_waitcnt vmcnt(8)
	v_lshlrev_b32_e32 v196, 16, v210
	v_and_b32_e32 v197, 0xffff0000, v210
	v_lshlrev_b32_e32 v210, 16, v211
	v_and_b32_e32 v211, 0xffff0000, v211
	v_lshlrev_b32_e32 v186, 16, v212
	v_and_b32_e32 v187, 0xffff0000, v212
	v_lshlrev_b32_e32 v212, 16, v213
	v_and_b32_e32 v213, 0xffff0000, v213
	v_sub_f32_e32 v211, v211, v232
	v_sub_f32_e32 v210, v210, v232
	v_sub_f32_e32 v197, v197, v232
	v_sub_f32_e32 v196, v196, v232
	v_pk_mul_f32 v[196:197], v[232:233], v[196:197] op_sel:[1,0]
	v_pk_mul_f32 v[210:211], v[232:233], v[210:211] op_sel:[1,0]
	v_sub_f32_e32 v213, v213, v232
	v_sub_f32_e32 v212, v212, v232
	v_sub_f32_e32 v187, v187, v232
	v_sub_f32_e32 v186, v186, v232
	v_pk_fma_f32 v[210:211], v[76:77], v[210:211], v[80:81]
	v_pk_fma_f32 v[196:197], v[74:75], v[196:197], v[78:79]
	v_pk_mul_f32 v[186:187], v[232:233], v[186:187] op_sel:[1,0]
	v_pk_mul_f32 v[212:213], v[232:233], v[212:213] op_sel:[1,0]
	v_pk_fma_f32 v[186:187], v[66:67], v[186:187], v[70:71]
	v_pk_fma_f32 v[212:213], v[68:69], v[212:213], v[72:73]
	v_pk_mul_f32 v[210:211], v[210:211], s[56:57] op_sel_hi:[1,0]
	v_pk_mul_f32 v[196:197], v[196:197], s[56:57] op_sel_hi:[1,0]
	v_pk_mul_f32 v[212:213], v[212:213], s[56:57] op_sel_hi:[1,0]
	v_pk_mul_f32 v[186:187], v[186:187], s[56:57] op_sel_hi:[1,0]
	v_pk_fma_f32 v[56:57], v[56:57], v[64:65], v[210:211]
	v_pk_fma_f32 v[54:55], v[54:55], v[62:63], v[196:197]
	v_pk_fma_f32 v[52:53], v[52:53], v[60:61], v[212:213]
	v_pk_fma_f32 v[50:51], v[50:51], v[58:59], v[186:187]
	v_cvt_pk_bf16_f32 v54, v54, v55
	v_cvt_pk_bf16_f32 v55, v56, v57
	v_cvt_pk_bf16_f32 v56, v50, v51
	v_cvt_pk_bf16_f32 v57, v52, v53
	global_store_dwordx4 v[184:185], v[54:57], off
	s_waitcnt vmcnt(8)
	v_lshlrev_b32_e32 v196, 16, v214
	v_and_b32_e32 v197, 0xffff0000, v214
	v_lshlrev_b32_e32 v214, 16, v215
	v_and_b32_e32 v215, 0xffff0000, v215
	v_lshlrev_b32_e32 v186, 16, v216
	v_and_b32_e32 v187, 0xffff0000, v216
	v_lshlrev_b32_e32 v216, 16, v217
	v_and_b32_e32 v217, 0xffff0000, v217
	v_sub_f32_e32 v215, v215, v232
	v_sub_f32_e32 v214, v214, v232
	v_sub_f32_e32 v197, v197, v232
	v_sub_f32_e32 v196, v196, v232
	v_pk_mul_f32 v[196:197], v[232:233], v[196:197] op_sel:[1,0]
	v_pk_mul_f32 v[214:215], v[232:233], v[214:215] op_sel:[1,0]
	v_sub_f32_e32 v217, v217, v232
	v_sub_f32_e32 v216, v216, v232
	v_sub_f32_e32 v187, v187, v232
	v_sub_f32_e32 v186, v186, v232
	v_pk_fma_f32 v[214:215], v[36:37], v[214:215], v[40:41]
	v_pk_fma_f32 v[196:197], v[34:35], v[196:197], v[38:39]
	v_pk_mul_f32 v[186:187], v[232:233], v[186:187] op_sel:[1,0]
	v_pk_mul_f32 v[216:217], v[232:233], v[216:217] op_sel:[1,0]
	v_pk_fma_f32 v[186:187], v[26:27], v[186:187], v[30:31]
	v_pk_fma_f32 v[216:217], v[28:29], v[216:217], v[32:33]
	v_pk_mul_f32 v[214:215], v[214:215], s[56:57] op_sel_hi:[1,0]
	v_pk_mul_f32 v[196:197], v[196:197], s[56:57] op_sel_hi:[1,0]
	v_pk_mul_f32 v[216:217], v[216:217], s[56:57] op_sel_hi:[1,0]
	v_pk_mul_f32 v[186:187], v[186:187], s[56:57] op_sel_hi:[1,0]
	v_pk_fma_f32 v[48:49], v[48:49], v[24:25], v[214:215]
	v_pk_fma_f32 v[46:47], v[46:47], v[22:23], v[196:197]
	v_pk_fma_f32 v[44:45], v[44:45], v[20:21], v[216:217]
	v_pk_fma_f32 v[42:43], v[42:43], v[18:19], v[186:187]
	v_cvt_pk_bf16_f32 v46, v46, v47
	v_cvt_pk_bf16_f32 v47, v48, v49
	v_cvt_pk_bf16_f32 v48, v42, v43
	v_cvt_pk_bf16_f32 v49, v44, v45
	global_store_dwordx4 v[184:185], v[46:49], off offset:256
	v_lshl_add_u64 v[184:185], v[184:185], 0, s[0:1]
	s_waitcnt vmcnt(5)
	v_lshlrev_b32_e32 v196, 16, v242
	v_and_b32_e32 v197, 0xffff0000, v242
	v_lshlrev_b32_e32 v242, 16, v243
	v_and_b32_e32 v243, 0xffff0000, v243
	v_lshlrev_b32_e32 v186, 16, v244
	v_and_b32_e32 v187, 0xffff0000, v244
	v_lshlrev_b32_e32 v244, 16, v245
	v_and_b32_e32 v245, 0xffff0000, v245
	v_sub_f32_e32 v243, v243, v250
	v_sub_f32_e32 v242, v242, v250
	v_sub_f32_e32 v197, v197, v250
	v_sub_f32_e32 v196, v196, v250
	v_pk_mul_f32 v[196:197], v[250:251], v[196:197] op_sel:[1,0]
	v_pk_mul_f32 v[242:243], v[250:251], v[242:243] op_sel:[1,0]
	v_sub_f32_e32 v245, v245, v250
	v_sub_f32_e32 v244, v244, v250
	v_sub_f32_e32 v187, v187, v250
	v_sub_f32_e32 v186, v186, v250
	v_pk_fma_f32 v[242:243], v[76:77], v[242:243], v[80:81]
	v_pk_fma_f32 v[196:197], v[74:75], v[196:197], v[78:79]
	v_pk_mul_f32 v[186:187], v[250:251], v[186:187] op_sel:[1,0]
	v_pk_mul_f32 v[244:245], v[250:251], v[244:245] op_sel:[1,0]
	v_pk_fma_f32 v[186:187], v[66:67], v[186:187], v[70:71]
	v_pk_fma_f32 v[244:245], v[68:69], v[244:245], v[72:73]
	v_pk_mul_f32 v[242:243], v[242:243], s[56:57] op_sel_hi:[1,0]
	v_pk_mul_f32 v[196:197], v[196:197], s[56:57] op_sel_hi:[1,0]
	v_pk_mul_f32 v[244:245], v[244:245], s[56:57] op_sel_hi:[1,0]
	v_pk_mul_f32 v[186:187], v[186:187], s[56:57] op_sel_hi:[1,0]
	v_pk_fma_f32 v[16:17], v[16:17], v[64:65], v[242:243]
	v_pk_fma_f32 v[14:15], v[14:15], v[62:63], v[196:197]
	v_pk_fma_f32 v[12:13], v[12:13], v[60:61], v[244:245]
	v_pk_fma_f32 v[10:11], v[10:11], v[58:59], v[186:187]
	v_cvt_pk_bf16_f32 v14, v14, v15
	v_cvt_pk_bf16_f32 v15, v16, v17
	v_cvt_pk_bf16_f32 v16, v10, v11
	v_cvt_pk_bf16_f32 v17, v12, v13
	global_store_dwordx4 v[184:185], v[14:17], off
	s_waitcnt vmcnt(5)
	v_lshlrev_b32_e32 v196, 16, v246
	v_and_b32_e32 v197, 0xffff0000, v246
	v_lshlrev_b32_e32 v246, 16, v247
	v_and_b32_e32 v247, 0xffff0000, v247
	v_lshlrev_b32_e32 v186, 16, v248
	v_and_b32_e32 v187, 0xffff0000, v248
	v_lshlrev_b32_e32 v248, 16, v249
	v_and_b32_e32 v249, 0xffff0000, v249
	v_sub_f32_e32 v247, v247, v250
	v_sub_f32_e32 v246, v246, v250
	v_sub_f32_e32 v197, v197, v250
	v_sub_f32_e32 v196, v196, v250
	v_pk_mul_f32 v[196:197], v[250:251], v[196:197] op_sel:[1,0]
	v_pk_mul_f32 v[246:247], v[250:251], v[246:247] op_sel:[1,0]
	v_sub_f32_e32 v249, v249, v250
	v_sub_f32_e32 v248, v248, v250
	v_sub_f32_e32 v187, v187, v250
	v_sub_f32_e32 v186, v186, v250
	v_pk_fma_f32 v[246:247], v[36:37], v[246:247], v[40:41]
	v_pk_fma_f32 v[196:197], v[34:35], v[196:197], v[38:39]
	v_pk_mul_f32 v[186:187], v[250:251], v[186:187] op_sel:[1,0]
	v_pk_mul_f32 v[248:249], v[250:251], v[248:249] op_sel:[1,0]
	v_pk_fma_f32 v[186:187], v[26:27], v[186:187], v[30:31]
	v_pk_fma_f32 v[248:249], v[28:29], v[248:249], v[32:33]
	v_pk_mul_f32 v[246:247], v[246:247], s[56:57] op_sel_hi:[1,0]
	v_pk_mul_f32 v[196:197], v[196:197], s[56:57] op_sel_hi:[1,0]
	v_pk_mul_f32 v[248:249], v[248:249], s[56:57] op_sel_hi:[1,0]
	v_pk_mul_f32 v[186:187], v[186:187], s[56:57] op_sel_hi:[1,0]
	v_pk_fma_f32 v[8:9], v[8:9], v[24:25], v[246:247]
	v_pk_fma_f32 v[6:7], v[6:7], v[22:23], v[196:197]
	v_pk_fma_f32 v[4:5], v[4:5], v[20:21], v[248:249]
	v_pk_fma_f32 v[2:3], v[2:3], v[18:19], v[186:187]
	v_cvt_pk_bf16_f32 v6, v6, v7
	v_cvt_pk_bf16_f32 v7, v8, v9
	v_cvt_pk_bf16_f32 v8, v2, v3
	v_cvt_pk_bf16_f32 v9, v4, v5
	global_store_dwordx4 v[184:185], v[6:9], off offset:256
	v_readfirstlane_b32 s98, v191
	s_cmpk_lt_u32 s98, 0x100
	s_cbranch_scc1 .Lrl_e1_780
	s_barrier
.Lrl_e1_780:
	s_cbranch_vccz .LBB0_777
	s_waitcnt vmcnt(0)
	s_cmpk_gt_u32 s19, 0xff
	s_mov_b32 s74, 0x3e75aa41
	s_mov_b32 s72, 0x40490fdb
	s_mov_b32 s80, 0xc0a55e0e
	s_brev_b32 s64, 60
	s_cbranch_scc1 .LBB0_784
	s_barrier

.LBB0_794:
	v_add_u32_e32 v0, s10, v161
	ds_read_b128 v[122:125], v0
	ds_read_b128 v[126:129], v0 offset:1024
	ds_read_b128 v[130:133], v0 offset:2048
	ds_read_b128 v[134:137], v0 offset:3072
	s_add_u32 s0, s20, 0xfffc0080
	s_addc_u32 s1, s21, -1
	s_cmp_eq_u32 s71, 12
	s_cselect_b32 s49, s7, s1
	s_cselect_b32 s48, s67, s0
	s_cselect_b32 s35, s3, s70
	s_cselect_b32 s34, s68, s69
	v_lshl_add_u64 v[158:159], s[20:21], 0, v[150:151]
	s_add_i32 m0, s24, 0xc000
	ds_read_b128 v[154:157], v163
	ds_read_b128 v[164:167], v163 offset:1024
	ds_read_b128 v[168:171], v163 offset:2048
	ds_read_b128 v[172:175], v163 offset:3072
	ds_read_b128 v[176:179], v163 offset:4096
	ds_read_b128 v[180:183], v163 offset:5120
	ds_read_b128 v[184:187], v163 offset:6144
	ds_read_b128 v[202:205], v163 offset:7168
	global_load_lds_dwordx4 v[158:159], off
	v_lshl_add_u64 v[158:159], s[20:21], 0, v[152:153]
	s_add_i32 m0, s24, 0xe000
	s_nop 0
	global_load_lds_dwordx4 v[158:159], off
	s_waitcnt lgkmcnt(8)
	s_barrier
	s_waitcnt lgkmcnt(0)
	s_setprio 1
	s_waitcnt lgkmcnt(0)
	v_mfma_f32_16x16x32_bf16 v[142:145], v[122:125], v[154:157], v[142:145]
	v_mfma_f32_16x16x32_bf16 v[138:141], v[130:133], v[154:157], v[138:141]
	v_mfma_f32_16x16x32_bf16 v[110:113], v[122:125], v[168:171], v[110:113]
	v_mfma_f32_16x16x32_bf16 v[106:109], v[130:133], v[168:171], v[106:109]
	v_mfma_f32_16x16x32_bf16 v[94:97], v[122:125], v[176:179], v[94:97]
	v_mfma_f32_16x16x32_bf16 v[90:93], v[130:133], v[176:179], v[90:93]
	v_mfma_f32_16x16x32_bf16 v[78:81], v[122:125], v[184:187], v[78:81]
	v_mfma_f32_16x16x32_bf16 v[74:77], v[130:133], v[184:187], v[74:77]
	v_mfma_f32_16x16x32_bf16 v[142:145], v[126:129], v[164:167], v[142:145]
	v_mfma_f32_16x16x32_bf16 v[138:141], v[134:137], v[164:167], v[138:141]
	v_mfma_f32_16x16x32_bf16 v[110:113], v[126:129], v[172:175], v[110:113]
	v_mfma_f32_16x16x32_bf16 v[106:109], v[134:137], v[172:175], v[106:109]
	v_mfma_f32_16x16x32_bf16 v[94:97], v[126:129], v[180:183], v[94:97]
	v_mfma_f32_16x16x32_bf16 v[90:93], v[134:137], v[180:183], v[90:93]
	v_mfma_f32_16x16x32_bf16 v[78:81], v[126:129], v[202:205], v[78:81]
	v_mfma_f32_16x16x32_bf16 v[74:77], v[134:137], v[202:205], v[74:77]
	s_setprio 0
	s_barrier
	s_mov_b32 m0, s11
	v_add_u32_e32 v0, s26, v161
	v_lshl_add_u64 v[158:159], s[34:35], 0, v[148:149]
	ds_read_b128 v[206:209], v0
	ds_read_b128 v[210:213], v0 offset:1024
	ds_read_b128 v[214:217], v0 offset:2048
	ds_read_b128 v[218:221], v0 offset:3072
	global_load_lds_dwordx4 v[158:159], off
	v_lshl_add_u64 v[188:189], s[34:35], 0, v[146:147]
	s_mov_b32 m0, s19
	s_nop 0
	global_load_lds_dwordx4 v[188:189], off
	s_barrier
	s_waitcnt lgkmcnt(0)
	s_setprio 1
	s_waitcnt lgkmcnt(0)
	v_mfma_f32_16x16x32_bf16 v[118:121], v[206:209], v[154:157], v[118:121]
	v_mfma_f32_16x16x32_bf16 v[114:117], v[214:217], v[154:157], v[114:117]
	v_mfma_f32_16x16x32_bf16 v[102:105], v[206:209], v[168:171], v[102:105]
	v_mfma_f32_16x16x32_bf16 v[98:101], v[214:217], v[168:171], v[98:101]
	v_mfma_f32_16x16x32_bf16 v[86:89], v[206:209], v[176:179], v[86:89]
	v_mfma_f32_16x16x32_bf16 v[82:85], v[214:217], v[176:179], v[82:85]
	v_mfma_f32_16x16x32_bf16 v[70:73], v[206:209], v[184:187], v[70:73]
	v_mfma_f32_16x16x32_bf16 v[66:69], v[214:217], v[184:187], v[66:69]
	v_mfma_f32_16x16x32_bf16 v[118:121], v[210:213], v[164:167], v[118:121]
	v_mfma_f32_16x16x32_bf16 v[114:117], v[218:221], v[164:167], v[114:117]
	v_mfma_f32_16x16x32_bf16 v[102:105], v[210:213], v[172:175], v[102:105]
	v_mfma_f32_16x16x32_bf16 v[98:101], v[218:221], v[172:175], v[98:101]
	v_mfma_f32_16x16x32_bf16 v[86:89], v[210:213], v[180:183], v[86:89]
	v_mfma_f32_16x16x32_bf16 v[82:85], v[218:221], v[180:183], v[82:85]
	v_mfma_f32_16x16x32_bf16 v[70:73], v[210:213], v[202:205], v[70:73]
	v_mfma_f32_16x16x32_bf16 v[66:69], v[218:221], v[202:205], v[66:69]
	s_setprio 0
	s_mov_b32 m0, s24
	v_lshl_add_u64 v[194:195], s[48:49], 0, v[148:149]
	s_barrier
	ds_read_b128 v[154:157], v163 offset:16384
	ds_read_b128 v[164:167], v163 offset:17408
	ds_read_b128 v[168:171], v163 offset:18432
	ds_read_b128 v[172:175], v163 offset:19456
	ds_read_b128 v[176:179], v163 offset:20480
	ds_read_b128 v[180:183], v163 offset:21504
	ds_read_b128 v[184:187], v163 offset:22528
	ds_read_b128 v[202:205], v163 offset:23552
	global_load_lds_dwordx4 v[194:195], off
	v_lshl_add_u64 v[196:197], s[48:49], 0, v[146:147]
	s_mov_b32 m0, s25
	s_nop 0
	global_load_lds_dwordx4 v[196:197], off
	s_barrier
	s_waitcnt lgkmcnt(0)
	s_setprio 1
	s_waitcnt lgkmcnt(0)
	v_mfma_f32_16x16x32_bf16 v[62:65], v[122:125], v[154:157], v[62:65]
	v_mfma_f32_16x16x32_bf16 v[58:61], v[130:133], v[154:157], v[58:61]
	v_mfma_f32_16x16x32_bf16 v[46:49], v[122:125], v[168:171], v[46:49]
	v_mfma_f32_16x16x32_bf16 v[42:45], v[130:133], v[168:171], v[42:45]
	v_mfma_f32_16x16x32_bf16 v[30:33], v[122:125], v[176:179], v[30:33]
	v_mfma_f32_16x16x32_bf16 v[26:29], v[130:133], v[176:179], v[26:29]
	v_mfma_f32_16x16x32_bf16 v[14:17], v[122:125], v[184:187], v[14:17]
	v_mfma_f32_16x16x32_bf16 v[10:13], v[130:133], v[184:187], v[10:13]
	v_mfma_f32_16x16x32_bf16 v[62:65], v[126:129], v[164:167], v[62:65]
	v_mfma_f32_16x16x32_bf16 v[58:61], v[134:137], v[164:167], v[58:61]
	v_mfma_f32_16x16x32_bf16 v[46:49], v[126:129], v[172:175], v[46:49]
	v_mfma_f32_16x16x32_bf16 v[42:45], v[134:137], v[172:175], v[42:45]
	v_mfma_f32_16x16x32_bf16 v[30:33], v[126:129], v[180:183], v[30:33]
	v_mfma_f32_16x16x32_bf16 v[26:29], v[134:137], v[180:183], v[26:29]
	v_mfma_f32_16x16x32_bf16 v[14:17], v[126:129], v[202:205], v[14:17]
	v_mfma_f32_16x16x32_bf16 v[10:13], v[134:137], v[202:205], v[10:13]
	s_setprio 0
	s_barrier
	s_add_u32 s0, s34, 0x40000
	s_addc_u32 s1, s35, 0
	s_mov_b32 m0, s28
	v_lshl_add_u64 v[122:123], s[0:1], 0, v[148:149]
	global_load_lds_dwordx4 v[122:123], off
	v_lshl_add_u64 v[122:123], s[0:1], 0, v[146:147]
	s_mov_b32 m0, s29
	s_nop 0
	global_load_lds_dwordx4 v[122:123], off
	s_waitcnt vmcnt(6)
	s_barrier
	s_setprio 1
	v_mfma_f32_16x16x32_bf16 v[54:57], v[206:209], v[154:157], v[54:57]
	v_mfma_f32_16x16x32_bf16 v[50:53], v[214:217], v[154:157], v[50:53]
	v_mfma_f32_16x16x32_bf16 v[38:41], v[206:209], v[168:171], v[38:41]
	v_mfma_f32_16x16x32_bf16 v[34:37], v[214:217], v[168:171], v[34:37]
	v_mfma_f32_16x16x32_bf16 v[22:25], v[206:209], v[176:179], v[22:25]
	v_mfma_f32_16x16x32_bf16 v[18:21], v[214:217], v[176:179], v[18:21]
	v_mfma_f32_16x16x32_bf16 v[6:9], v[206:209], v[184:187], v[6:9]
	v_mfma_f32_16x16x32_bf16 v[2:5], v[214:217], v[184:187], v[2:5]
	v_mfma_f32_16x16x32_bf16 v[54:57], v[210:213], v[164:167], v[54:57]
	v_mfma_f32_16x16x32_bf16 v[50:53], v[218:221], v[164:167], v[50:53]
	v_mfma_f32_16x16x32_bf16 v[38:41], v[210:213], v[172:175], v[38:41]
	v_mfma_f32_16x16x32_bf16 v[34:37], v[218:221], v[172:175], v[34:37]
	v_mfma_f32_16x16x32_bf16 v[22:25], v[210:213], v[180:183], v[22:25]
	v_mfma_f32_16x16x32_bf16 v[18:21], v[218:221], v[180:183], v[18:21]
	v_mfma_f32_16x16x32_bf16 v[6:9], v[210:213], v[202:205], v[6:9]
	v_mfma_f32_16x16x32_bf16 v[2:5], v[218:221], v[202:205], v[2:5]
	s_setprio 0
	v_add_u32_e32 v0, s43, v161
	s_barrier
	ds_read_b128 v[122:125], v0
	ds_read_b128 v[126:129], v0 offset:1024
	ds_read_b128 v[130:133], v0 offset:2048
	ds_read_b128 v[134:137], v0 offset:3072
	s_add_u32 s0, s48, 0x40000
	s_addc_u32 s1, s49, 0
	s_mov_b32 m0, s30
	v_lshl_add_u64 v[206:207], s[0:1], 0, v[148:149]
	ds_read_b128 v[154:157], v163 offset:32768
	ds_read_b128 v[164:167], v163 offset:33792
	ds_read_b128 v[168:171], v163 offset:34816
	ds_read_b128 v[172:175], v163 offset:35840
	ds_read_b128 v[176:179], v163 offset:36864
	ds_read_b128 v[180:183], v163 offset:37888
	ds_read_b128 v[184:187], v163 offset:38912
	ds_read_b128 v[202:205], v163 offset:39936
	global_load_lds_dwordx4 v[206:207], off
	v_lshl_add_u64 v[206:207], s[0:1], 0, v[146:147]
	s_mov_b32 m0, s36
	s_nop 0
	global_load_lds_dwordx4 v[206:207], off
	s_waitcnt lgkmcnt(8)
	s_barrier
	s_waitcnt lgkmcnt(0)
	s_setprio 1
	s_waitcnt lgkmcnt(0)
	v_mfma_f32_16x16x32_bf16 v[142:145], v[122:125], v[154:157], v[142:145]
	v_mfma_f32_16x16x32_bf16 v[138:141], v[130:133], v[154:157], v[138:141]
	v_mfma_f32_16x16x32_bf16 v[110:113], v[122:125], v[168:171], v[110:113]
	v_mfma_f32_16x16x32_bf16 v[106:109], v[130:133], v[168:171], v[106:109]
	v_mfma_f32_16x16x32_bf16 v[94:97], v[122:125], v[176:179], v[94:97]
	v_mfma_f32_16x16x32_bf16 v[90:93], v[130:133], v[176:179], v[90:93]
	v_mfma_f32_16x16x32_bf16 v[78:81], v[122:125], v[184:187], v[78:81]
	v_mfma_f32_16x16x32_bf16 v[74:77], v[130:133], v[184:187], v[74:77]
	v_mfma_f32_16x16x32_bf16 v[142:145], v[126:129], v[164:167], v[142:145]
	v_mfma_f32_16x16x32_bf16 v[138:141], v[134:137], v[164:167], v[138:141]
	v_mfma_f32_16x16x32_bf16 v[110:113], v[126:129], v[172:175], v[110:113]
	v_mfma_f32_16x16x32_bf16 v[106:109], v[134:137], v[172:175], v[106:109]
	v_mfma_f32_16x16x32_bf16 v[94:97], v[126:129], v[180:183], v[94:97]
	v_mfma_f32_16x16x32_bf16 v[90:93], v[134:137], v[180:183], v[90:93]
	v_mfma_f32_16x16x32_bf16 v[78:81], v[126:129], v[202:205], v[78:81]
	v_mfma_f32_16x16x32_bf16 v[74:77], v[134:137], v[202:205], v[74:77]
	s_setprio 0
	s_barrier
	s_mov_b32 m0, s50
	v_add_u32_e32 v0, s58, v161
	v_lshl_add_u64 v[158:159], v[158:159], 0, s[88:89]
	ds_read_b128 v[206:209], v0
	ds_read_b128 v[210:213], v0 offset:1024
	ds_read_b128 v[214:217], v0 offset:2048
	ds_read_b128 v[218:221], v0 offset:3072
	global_load_lds_dwordx4 v[158:159], off
	v_lshl_add_u64 v[158:159], v[188:189], 0, s[88:89]
	s_mov_b32 m0, s51
	s_nop 0
	global_load_lds_dwordx4 v[158:159], off
	s_barrier
	s_waitcnt lgkmcnt(0)
	s_setprio 1
	s_waitcnt lgkmcnt(0)
	v_mfma_f32_16x16x32_bf16 v[118:121], v[206:209], v[154:157], v[118:121]
	v_mfma_f32_16x16x32_bf16 v[114:117], v[214:217], v[154:157], v[114:117]
	v_mfma_f32_16x16x32_bf16 v[102:105], v[206:209], v[168:171], v[102:105]
	v_mfma_f32_16x16x32_bf16 v[98:101], v[214:217], v[168:171], v[98:101]
	v_mfma_f32_16x16x32_bf16 v[86:89], v[206:209], v[176:179], v[86:89]
	v_mfma_f32_16x16x32_bf16 v[82:85], v[214:217], v[176:179], v[82:85]
	v_mfma_f32_16x16x32_bf16 v[70:73], v[206:209], v[184:187], v[70:73]
	v_mfma_f32_16x16x32_bf16 v[66:69], v[214:217], v[184:187], v[66:69]
	v_mfma_f32_16x16x32_bf16 v[118:121], v[210:213], v[164:167], v[118:121]
	v_mfma_f32_16x16x32_bf16 v[114:117], v[218:221], v[164:167], v[114:117]
	v_mfma_f32_16x16x32_bf16 v[102:105], v[210:213], v[172:175], v[102:105]
	v_mfma_f32_16x16x32_bf16 v[98:101], v[218:221], v[172:175], v[98:101]
	v_mfma_f32_16x16x32_bf16 v[86:89], v[210:213], v[180:183], v[86:89]
	v_mfma_f32_16x16x32_bf16 v[82:85], v[218:221], v[180:183], v[82:85]
	v_mfma_f32_16x16x32_bf16 v[70:73], v[210:213], v[202:205], v[70:73]
	v_mfma_f32_16x16x32_bf16 v[66:69], v[218:221], v[202:205], v[66:69]
	s_setprio 0
	s_mov_b32 m0, s54
	v_lshl_add_u64 v[158:159], v[194:195], 0, s[88:89]
	s_barrier
	ds_read_b128 v[154:157], v163 offset:49152
	ds_read_b128 v[164:167], v163 offset:50176
	ds_read_b128 v[168:171], v163 offset:51200
	ds_read_b128 v[172:175], v163 offset:52224
	ds_read_b128 v[176:179], v163 offset:53248
	ds_read_b128 v[180:183], v163 offset:54272
	ds_read_b128 v[184:187], v163 offset:55296
	ds_read_b128 v[202:205], v163 offset:56320
	global_load_lds_dwordx4 v[158:159], off
	v_lshl_add_u64 v[158:159], v[196:197], 0, s[88:89]
	s_mov_b32 m0, s55
	s_nop 0
	global_load_lds_dwordx4 v[158:159], off
	s_barrier
	s_waitcnt lgkmcnt(0)
	s_setprio 1
	s_waitcnt lgkmcnt(0)
	v_mfma_f32_16x16x32_bf16 v[62:65], v[122:125], v[154:157], v[62:65]
	v_mfma_f32_16x16x32_bf16 v[58:61], v[130:133], v[154:157], v[58:61]
	v_mfma_f32_16x16x32_bf16 v[46:49], v[122:125], v[168:171], v[46:49]
	v_mfma_f32_16x16x32_bf16 v[42:45], v[130:133], v[168:171], v[42:45]
	v_mfma_f32_16x16x32_bf16 v[30:33], v[122:125], v[176:179], v[30:33]
	v_mfma_f32_16x16x32_bf16 v[26:29], v[130:133], v[176:179], v[26:29]
	v_mfma_f32_16x16x32_bf16 v[14:17], v[122:125], v[184:187], v[14:17]
	v_mfma_f32_16x16x32_bf16 v[10:13], v[130:133], v[184:187], v[10:13]
	v_mfma_f32_16x16x32_bf16 v[62:65], v[126:129], v[164:167], v[62:65]
	v_mfma_f32_16x16x32_bf16 v[58:61], v[134:137], v[164:167], v[58:61]
	v_mfma_f32_16x16x32_bf16 v[46:49], v[126:129], v[172:175], v[46:49]
	v_mfma_f32_16x16x32_bf16 v[42:45], v[134:137], v[172:175], v[42:45]
	v_mfma_f32_16x16x32_bf16 v[30:33], v[126:129], v[180:183], v[30:33]
	v_mfma_f32_16x16x32_bf16 v[26:29], v[134:137], v[180:183], v[26:29]
	v_mfma_f32_16x16x32_bf16 v[14:17], v[126:129], v[202:205], v[14:17]
	v_mfma_f32_16x16x32_bf16 v[10:13], v[134:137], v[202:205], v[10:13]
	s_setprio 0
	s_barrier
	s_add_u32 s0, s34, 0x40080
	s_addc_u32 s1, s35, 0
	s_mov_b32 m0, s60
	v_lshl_add_u64 v[122:123], s[0:1], 0, v[148:149]
	global_load_lds_dwordx4 v[122:123], off
	v_lshl_add_u64 v[122:123], s[0:1], 0, v[146:147]
	s_mov_b32 m0, s61
	s_nop 0
	global_load_lds_dwordx4 v[122:123], off
	s_waitcnt vmcnt(6)
	s_barrier
	s_setprio 1
	v_mfma_f32_16x16x32_bf16 v[54:57], v[206:209], v[154:157], v[54:57]
	v_mfma_f32_16x16x32_bf16 v[50:53], v[214:217], v[154:157], v[50:53]
	v_mfma_f32_16x16x32_bf16 v[38:41], v[206:209], v[168:171], v[38:41]
	v_mfma_f32_16x16x32_bf16 v[34:37], v[214:217], v[168:171], v[34:37]
	v_mfma_f32_16x16x32_bf16 v[22:25], v[206:209], v[176:179], v[22:25]
	v_mfma_f32_16x16x32_bf16 v[18:21], v[214:217], v[176:179], v[18:21]
	v_mfma_f32_16x16x32_bf16 v[6:9], v[206:209], v[184:187], v[6:9]
	v_mfma_f32_16x16x32_bf16 v[2:5], v[214:217], v[184:187], v[2:5]
	v_mfma_f32_16x16x32_bf16 v[54:57], v[210:213], v[164:167], v[54:57]
	v_mfma_f32_16x16x32_bf16 v[50:53], v[218:221], v[164:167], v[50:53]
	v_mfma_f32_16x16x32_bf16 v[38:41], v[210:213], v[172:175], v[38:41]
	v_mfma_f32_16x16x32_bf16 v[34:37], v[218:221], v[172:175], v[34:37]
	v_mfma_f32_16x16x32_bf16 v[22:25], v[210:213], v[180:183], v[22:25]
	v_mfma_f32_16x16x32_bf16 v[18:21], v[218:221], v[180:183], v[18:21]
	v_mfma_f32_16x16x32_bf16 v[6:9], v[210:213], v[202:205], v[6:9]
	v_mfma_f32_16x16x32_bf16 v[2:5], v[218:221], v[202:205], v[2:5]
	s_setprio 0
	s_add_i32 s71, s71, 2
	s_add_u32 s20, s20, 0x100
	s_addc_u32 s21, s21, 0
	s_add_u32 s69, s69, 0x100
	s_addc_u32 s70, s70, 0
	s_cmp_gt_u32 s71, 13
	s_barrier
	s_cbranch_scc0 .LBB0_794
	v_readfirstlane_b32 s98, v191
	s_cmpk_gt_u32 s98, 0xff
	s_cbranch_scc1 .Lrl_e0_794
	s_barrier
.Lrl_e0_794:
	s_lshl_b32 s3, s42, 8
	s_add_i32 s0, s3, 0xfffff000
	s_lshr_b32 s0, s0, 11
	s_mulk_i32 s0, 0x1800
	s_addk_i32 s0, 0x1800
	v_add_u32_e32 v158, s3, v160
	s_cmp_gt_i32 s42, 15
	v_ashrrev_i32_e32 v159, 31, v158
	v_add_u32_e32 v0, 0xfffff000, v158
	v_lshl_or_b32 v194, s66, 8, v162
	s_cselect_b32 s86, s0, 0
	v_lshlrev_b64 v[218:219], 12, v[0:1]
	v_lshlrev_b64 v[220:221], 12, v[158:159]
	s_lshl_b64 s[0:1], s[86:87], 2
	v_ashrrev_i32_e32 v195, 31, v194
	v_lshl_add_u64 v[220:221], s[44:45], 0, v[220:221]
	v_lshl_add_u64 v[218:219], s[46:47], 0, v[218:219]
	v_cmp_gt_i32_e32 vcc, s33, v158
	v_lshlrev_b64 v[196:197], 2, v[194:195]
	s_add_u32 s0, s37, s0
	v_cndmask_b32_e32 v219, v219, v221, vcc
	v_cndmask_b32_e32 v218, v218, v220, vcc
	v_lshl_add_u64 v[154:155], v[218:219], 0, v[196:197]
	s_addc_u32 s1, s38, s1
	v_lshl_add_u64 v[218:219], s[0:1], 0, v[196:197]
	global_load_dwordx4 v[134:137], v[218:219], off
	global_load_dwordx4 v[130:133], v[218:219], off offset:16
	global_load_dwordx4 v[122:125], v[218:219], off offset:528
	global_load_dwordx4 v[126:129], v[218:219], off offset:512
	v_lshlrev_b64 v[196:197], 1, v[194:195]
	v_lshlrev_b64 v[156:157], 11, v[158:159]
	v_lshl_add_u64 v[156:157], s[12:13], 0, v[156:157]
	v_lshl_add_u64 v[156:157], v[156:157], 0, v[196:197]
	s_mov_b32 s66, s2
	s_mov_b64 s[34:35], s[16:17]
	s_mov_b64 s[20:21], s[14:15]
	s_mov_b32 s42, s6
	global_load_dwordx4 v[164:167], v[154:155], off
	global_load_dwordx4 v[168:171], v[154:155], off offset:16
	global_load_dwordx4 v[172:175], v[154:155], off offset:512
	global_load_dwordx4 v[176:179], v[154:155], off offset:528
	s_mov_b32 s0, 0x10000
	s_mov_b32 s1, 0
	v_lshl_add_u64 v[154:155], v[154:155], 0, s[0:1]
	global_load_dwordx4 v[180:183], v[154:155], off
	global_load_dwordx4 v[184:187], v[154:155], off offset:16
	global_load_dwordx4 v[202:205], v[154:155], off offset:512
	global_load_dwordx4 v[206:209], v[154:155], off offset:528
	v_lshl_add_u64 v[154:155], v[154:155], 0, s[0:1]
	global_load_dwordx4 v[210:213], v[154:155], off
	global_load_dwordx4 v[214:217], v[154:155], off offset:16
	global_load_dwordx4 v[194:197], v[154:155], off offset:512
	global_load_dwordx4 v[218:221], v[154:155], off offset:528
	v_lshl_add_u64 v[154:155], v[154:155], 0, s[0:1]
	s_waitcnt vmcnt(10)
	v_pk_mul_f32 v[166:167], v[166:167], s[56:57] op_sel_hi:[1,0]
	v_pk_mul_f32 v[164:165], v[164:165], s[56:57] op_sel_hi:[1,0]
	v_pk_mul_f32 v[170:171], v[170:171], s[56:57] op_sel_hi:[1,0]
	v_pk_mul_f32 v[168:169], v[168:169], s[56:57] op_sel_hi:[1,0]
	v_pk_fma_f32 v[144:145], v[144:145], v[136:137], v[166:167]
	v_pk_fma_f32 v[142:143], v[142:143], v[134:135], v[164:165]
	v_pk_fma_f32 v[140:141], v[140:141], v[132:133], v[170:171]
	v_pk_fma_f32 v[138:139], v[138:139], v[130:131], v[168:169]
	v_cvt_pk_bf16_f32 v164, v142, v143
	v_cvt_pk_bf16_f32 v165, v144, v145
	v_cvt_pk_bf16_f32 v166, v138, v139
	v_cvt_pk_bf16_f32 v167, v140, v141
	global_store_dwordx4 v[156:157], v[164:167], off
	s_nop 0
	global_load_dwordx4 v[164:167], v[154:155], off
	global_load_dwordx4 v[168:171], v[154:155], off offset:16
	s_waitcnt vmcnt(11)
	v_pk_mul_f32 v[174:175], v[174:175], s[56:57] op_sel_hi:[1,0]
	v_pk_mul_f32 v[172:173], v[172:173], s[56:57] op_sel_hi:[1,0]
	v_pk_mul_f32 v[178:179], v[178:179], s[56:57] op_sel_hi:[1,0]
	v_pk_mul_f32 v[176:177], v[176:177], s[56:57] op_sel_hi:[1,0]
	v_pk_fma_f32 v[120:121], v[120:121], v[128:129], v[174:175]
	v_pk_fma_f32 v[118:119], v[118:119], v[126:127], v[172:173]
	v_pk_fma_f32 v[116:117], v[116:117], v[124:125], v[178:179]
	v_pk_fma_f32 v[114:115], v[114:115], v[122:123], v[176:177]
	v_cvt_pk_bf16_f32 v172, v118, v119
	v_cvt_pk_bf16_f32 v173, v120, v121
	v_cvt_pk_bf16_f32 v174, v114, v115
	v_cvt_pk_bf16_f32 v175, v116, v117
	global_store_dwordx4 v[156:157], v[172:175], off offset:256
	s_mov_b32 s0, 0x8000
	v_lshl_add_u64 v[156:157], v[156:157], 0, s[0:1]
	global_load_dwordx4 v[172:175], v[154:155], off offset:512
	global_load_dwordx4 v[176:179], v[154:155], off offset:528
	s_mov_b32 s0, 0x50000
	v_lshl_add_u64 v[154:155], v[154:155], 0, s[0:1]
	s_waitcnt vmcnt(12)
	v_pk_mul_f32 v[182:183], v[182:183], s[56:57] op_sel_hi:[1,0]
	v_pk_mul_f32 v[180:181], v[180:181], s[56:57] op_sel_hi:[1,0]
	v_pk_mul_f32 v[186:187], v[186:187], s[56:57] op_sel_hi:[1,0]
	v_pk_mul_f32 v[184:185], v[184:185], s[56:57] op_sel_hi:[1,0]
	v_pk_fma_f32 v[112:113], v[112:113], v[136:137], v[182:183]
	v_pk_fma_f32 v[110:111], v[110:111], v[134:135], v[180:181]
	v_pk_fma_f32 v[108:109], v[108:109], v[132:133], v[186:187]
	v_pk_fma_f32 v[106:107], v[106:107], v[130:131], v[184:185]
	v_cvt_pk_bf16_f32 v180, v110, v111
	v_cvt_pk_bf16_f32 v181, v112, v113
	v_cvt_pk_bf16_f32 v182, v106, v107
	v_cvt_pk_bf16_f32 v183, v108, v109
	global_store_dwordx4 v[156:157], v[180:183], off
	s_nop 0
	global_load_dwordx4 v[180:183], v[154:155], off
	global_load_dwordx4 v[184:187], v[154:155], off offset:16
	s_waitcnt vmcnt(13)
	v_pk_mul_f32 v[204:205], v[204:205], s[56:57] op_sel_hi:[1,0]
	v_pk_mul_f32 v[202:203], v[202:203], s[56:57] op_sel_hi:[1,0]
	v_pk_mul_f32 v[208:209], v[208:209], s[56:57] op_sel_hi:[1,0]
	v_pk_mul_f32 v[206:207], v[206:207], s[56:57] op_sel_hi:[1,0]
	v_pk_fma_f32 v[104:105], v[104:105], v[128:129], v[204:205]
	v_pk_fma_f32 v[102:103], v[102:103], v[126:127], v[202:203]
	v_pk_fma_f32 v[100:101], v[100:101], v[124:125], v[208:209]
	v_pk_fma_f32 v[98:99], v[98:99], v[122:123], v[206:207]
	v_cvt_pk_bf16_f32 v202, v102, v103
	v_cvt_pk_bf16_f32 v203, v104, v105
	v_cvt_pk_bf16_f32 v204, v98, v99
	v_cvt_pk_bf16_f32 v205, v100, v101
	global_store_dwordx4 v[156:157], v[202:205], off offset:256
	s_mov_b32 s0, 0x8000
	v_lshl_add_u64 v[156:157], v[156:157], 0, s[0:1]
	global_load_dwordx4 v[202:205], v[154:155], off offset:512
	global_load_dwordx4 v[206:209], v[154:155], off offset:528
	s_mov_b32 s0, 0x10000
	v_lshl_add_u64 v[154:155], v[154:155], 0, s[0:1]
	s_waitcnt vmcnt(14)
	v_pk_mul_f32 v[212:213], v[212:213], s[56:57] op_sel_hi:[1,0]
	v_pk_mul_f32 v[210:211], v[210:211], s[56:57] op_sel_hi:[1,0]
	v_pk_mul_f32 v[216:217], v[216:217], s[56:57] op_sel_hi:[1,0]
	v_pk_mul_f32 v[214:215], v[214:215], s[56:57] op_sel_hi:[1,0]
	v_pk_fma_f32 v[96:97], v[96:97], v[136:137], v[212:213]
	v_pk_fma_f32 v[94:95], v[94:95], v[134:135], v[210:211]
	v_pk_fma_f32 v[92:93], v[92:93], v[132:133], v[216:217]
	v_pk_fma_f32 v[90:91], v[90:91], v[130:131], v[214:215]
	v_cvt_pk_bf16_f32 v210, v94, v95
	v_cvt_pk_bf16_f32 v211, v96, v97
	v_cvt_pk_bf16_f32 v212, v90, v91
	v_cvt_pk_bf16_f32 v213, v92, v93
	global_store_dwordx4 v[156:157], v[210:213], off
	s_nop 0
	global_load_dwordx4 v[210:213], v[154:155], off
	global_load_dwordx4 v[214:217], v[154:155], off offset:16
	s_waitcnt vmcnt(15)
	v_pk_mul_f32 v[196:197], v[196:197], s[56:57] op_sel_hi:[1,0]
	v_pk_mul_f32 v[194:195], v[194:195], s[56:57] op_sel_hi:[1,0]
	v_pk_mul_f32 v[220:221], v[220:221], s[56:57] op_sel_hi:[1,0]
	v_pk_mul_f32 v[218:219], v[218:219], s[56:57] op_sel_hi:[1,0]
	v_pk_fma_f32 v[88:89], v[88:89], v[128:129], v[196:197]
	v_pk_fma_f32 v[86:87], v[86:87], v[126:127], v[194:195]
	v_pk_fma_f32 v[84:85], v[84:85], v[124:125], v[220:221]
	v_pk_fma_f32 v[82:83], v[82:83], v[122:123], v[218:219]
	v_cvt_pk_bf16_f32 v194, v86, v87
	v_cvt_pk_bf16_f32 v195, v88, v89
	v_cvt_pk_bf16_f32 v196, v82, v83
	v_cvt_pk_bf16_f32 v197, v84, v85
	global_store_dwordx4 v[156:157], v[194:197], off offset:256
	s_mov_b32 s0, 0x8000
	v_lshl_add_u64 v[156:157], v[156:157], 0, s[0:1]
	global_load_dwordx4 v[194:197], v[154:155], off offset:512
	global_load_dwordx4 v[218:221], v[154:155], off offset:528
	s_mov_b32 s0, 0x10000
	v_lshl_add_u64 v[154:155], v[154:155], 0, s[0:1]
	s_waitcnt vmcnt(15)
	v_pk_mul_f32 v[166:167], v[166:167], s[56:57] op_sel_hi:[1,0]
	v_pk_mul_f32 v[164:165], v[164:165], s[56:57] op_sel_hi:[1,0]
	v_pk_mul_f32 v[170:171], v[170:171], s[56:57] op_sel_hi:[1,0]
	v_pk_mul_f32 v[168:169], v[168:169], s[56:57] op_sel_hi:[1,0]
	v_pk_fma_f32 v[80:81], v[80:81], v[136:137], v[166:167]
	v_pk_fma_f32 v[78:79], v[78:79], v[134:135], v[164:165]
	v_pk_fma_f32 v[76:77], v[76:77], v[132:133], v[170:171]
	v_pk_fma_f32 v[74:75], v[74:75], v[130:131], v[168:169]
	v_cvt_pk_bf16_f32 v164, v78, v79
	v_cvt_pk_bf16_f32 v165, v80, v81
	v_cvt_pk_bf16_f32 v166, v74, v75
	v_cvt_pk_bf16_f32 v167, v76, v77
	global_store_dwordx4 v[156:157], v[164:167], off
	s_nop 0
	global_load_dwordx4 v[164:167], v[154:155], off
	global_load_dwordx4 v[168:171], v[154:155], off offset:16
	s_waitcnt vmcnt(15)
	v_pk_mul_f32 v[174:175], v[174:175], s[56:57] op_sel_hi:[1,0]
	v_pk_mul_f32 v[172:173], v[172:173], s[56:57] op_sel_hi:[1,0]
	v_pk_mul_f32 v[178:179], v[178:179], s[56:57] op_sel_hi:[1,0]
	v_pk_mul_f32 v[176:177], v[176:177], s[56:57] op_sel_hi:[1,0]
	v_pk_fma_f32 v[72:73], v[72:73], v[128:129], v[174:175]
	v_pk_fma_f32 v[70:71], v[70:71], v[126:127], v[172:173]
	v_pk_fma_f32 v[68:69], v[68:69], v[124:125], v[178:179]
	v_pk_fma_f32 v[66:67], v[66:67], v[122:123], v[176:177]
	v_cvt_pk_bf16_f32 v172, v70, v71
	v_cvt_pk_bf16_f32 v173, v72, v73
	v_cvt_pk_bf16_f32 v174, v66, v67
	v_cvt_pk_bf16_f32 v175, v68, v69
	global_store_dwordx4 v[156:157], v[172:175], off offset:256
	s_mov_b32 s0, 0x28000
	v_lshl_add_u64 v[156:157], v[156:157], 0, s[0:1]
	global_load_dwordx4 v[172:175], v[154:155], off offset:512
	global_load_dwordx4 v[176:179], v[154:155], off offset:528
	s_mov_b32 s0, 0x10000
	v_lshl_add_u64 v[154:155], v[154:155], 0, s[0:1]
	s_waitcnt vmcnt(15)
	v_pk_mul_f32 v[182:183], v[182:183], s[56:57] op_sel_hi:[1,0]
	v_pk_mul_f32 v[180:181], v[180:181], s[56:57] op_sel_hi:[1,0]
	v_pk_mul_f32 v[186:187], v[186:187], s[56:57] op_sel_hi:[1,0]
	v_pk_mul_f32 v[184:185], v[184:185], s[56:57] op_sel_hi:[1,0]
	v_pk_fma_f32 v[64:65], v[64:65], v[136:137], v[182:183]
	v_pk_fma_f32 v[62:63], v[62:63], v[134:135], v[180:181]
	v_pk_fma_f32 v[60:61], v[60:61], v[132:133], v[186:187]
	v_pk_fma_f32 v[58:59], v[58:59], v[130:131], v[184:185]
	v_cvt_pk_bf16_f32 v180, v62, v63
	v_cvt_pk_bf16_f32 v181, v64, v65
	v_cvt_pk_bf16_f32 v182, v58, v59
	v_cvt_pk_bf16_f32 v183, v60, v61
	global_store_dwordx4 v[156:157], v[180:183], off
	s_nop 0
	global_load_dwordx4 v[180:183], v[154:155], off
	global_load_dwordx4 v[184:187], v[154:155], off offset:16
	s_waitcnt vmcnt(15)
	v_pk_mul_f32 v[204:205], v[204:205], s[56:57] op_sel_hi:[1,0]
	v_pk_mul_f32 v[202:203], v[202:203], s[56:57] op_sel_hi:[1,0]
	v_pk_mul_f32 v[208:209], v[208:209], s[56:57] op_sel_hi:[1,0]
	v_pk_mul_f32 v[206:207], v[206:207], s[56:57] op_sel_hi:[1,0]
	v_pk_fma_f32 v[56:57], v[56:57], v[128:129], v[204:205]
	v_pk_fma_f32 v[54:55], v[54:55], v[126:127], v[202:203]
	v_pk_fma_f32 v[52:53], v[52:53], v[124:125], v[208:209]
	v_pk_fma_f32 v[50:51], v[50:51], v[122:123], v[206:207]
	v_cvt_pk_bf16_f32 v202, v54, v55
	v_cvt_pk_bf16_f32 v203, v56, v57
	v_cvt_pk_bf16_f32 v204, v50, v51
	v_cvt_pk_bf16_f32 v205, v52, v53
	global_store_dwordx4 v[156:157], v[202:205], off offset:256
	s_mov_b32 s0, 0x8000
	v_lshl_add_u64 v[156:157], v[156:157], 0, s[0:1]
	global_load_dwordx4 v[202:205], v[154:155], off offset:512
	global_load_dwordx4 v[206:209], v[154:155], off offset:528
	s_waitcnt vmcnt(15)
	v_pk_mul_f32 v[212:213], v[212:213], s[56:57] op_sel_hi:[1,0]
	v_pk_mul_f32 v[210:211], v[210:211], s[56:57] op_sel_hi:[1,0]
	v_pk_mul_f32 v[216:217], v[216:217], s[56:57] op_sel_hi:[1,0]
	v_pk_mul_f32 v[214:215], v[214:215], s[56:57] op_sel_hi:[1,0]
	v_pk_fma_f32 v[48:49], v[48:49], v[136:137], v[212:213]
	v_pk_fma_f32 v[46:47], v[46:47], v[134:135], v[210:211]
	v_pk_fma_f32 v[44:45], v[44:45], v[132:133], v[216:217]
	v_pk_fma_f32 v[42:43], v[42:43], v[130:131], v[214:215]
	v_cvt_pk_bf16_f32 v210, v46, v47
	v_cvt_pk_bf16_f32 v211, v48, v49
	v_cvt_pk_bf16_f32 v212, v42, v43
	v_cvt_pk_bf16_f32 v213, v44, v45
	global_store_dwordx4 v[156:157], v[210:213], off
	s_nop 0
	s_waitcnt vmcnt(13)
	v_pk_mul_f32 v[196:197], v[196:197], s[56:57] op_sel_hi:[1,0]
	v_pk_mul_f32 v[194:195], v[194:195], s[56:57] op_sel_hi:[1,0]
	v_pk_mul_f32 v[220:221], v[220:221], s[56:57] op_sel_hi:[1,0]
	v_pk_mul_f32 v[218:219], v[218:219], s[56:57] op_sel_hi:[1,0]
	v_pk_fma_f32 v[40:41], v[40:41], v[128:129], v[196:197]
	v_pk_fma_f32 v[38:39], v[38:39], v[126:127], v[194:195]
	v_pk_fma_f32 v[36:37], v[36:37], v[124:125], v[220:221]
	v_pk_fma_f32 v[34:35], v[34:35], v[122:123], v[218:219]
	v_cvt_pk_bf16_f32 v194, v38, v39
	v_cvt_pk_bf16_f32 v195, v40, v41
	v_cvt_pk_bf16_f32 v196, v34, v35
	v_cvt_pk_bf16_f32 v197, v36, v37
	global_store_dwordx4 v[156:157], v[194:197], off offset:256
	v_lshl_add_u64 v[156:157], v[156:157], 0, s[0:1]
	s_waitcnt vmcnt(11)
	v_pk_mul_f32 v[166:167], v[166:167], s[56:57] op_sel_hi:[1,0]
	v_pk_mul_f32 v[164:165], v[164:165], s[56:57] op_sel_hi:[1,0]
	v_pk_mul_f32 v[170:171], v[170:171], s[56:57] op_sel_hi:[1,0]
	v_pk_mul_f32 v[168:169], v[168:169], s[56:57] op_sel_hi:[1,0]
	v_pk_fma_f32 v[32:33], v[32:33], v[136:137], v[166:167]
	v_pk_fma_f32 v[30:31], v[30:31], v[134:135], v[164:165]
	v_pk_fma_f32 v[28:29], v[28:29], v[132:133], v[170:171]
	v_pk_fma_f32 v[26:27], v[26:27], v[130:131], v[168:169]
	v_cvt_pk_bf16_f32 v164, v30, v31
	v_cvt_pk_bf16_f32 v165, v32, v33
	v_cvt_pk_bf16_f32 v166, v26, v27
	v_cvt_pk_bf16_f32 v167, v28, v29
	global_store_dwordx4 v[156:157], v[164:167], off
	s_nop 0
	s_waitcnt vmcnt(9)
	v_pk_mul_f32 v[174:175], v[174:175], s[56:57] op_sel_hi:[1,0]
	v_pk_mul_f32 v[172:173], v[172:173], s[56:57] op_sel_hi:[1,0]
	v_pk_mul_f32 v[178:179], v[178:179], s[56:57] op_sel_hi:[1,0]
	v_pk_mul_f32 v[176:177], v[176:177], s[56:57] op_sel_hi:[1,0]
	v_pk_fma_f32 v[24:25], v[24:25], v[128:129], v[174:175]
	v_pk_fma_f32 v[22:23], v[22:23], v[126:127], v[172:173]
	v_pk_fma_f32 v[20:21], v[20:21], v[124:125], v[178:179]
	v_pk_fma_f32 v[18:19], v[18:19], v[122:123], v[176:177]
	v_cvt_pk_bf16_f32 v172, v22, v23
	v_cvt_pk_bf16_f32 v173, v24, v25
	v_cvt_pk_bf16_f32 v174, v18, v19
	v_cvt_pk_bf16_f32 v175, v20, v21
	global_store_dwordx4 v[156:157], v[172:175], off offset:256
	v_lshl_add_u64 v[156:157], v[156:157], 0, s[0:1]
	s_waitcnt vmcnt(7)
	v_pk_mul_f32 v[182:183], v[182:183], s[56:57] op_sel_hi:[1,0]
	v_pk_mul_f32 v[180:181], v[180:181], s[56:57] op_sel_hi:[1,0]
	v_pk_mul_f32 v[186:187], v[186:187], s[56:57] op_sel_hi:[1,0]
	v_pk_mul_f32 v[184:185], v[184:185], s[56:57] op_sel_hi:[1,0]
	v_pk_fma_f32 v[16:17], v[16:17], v[136:137], v[182:183]
	v_pk_fma_f32 v[14:15], v[14:15], v[134:135], v[180:181]
	v_pk_fma_f32 v[12:13], v[12:13], v[132:133], v[186:187]
	v_pk_fma_f32 v[10:11], v[10:11], v[130:131], v[184:185]
	v_cvt_pk_bf16_f32 v180, v14, v15
	v_cvt_pk_bf16_f32 v181, v16, v17
	v_cvt_pk_bf16_f32 v182, v10, v11
	v_cvt_pk_bf16_f32 v183, v12, v13
	global_store_dwordx4 v[156:157], v[180:183], off
	s_nop 0
	s_waitcnt vmcnt(5)
	v_pk_mul_f32 v[204:205], v[204:205], s[56:57] op_sel_hi:[1,0]
	v_pk_mul_f32 v[202:203], v[202:203], s[56:57] op_sel_hi:[1,0]
	v_pk_mul_f32 v[208:209], v[208:209], s[56:57] op_sel_hi:[1,0]
	v_pk_mul_f32 v[206:207], v[206:207], s[56:57] op_sel_hi:[1,0]
	v_pk_fma_f32 v[8:9], v[8:9], v[128:129], v[204:205]
	v_pk_fma_f32 v[6:7], v[6:7], v[126:127], v[202:203]
	v_pk_fma_f32 v[4:5], v[4:5], v[124:125], v[208:209]
	v_pk_fma_f32 v[2:3], v[2:3], v[122:123], v[206:207]
	v_cvt_pk_bf16_f32 v202, v6, v7
	v_cvt_pk_bf16_f32 v203, v8, v9
	v_cvt_pk_bf16_f32 v204, v2, v3
	v_cvt_pk_bf16_f32 v205, v4, v5
	global_store_dwordx4 v[156:157], v[202:205], off offset:256
	s_nop 0
	s_and_b64 vcc, exec, s[40:41]
	v_readfirstlane_b32 s98, v191
	s_cmpk_lt_u32 s98, 0x100
	s_cbranch_scc1 .Lrl_e1_794
	s_barrier
.Lrl_e1_794:
	s_cbranch_vccz .LBB0_791
	s_waitcnt vmcnt(0)
	v_readlane_b32 s48, v254, 11
	s_cmpk_gt_u32 s4, 0xff
	v_readlane_b32 s49, v254, 12
	v_readlane_b32 s50, v254, 13
	s_mov_b32 s58, 0x800000
	s_mov_b32 s37, s75
	v_readlane_b32 s51, v254, 14
	s_cbranch_scc1 .LBB0_798
	s_barrier

.LBB0_814:
	v_add_u32_e32 v152, s19, v136
	ds_read_b128 v[138:141], v152
	ds_read_b128 v[142:145], v152 offset:1024
	ds_read_b128 v[148:151], v152 offset:2048
	ds_read_b128 v[162:165], v152 offset:3072
	s_add_i32 s70, s70, 2
	s_cmp_lg_u32 s69, s20
	s_cselect_b32 s1, s20, 0
	s_cselect_b32 s0, s21, 0
	s_add_u32 s34, s16, s1
	s_addc_u32 s35, s17, s0
	s_add_u32 s42, s14, s1
	s_addc_u32 s43, s15, s0
	v_lshl_add_u64 v[152:153], v[134:135], 0, s[20:21]
	v_lshl_add_u64 v[152:153], v[152:153], 0, s[76:77]
	s_add_i32 m0, s52, 0xc000
	ds_read_b128 v[166:169], v137
	ds_read_b128 v[170:173], v137 offset:1024
	ds_read_b128 v[174:177], v137 offset:2048
	ds_read_b128 v[178:181], v137 offset:3072
	ds_read_b128 v[182:185], v137 offset:4096
	ds_read_b128 v[186:189], v137 offset:5120
	ds_read_b128 v[202:205], v137 offset:6144
	ds_read_b128 v[206:209], v137 offset:7168
	global_load_lds_dwordx4 v[152:153], off
	v_lshl_add_u64 v[152:153], v[132:133], 0, s[20:21]
	v_lshl_add_u64 v[152:153], v[152:153], 0, s[76:77]
	s_add_i32 m0, s52, 0xe000
	s_nop 0
	global_load_lds_dwordx4 v[152:153], off
	s_waitcnt lgkmcnt(8)
	s_barrier
	s_waitcnt lgkmcnt(0)
	s_setprio 1
	s_waitcnt lgkmcnt(0)
	v_mfma_f32_16x16x32_bf16 v[126:129], v[138:141], v[166:169], v[126:129]
	v_mfma_f32_16x16x32_bf16 v[122:125], v[148:151], v[166:169], v[122:125]
	v_mfma_f32_16x16x32_bf16 v[118:121], v[138:141], v[174:177], v[118:121]
	v_mfma_f32_16x16x32_bf16 v[114:117], v[148:151], v[174:177], v[114:117]
	v_mfma_f32_16x16x32_bf16 v[110:113], v[138:141], v[182:185], v[110:113]
	v_mfma_f32_16x16x32_bf16 v[106:109], v[148:151], v[182:185], v[106:109]
	v_mfma_f32_16x16x32_bf16 v[102:105], v[138:141], v[202:205], v[102:105]
	v_mfma_f32_16x16x32_bf16 v[98:101], v[148:151], v[202:205], v[98:101]
	v_mfma_f32_16x16x32_bf16 v[126:129], v[142:145], v[170:173], v[126:129]
	v_mfma_f32_16x16x32_bf16 v[122:125], v[162:165], v[170:173], v[122:125]
	v_mfma_f32_16x16x32_bf16 v[118:121], v[142:145], v[178:181], v[118:121]
	v_mfma_f32_16x16x32_bf16 v[114:117], v[162:165], v[178:181], v[114:117]
	v_mfma_f32_16x16x32_bf16 v[110:113], v[142:145], v[186:189], v[110:113]
	v_mfma_f32_16x16x32_bf16 v[106:109], v[162:165], v[186:189], v[106:109]
	v_mfma_f32_16x16x32_bf16 v[102:105], v[142:145], v[206:209], v[102:105]
	v_mfma_f32_16x16x32_bf16 v[98:101], v[162:165], v[206:209], v[98:101]
	s_setprio 0
	s_barrier
	v_add_u32_e32 v152, s24, v136
	s_mov_b32 m0, s50
	ds_read_b128 v[210:213], v152
	ds_read_b128 v[214:217], v152 offset:1024
	ds_read_b128 v[218:221], v152 offset:2048
	ds_read_b128 v[242:245], v152 offset:3072
	v_lshl_add_u64 v[152:153], s[42:43], 0, v[0:1]
	global_load_lds_dwordx4 v[152:153], off
	v_lshl_add_u64 v[194:195], s[42:43], 0, v[130:131]
	s_mov_b32 m0, s51
	s_nop 0
	global_load_lds_dwordx4 v[194:195], off
	s_barrier
	s_waitcnt lgkmcnt(0)
	s_setprio 1
	s_waitcnt lgkmcnt(0)
	v_mfma_f32_16x16x32_bf16 v[94:97], v[210:213], v[166:169], v[94:97]
	v_mfma_f32_16x16x32_bf16 v[90:93], v[218:221], v[166:169], v[90:93]
	v_mfma_f32_16x16x32_bf16 v[86:89], v[210:213], v[174:177], v[86:89]
	v_mfma_f32_16x16x32_bf16 v[82:85], v[218:221], v[174:177], v[82:85]
	v_mfma_f32_16x16x32_bf16 v[78:81], v[210:213], v[182:185], v[78:81]
	v_mfma_f32_16x16x32_bf16 v[74:77], v[218:221], v[182:185], v[74:77]
	v_mfma_f32_16x16x32_bf16 v[70:73], v[210:213], v[202:205], v[70:73]
	v_mfma_f32_16x16x32_bf16 v[66:69], v[218:221], v[202:205], v[66:69]
	v_mfma_f32_16x16x32_bf16 v[94:97], v[214:217], v[170:173], v[94:97]
	v_mfma_f32_16x16x32_bf16 v[90:93], v[242:245], v[170:173], v[90:93]
	v_mfma_f32_16x16x32_bf16 v[86:89], v[214:217], v[178:181], v[86:89]
	v_mfma_f32_16x16x32_bf16 v[82:85], v[242:245], v[178:181], v[82:85]
	v_mfma_f32_16x16x32_bf16 v[78:81], v[214:217], v[186:189], v[78:81]
	v_mfma_f32_16x16x32_bf16 v[74:77], v[242:245], v[186:189], v[74:77]
	v_mfma_f32_16x16x32_bf16 v[70:73], v[214:217], v[206:209], v[70:73]
	v_mfma_f32_16x16x32_bf16 v[66:69], v[242:245], v[206:209], v[66:69]
	s_setprio 0
	s_mov_b32 m0, s52
	v_lshl_add_u64 v[196:197], s[34:35], 0, v[0:1]
	s_barrier
	ds_read_b128 v[166:169], v137 offset:16384
	ds_read_b128 v[170:173], v137 offset:17408
	ds_read_b128 v[174:177], v137 offset:18432
	ds_read_b128 v[178:181], v137 offset:19456
	ds_read_b128 v[182:185], v137 offset:20480
	ds_read_b128 v[186:189], v137 offset:21504
	ds_read_b128 v[202:205], v137 offset:22528
	ds_read_b128 v[206:209], v137 offset:23552
	global_load_lds_dwordx4 v[196:197], off
	v_lshl_add_u64 v[222:223], s[34:35], 0, v[130:131]
	s_mov_b32 m0, s53
	s_nop 0
	global_load_lds_dwordx4 v[222:223], off
	s_barrier
	s_waitcnt lgkmcnt(0)
	s_setprio 1
	s_waitcnt lgkmcnt(0)
	v_mfma_f32_16x16x32_bf16 v[62:65], v[138:141], v[166:169], v[62:65]
	v_mfma_f32_16x16x32_bf16 v[58:61], v[148:151], v[166:169], v[58:61]
	v_mfma_f32_16x16x32_bf16 v[54:57], v[138:141], v[174:177], v[54:57]
	v_mfma_f32_16x16x32_bf16 v[50:53], v[148:151], v[174:177], v[50:53]
	v_mfma_f32_16x16x32_bf16 v[46:49], v[138:141], v[182:185], v[46:49]
	v_mfma_f32_16x16x32_bf16 v[42:45], v[148:151], v[182:185], v[42:45]
	v_mfma_f32_16x16x32_bf16 v[38:41], v[138:141], v[202:205], v[38:41]
	v_mfma_f32_16x16x32_bf16 v[34:37], v[148:151], v[202:205], v[34:37]
	v_mfma_f32_16x16x32_bf16 v[62:65], v[142:145], v[170:173], v[62:65]
	v_mfma_f32_16x16x32_bf16 v[58:61], v[162:165], v[170:173], v[58:61]
	v_mfma_f32_16x16x32_bf16 v[54:57], v[142:145], v[178:181], v[54:57]
	v_mfma_f32_16x16x32_bf16 v[50:53], v[162:165], v[178:181], v[50:53]
	v_mfma_f32_16x16x32_bf16 v[46:49], v[142:145], v[186:189], v[46:49]
	v_mfma_f32_16x16x32_bf16 v[42:45], v[162:165], v[186:189], v[42:45]
	v_mfma_f32_16x16x32_bf16 v[38:41], v[142:145], v[206:209], v[38:41]
	v_mfma_f32_16x16x32_bf16 v[34:37], v[162:165], v[206:209], v[34:37]
	s_setprio 0
	s_barrier
	s_add_u32 s0, s42, s49
	s_addc_u32 s1, s43, 0
	s_mov_b32 m0, s54
	v_lshl_add_u64 v[246:247], s[0:1], 0, v[0:1]
	global_load_lds_dwordx4 v[246:247], off
	v_lshl_add_u64 v[248:249], s[0:1], 0, v[130:131]
	s_mov_b32 m0, s55
	s_nop 0
	global_load_lds_dwordx4 v[248:249], off
	s_waitcnt vmcnt(6)
	s_barrier
	s_setprio 1
	v_mfma_f32_16x16x32_bf16 v[30:33], v[210:213], v[166:169], v[30:33]
	v_mfma_f32_16x16x32_bf16 v[26:29], v[218:221], v[166:169], v[26:29]
	v_mfma_f32_16x16x32_bf16 v[22:25], v[210:213], v[174:177], v[22:25]
	v_mfma_f32_16x16x32_bf16 v[18:21], v[218:221], v[174:177], v[18:21]
	v_mfma_f32_16x16x32_bf16 v[14:17], v[210:213], v[182:185], v[14:17]
	v_mfma_f32_16x16x32_bf16 v[10:13], v[218:221], v[182:185], v[10:13]
	v_mfma_f32_16x16x32_bf16 v[6:9], v[210:213], v[202:205], v[6:9]
	v_mfma_f32_16x16x32_bf16 v[2:5], v[218:221], v[202:205], v[2:5]
	v_mfma_f32_16x16x32_bf16 v[30:33], v[214:217], v[170:173], v[30:33]
	v_mfma_f32_16x16x32_bf16 v[26:29], v[242:245], v[170:173], v[26:29]
	v_mfma_f32_16x16x32_bf16 v[22:25], v[214:217], v[178:181], v[22:25]
	v_mfma_f32_16x16x32_bf16 v[18:21], v[242:245], v[178:181], v[18:21]
	v_mfma_f32_16x16x32_bf16 v[14:17], v[214:217], v[186:189], v[14:17]
	v_mfma_f32_16x16x32_bf16 v[10:13], v[242:245], v[186:189], v[10:13]
	v_mfma_f32_16x16x32_bf16 v[6:9], v[214:217], v[206:209], v[6:9]
	v_mfma_f32_16x16x32_bf16 v[2:5], v[242:245], v[206:209], v[2:5]
	s_setprio 0
	v_add_u32_e32 v162, s25, v136
	s_barrier
	ds_read_b128 v[138:141], v162
	ds_read_b128 v[142:145], v162 offset:1024
	ds_read_b128 v[148:151], v162 offset:2048
	ds_read_b128 v[162:165], v162 offset:3072
	s_add_u32 s0, s34, s49
	s_addc_u32 s1, s35, 0
	s_mov_b32 m0, s58
	v_lshl_add_u64 v[210:211], s[0:1], 0, v[0:1]
	ds_read_b128 v[166:169], v137 offset:32768
	ds_read_b128 v[170:173], v137 offset:33792
	ds_read_b128 v[174:177], v137 offset:34816
	ds_read_b128 v[178:181], v137 offset:35840
	ds_read_b128 v[182:185], v137 offset:36864
	ds_read_b128 v[186:189], v137 offset:37888
	ds_read_b128 v[202:205], v137 offset:38912
	ds_read_b128 v[206:209], v137 offset:39936
	global_load_lds_dwordx4 v[210:211], off
	v_lshl_add_u64 v[210:211], s[0:1], 0, v[130:131]
	s_mov_b32 m0, s60
	s_nop 0
	global_load_lds_dwordx4 v[210:211], off
	s_waitcnt lgkmcnt(8)
	s_barrier
	s_waitcnt lgkmcnt(0)
	s_setprio 1
	s_waitcnt lgkmcnt(0)
	v_mfma_f32_16x16x32_bf16 v[126:129], v[138:141], v[166:169], v[126:129]
	v_mfma_f32_16x16x32_bf16 v[122:125], v[148:151], v[166:169], v[122:125]
	v_mfma_f32_16x16x32_bf16 v[118:121], v[138:141], v[174:177], v[118:121]
	v_mfma_f32_16x16x32_bf16 v[114:117], v[148:151], v[174:177], v[114:117]
	v_mfma_f32_16x16x32_bf16 v[110:113], v[138:141], v[182:185], v[110:113]
	v_mfma_f32_16x16x32_bf16 v[106:109], v[148:151], v[182:185], v[106:109]
	v_mfma_f32_16x16x32_bf16 v[102:105], v[138:141], v[202:205], v[102:105]
	v_mfma_f32_16x16x32_bf16 v[98:101], v[148:151], v[202:205], v[98:101]
	v_mfma_f32_16x16x32_bf16 v[126:129], v[142:145], v[170:173], v[126:129]
	v_mfma_f32_16x16x32_bf16 v[122:125], v[162:165], v[170:173], v[122:125]
	v_mfma_f32_16x16x32_bf16 v[118:121], v[142:145], v[178:181], v[118:121]
	v_mfma_f32_16x16x32_bf16 v[114:117], v[162:165], v[178:181], v[114:117]
	v_mfma_f32_16x16x32_bf16 v[110:113], v[142:145], v[186:189], v[110:113]
	v_mfma_f32_16x16x32_bf16 v[106:109], v[162:165], v[186:189], v[106:109]
	v_mfma_f32_16x16x32_bf16 v[102:105], v[142:145], v[206:209], v[102:105]
	v_mfma_f32_16x16x32_bf16 v[98:101], v[162:165], v[206:209], v[98:101]
	s_setprio 0
	s_barrier
	s_mov_b32 m0, s61
	v_add_u32_e32 v201, s26, v136
	v_lshl_add_u64 v[152:153], v[152:153], 0, s[88:89]
	ds_read_b128 v[210:213], v201
	ds_read_b128 v[214:217], v201 offset:1024
	ds_read_b128 v[218:221], v201 offset:2048
	ds_read_b128 v[242:245], v201 offset:3072
	global_load_lds_dwordx4 v[152:153], off
	v_lshl_add_u64 v[152:153], v[194:195], 0, s[88:89]
	s_mov_b32 m0, s62
	s_nop 0
	global_load_lds_dwordx4 v[152:153], off
	s_barrier
	s_waitcnt lgkmcnt(0)
	s_setprio 1
	s_waitcnt lgkmcnt(0)
	v_mfma_f32_16x16x32_bf16 v[94:97], v[210:213], v[166:169], v[94:97]
	v_mfma_f32_16x16x32_bf16 v[90:93], v[218:221], v[166:169], v[90:93]
	v_mfma_f32_16x16x32_bf16 v[86:89], v[210:213], v[174:177], v[86:89]
	v_mfma_f32_16x16x32_bf16 v[82:85], v[218:221], v[174:177], v[82:85]
	v_mfma_f32_16x16x32_bf16 v[78:81], v[210:213], v[182:185], v[78:81]
	v_mfma_f32_16x16x32_bf16 v[74:77], v[218:221], v[182:185], v[74:77]
	v_mfma_f32_16x16x32_bf16 v[70:73], v[210:213], v[202:205], v[70:73]
	v_mfma_f32_16x16x32_bf16 v[66:69], v[218:221], v[202:205], v[66:69]
	v_mfma_f32_16x16x32_bf16 v[94:97], v[214:217], v[170:173], v[94:97]
	v_mfma_f32_16x16x32_bf16 v[90:93], v[242:245], v[170:173], v[90:93]
	v_mfma_f32_16x16x32_bf16 v[86:89], v[214:217], v[178:181], v[86:89]
	v_mfma_f32_16x16x32_bf16 v[82:85], v[242:245], v[178:181], v[82:85]
	v_mfma_f32_16x16x32_bf16 v[78:81], v[214:217], v[186:189], v[78:81]
	v_mfma_f32_16x16x32_bf16 v[74:77], v[242:245], v[186:189], v[74:77]
	v_mfma_f32_16x16x32_bf16 v[70:73], v[214:217], v[206:209], v[70:73]
	v_mfma_f32_16x16x32_bf16 v[66:69], v[242:245], v[206:209], v[66:69]
	s_setprio 0
	s_mov_b32 m0, s63
	v_lshl_add_u64 v[152:153], v[196:197], 0, s[88:89]
	s_barrier
	ds_read_b128 v[166:169], v137 offset:49152
	ds_read_b128 v[170:173], v137 offset:50176
	ds_read_b128 v[174:177], v137 offset:51200
	ds_read_b128 v[178:181], v137 offset:52224
	ds_read_b128 v[182:185], v137 offset:53248
	ds_read_b128 v[186:189], v137 offset:54272
	ds_read_b128 v[202:205], v137 offset:55296
	ds_read_b128 v[206:209], v137 offset:56320
	global_load_lds_dwordx4 v[152:153], off
	v_lshl_add_u64 v[152:153], v[222:223], 0, s[88:89]
	s_mov_b32 m0, s66
	s_nop 0
	global_load_lds_dwordx4 v[152:153], off
	s_barrier
	s_waitcnt lgkmcnt(0)
	s_setprio 1
	s_waitcnt lgkmcnt(0)
	v_mfma_f32_16x16x32_bf16 v[62:65], v[138:141], v[166:169], v[62:65]
	v_mfma_f32_16x16x32_bf16 v[58:61], v[148:151], v[166:169], v[58:61]
	v_mfma_f32_16x16x32_bf16 v[54:57], v[138:141], v[174:177], v[54:57]
	v_mfma_f32_16x16x32_bf16 v[50:53], v[148:151], v[174:177], v[50:53]
	v_mfma_f32_16x16x32_bf16 v[46:49], v[138:141], v[182:185], v[46:49]
	v_mfma_f32_16x16x32_bf16 v[42:45], v[148:151], v[182:185], v[42:45]
	v_mfma_f32_16x16x32_bf16 v[38:41], v[138:141], v[202:205], v[38:41]
	v_mfma_f32_16x16x32_bf16 v[34:37], v[148:151], v[202:205], v[34:37]
	v_mfma_f32_16x16x32_bf16 v[62:65], v[142:145], v[170:173], v[62:65]
	v_mfma_f32_16x16x32_bf16 v[58:61], v[162:165], v[170:173], v[58:61]
	v_mfma_f32_16x16x32_bf16 v[54:57], v[142:145], v[178:181], v[54:57]
	v_mfma_f32_16x16x32_bf16 v[50:53], v[162:165], v[178:181], v[50:53]
	v_mfma_f32_16x16x32_bf16 v[46:49], v[142:145], v[186:189], v[46:49]
	v_mfma_f32_16x16x32_bf16 v[42:45], v[162:165], v[186:189], v[42:45]
	v_mfma_f32_16x16x32_bf16 v[38:41], v[142:145], v[206:209], v[38:41]
	v_mfma_f32_16x16x32_bf16 v[34:37], v[162:165], v[206:209], v[34:37]
	s_setprio 0
	s_barrier
	s_mov_b32 m0, s67
	v_lshl_add_u64 v[138:139], v[246:247], 0, s[88:89]
	global_load_lds_dwordx4 v[138:139], off
	v_lshl_add_u64 v[138:139], v[248:249], 0, s[88:89]
	s_mov_b32 m0, s68
	s_nop 0
	global_load_lds_dwordx4 v[138:139], off
	s_waitcnt vmcnt(6)
	s_barrier
	s_setprio 1
	v_mfma_f32_16x16x32_bf16 v[30:33], v[210:213], v[166:169], v[30:33]
	v_mfma_f32_16x16x32_bf16 v[26:29], v[218:221], v[166:169], v[26:29]
	v_mfma_f32_16x16x32_bf16 v[22:25], v[210:213], v[174:177], v[22:25]
	v_mfma_f32_16x16x32_bf16 v[18:21], v[218:221], v[174:177], v[18:21]
	v_mfma_f32_16x16x32_bf16 v[14:17], v[210:213], v[182:185], v[14:17]
	v_mfma_f32_16x16x32_bf16 v[10:13], v[218:221], v[182:185], v[10:13]
	v_mfma_f32_16x16x32_bf16 v[6:9], v[210:213], v[202:205], v[6:9]
	v_mfma_f32_16x16x32_bf16 v[2:5], v[218:221], v[202:205], v[2:5]
	v_mfma_f32_16x16x32_bf16 v[30:33], v[214:217], v[170:173], v[30:33]
	v_mfma_f32_16x16x32_bf16 v[26:29], v[242:245], v[170:173], v[26:29]
	v_mfma_f32_16x16x32_bf16 v[22:25], v[214:217], v[178:181], v[22:25]
	v_mfma_f32_16x16x32_bf16 v[18:21], v[242:245], v[178:181], v[18:21]
	v_mfma_f32_16x16x32_bf16 v[14:17], v[214:217], v[186:189], v[14:17]
	v_mfma_f32_16x16x32_bf16 v[10:13], v[242:245], v[186:189], v[10:13]
	v_mfma_f32_16x16x32_bf16 v[6:9], v[214:217], v[206:209], v[6:9]
	v_mfma_f32_16x16x32_bf16 v[2:5], v[242:245], v[206:209], v[2:5]
	s_setprio 0
	s_add_u32 s20, s20, 0x100
	s_addc_u32 s21, s21, 0
	s_cmp_ge_u32 s70, s44
	s_barrier
	s_cbranch_scc0 .LBB0_814
	v_readfirstlane_b32 s98, v191
	s_cmpk_gt_u32 s98, 0xff
	s_cbranch_scc1 .Lrl_e0_814
	s_barrier
.Lrl_e0_814:
	s_lshl_b32 s0, s45, 2
	s_or_b32 s14, s0, s47
	v_lshl_or_b32 v130, s14, 6, v160
	s_ashr_i32 s15, s14, 31
	v_ashrrev_i32_e32 v131, 31, v130
	v_readlane_b32 s76, v254, 9
	v_lshlrev_b64 v[148:149], 4, v[130:131]
	s_cmp_lg_u32 s2, 1
	s_mov_b64 s[16:17], -1
	s_mov_b32 s58, 0x800000
	s_brev_b32 s64, 60
	v_readlane_b32 s77, v254, 10
	s_cbranch_scc0 .LBB0_843
	s_cmp_eq_u32 s2, 2
	s_cselect_b64 s[42:43], -1, 0
	s_cmp_lg_u32 s2, 2
	s_cbranch_scc1 .LBB0_826
	s_lshl_b32 s0, s3, 5
	s_add_u32 s16, s30, s0
	s_addc_u32 s17, s36, 0
	s_lshl_b64 s[0:1], s[14:15], 2
	s_add_u32 s16, s16, s0
	s_addc_u32 s17, s17, s1
	s_mov_b32 s18, 0x400001
	s_branch .LBB0_819

.LBB0_1241:
	v_add_u32_e32 v0, s37, v144
	ds_read_b128 v[140:143], v0
	ds_read_b128 v[150:153], v0 offset:1024
	ds_read_b128 v[154:157], v0 offset:2048
	ds_read_b128 v[158:161], v0 offset:3072
	s_add_u32 s0, s20, 0xfffc0080
	s_addc_u32 s1, s21, -1
	s_cmp_eq_u32 s51, 12
	s_cselect_b32 s49, s15, s1
	s_cselect_b32 s48, s29, s0
	s_cselect_b32 s35, s7, s50
	s_cselect_b32 s34, s43, s45
	v_lshl_add_u64 v[194:195], s[20:21], 0, v[136:137]
	s_add_i32 m0, s66, 0xc000
	ds_read_b128 v[162:165], v149
	ds_read_b128 v[166:169], v149 offset:1024
	ds_read_b128 v[170:173], v149 offset:2048
	ds_read_b128 v[174:177], v149 offset:3072
	ds_read_b128 v[178:181], v149 offset:4096
	ds_read_b128 v[182:185], v149 offset:5120
	ds_read_b128 v[186:189], v149 offset:6144
	ds_read_b128 v[202:205], v149 offset:7168
	global_load_lds_dwordx4 v[194:195], off
	v_lshl_add_u64 v[194:195], s[20:21], 0, v[138:139]
	s_add_i32 m0, s66, 0xe000
	s_nop 0
	global_load_lds_dwordx4 v[194:195], off
	s_waitcnt lgkmcnt(8)
	s_barrier
	s_waitcnt lgkmcnt(0)
	s_setprio 1
	s_waitcnt lgkmcnt(0)
	v_mfma_f32_16x16x32_bf16 v[126:129], v[140:143], v[162:165], v[126:129]
	v_mfma_f32_16x16x32_bf16 v[122:125], v[154:157], v[162:165], v[122:125]
	v_mfma_f32_16x16x32_bf16 v[110:113], v[140:143], v[170:173], v[110:113]
	v_mfma_f32_16x16x32_bf16 v[106:109], v[154:157], v[170:173], v[106:109]
	v_mfma_f32_16x16x32_bf16 v[94:97], v[140:143], v[178:181], v[94:97]
	v_mfma_f32_16x16x32_bf16 v[90:93], v[154:157], v[178:181], v[90:93]
	v_mfma_f32_16x16x32_bf16 v[78:81], v[140:143], v[186:189], v[78:81]
	v_mfma_f32_16x16x32_bf16 v[74:77], v[154:157], v[186:189], v[74:77]
	v_mfma_f32_16x16x32_bf16 v[126:129], v[150:153], v[166:169], v[126:129]
	v_mfma_f32_16x16x32_bf16 v[122:125], v[158:161], v[166:169], v[122:125]
	v_mfma_f32_16x16x32_bf16 v[110:113], v[150:153], v[174:177], v[110:113]
	v_mfma_f32_16x16x32_bf16 v[106:109], v[158:161], v[174:177], v[106:109]
	v_mfma_f32_16x16x32_bf16 v[94:97], v[150:153], v[182:185], v[94:97]
	v_mfma_f32_16x16x32_bf16 v[90:93], v[158:161], v[182:185], v[90:93]
	v_mfma_f32_16x16x32_bf16 v[78:81], v[150:153], v[202:205], v[78:81]
	v_mfma_f32_16x16x32_bf16 v[74:77], v[158:161], v[202:205], v[74:77]
	s_setprio 0
	s_barrier
	s_mov_b32 m0, s62
	v_add_u32_e32 v0, s26, v144
	v_lshl_add_u64 v[194:195], s[34:35], 0, v[130:131]
	ds_read_b128 v[206:209], v0
	ds_read_b128 v[210:213], v0 offset:1024
	ds_read_b128 v[214:217], v0 offset:2048
	ds_read_b128 v[218:221], v0 offset:3072
	global_load_lds_dwordx4 v[194:195], off
	v_lshl_add_u64 v[196:197], s[34:35], 0, v[132:133]
	s_mov_b32 m0, s63
	s_nop 0
	global_load_lds_dwordx4 v[196:197], off
	s_barrier
	s_waitcnt lgkmcnt(0)
	s_setprio 1
	s_waitcnt lgkmcnt(0)
	v_mfma_f32_16x16x32_bf16 v[118:121], v[206:209], v[162:165], v[118:121]
	v_mfma_f32_16x16x32_bf16 v[114:117], v[214:217], v[162:165], v[114:117]
	v_mfma_f32_16x16x32_bf16 v[102:105], v[206:209], v[170:173], v[102:105]
	v_mfma_f32_16x16x32_bf16 v[98:101], v[214:217], v[170:173], v[98:101]
	v_mfma_f32_16x16x32_bf16 v[86:89], v[206:209], v[178:181], v[86:89]
	v_mfma_f32_16x16x32_bf16 v[82:85], v[214:217], v[178:181], v[82:85]
	v_mfma_f32_16x16x32_bf16 v[70:73], v[206:209], v[186:189], v[70:73]
	v_mfma_f32_16x16x32_bf16 v[66:69], v[214:217], v[186:189], v[66:69]
	v_mfma_f32_16x16x32_bf16 v[118:121], v[210:213], v[166:169], v[118:121]
	v_mfma_f32_16x16x32_bf16 v[114:117], v[218:221], v[166:169], v[114:117]
	v_mfma_f32_16x16x32_bf16 v[102:105], v[210:213], v[174:177], v[102:105]
	v_mfma_f32_16x16x32_bf16 v[98:101], v[218:221], v[174:177], v[98:101]
	v_mfma_f32_16x16x32_bf16 v[86:89], v[210:213], v[182:185], v[86:89]
	v_mfma_f32_16x16x32_bf16 v[82:85], v[218:221], v[182:185], v[82:85]
	v_mfma_f32_16x16x32_bf16 v[70:73], v[210:213], v[202:205], v[70:73]
	v_mfma_f32_16x16x32_bf16 v[66:69], v[218:221], v[202:205], v[66:69]
	s_setprio 0
	s_mov_b32 m0, s66
	v_lshl_add_u64 v[222:223], s[48:49], 0, v[130:131]
	s_barrier
	ds_read_b128 v[162:165], v149 offset:16384
	ds_read_b128 v[166:169], v149 offset:17408
	ds_read_b128 v[170:173], v149 offset:18432
	ds_read_b128 v[174:177], v149 offset:19456
	ds_read_b128 v[178:181], v149 offset:20480
	ds_read_b128 v[182:185], v149 offset:21504
	ds_read_b128 v[186:189], v149 offset:22528
	ds_read_b128 v[202:205], v149 offset:23552
	global_load_lds_dwordx4 v[222:223], off
	v_lshl_add_u64 v[242:243], s[48:49], 0, v[132:133]
	s_mov_b32 m0, s67
	s_nop 0
	global_load_lds_dwordx4 v[242:243], off
	s_barrier
	s_waitcnt lgkmcnt(0)
	s_setprio 1
	s_waitcnt lgkmcnt(0)
	v_mfma_f32_16x16x32_bf16 v[62:65], v[140:143], v[162:165], v[62:65]
	v_mfma_f32_16x16x32_bf16 v[58:61], v[154:157], v[162:165], v[58:61]
	v_mfma_f32_16x16x32_bf16 v[46:49], v[140:143], v[170:173], v[46:49]
	v_mfma_f32_16x16x32_bf16 v[42:45], v[154:157], v[170:173], v[42:45]
	v_mfma_f32_16x16x32_bf16 v[30:33], v[140:143], v[178:181], v[30:33]
	v_mfma_f32_16x16x32_bf16 v[26:29], v[154:157], v[178:181], v[26:29]
	v_mfma_f32_16x16x32_bf16 v[14:17], v[140:143], v[186:189], v[14:17]
	v_mfma_f32_16x16x32_bf16 v[10:13], v[154:157], v[186:189], v[10:13]
	v_mfma_f32_16x16x32_bf16 v[62:65], v[150:153], v[166:169], v[62:65]
	v_mfma_f32_16x16x32_bf16 v[58:61], v[158:161], v[166:169], v[58:61]
	v_mfma_f32_16x16x32_bf16 v[46:49], v[150:153], v[174:177], v[46:49]
	v_mfma_f32_16x16x32_bf16 v[42:45], v[158:161], v[174:177], v[42:45]
	v_mfma_f32_16x16x32_bf16 v[30:33], v[150:153], v[182:185], v[30:33]
	v_mfma_f32_16x16x32_bf16 v[26:29], v[158:161], v[182:185], v[26:29]
	v_mfma_f32_16x16x32_bf16 v[14:17], v[150:153], v[202:205], v[14:17]
	v_mfma_f32_16x16x32_bf16 v[10:13], v[158:161], v[202:205], v[10:13]
	s_setprio 0
	s_barrier
	s_add_u32 s0, s34, 0x40000
	s_addc_u32 s1, s35, 0
	s_mov_b32 m0, s68
	v_lshl_add_u64 v[140:141], s[0:1], 0, v[130:131]
	global_load_lds_dwordx4 v[140:141], off
	v_lshl_add_u64 v[140:141], s[0:1], 0, v[132:133]
	s_mov_b32 m0, s28
	s_nop 0
	global_load_lds_dwordx4 v[140:141], off
	s_waitcnt vmcnt(6)
	s_barrier
	s_setprio 1
	v_mfma_f32_16x16x32_bf16 v[54:57], v[206:209], v[162:165], v[54:57]
	v_mfma_f32_16x16x32_bf16 v[50:53], v[214:217], v[162:165], v[50:53]
	v_mfma_f32_16x16x32_bf16 v[38:41], v[206:209], v[170:173], v[38:41]
	v_mfma_f32_16x16x32_bf16 v[34:37], v[214:217], v[170:173], v[34:37]
	v_mfma_f32_16x16x32_bf16 v[22:25], v[206:209], v[178:181], v[22:25]
	v_mfma_f32_16x16x32_bf16 v[18:21], v[214:217], v[178:181], v[18:21]
	v_mfma_f32_16x16x32_bf16 v[6:9], v[206:209], v[186:189], v[6:9]
	v_mfma_f32_16x16x32_bf16 v[2:5], v[214:217], v[186:189], v[2:5]
	v_mfma_f32_16x16x32_bf16 v[54:57], v[210:213], v[166:169], v[54:57]
	v_mfma_f32_16x16x32_bf16 v[50:53], v[218:221], v[166:169], v[50:53]
	v_mfma_f32_16x16x32_bf16 v[38:41], v[210:213], v[174:177], v[38:41]
	v_mfma_f32_16x16x32_bf16 v[34:37], v[218:221], v[174:177], v[34:37]
	v_mfma_f32_16x16x32_bf16 v[22:25], v[210:213], v[182:185], v[22:25]
	v_mfma_f32_16x16x32_bf16 v[18:21], v[218:221], v[182:185], v[18:21]
	v_mfma_f32_16x16x32_bf16 v[6:9], v[210:213], v[202:205], v[6:9]
	v_mfma_f32_16x16x32_bf16 v[2:5], v[218:221], v[202:205], v[2:5]
	s_setprio 0
	v_add_u32_e32 v0, s36, v144
	s_barrier
	ds_read_b128 v[140:143], v0
	ds_read_b128 v[150:153], v0 offset:1024
	ds_read_b128 v[154:157], v0 offset:2048
	ds_read_b128 v[158:161], v0 offset:3072
	s_add_u32 s0, s48, 0x40000
	s_addc_u32 s1, s49, 0
	s_mov_b32 m0, s30
	v_lshl_add_u64 v[206:207], s[0:1], 0, v[130:131]
	ds_read_b128 v[162:165], v149 offset:32768
	ds_read_b128 v[166:169], v149 offset:33792
	ds_read_b128 v[170:173], v149 offset:34816
	ds_read_b128 v[174:177], v149 offset:35840
	ds_read_b128 v[178:181], v149 offset:36864
	ds_read_b128 v[182:185], v149 offset:37888
	ds_read_b128 v[186:189], v149 offset:38912
	ds_read_b128 v[202:205], v149 offset:39936
	global_load_lds_dwordx4 v[206:207], off
	v_lshl_add_u64 v[206:207], s[0:1], 0, v[132:133]
	s_mov_b32 m0, s69
	s_nop 0
	global_load_lds_dwordx4 v[206:207], off
	s_waitcnt lgkmcnt(8)
	s_barrier
	s_waitcnt lgkmcnt(0)
	s_setprio 1
	s_waitcnt lgkmcnt(0)
	v_mfma_f32_16x16x32_bf16 v[126:129], v[140:143], v[162:165], v[126:129]
	v_mfma_f32_16x16x32_bf16 v[122:125], v[154:157], v[162:165], v[122:125]
	v_mfma_f32_16x16x32_bf16 v[110:113], v[140:143], v[170:173], v[110:113]
	v_mfma_f32_16x16x32_bf16 v[106:109], v[154:157], v[170:173], v[106:109]
	v_mfma_f32_16x16x32_bf16 v[94:97], v[140:143], v[178:181], v[94:97]
	v_mfma_f32_16x16x32_bf16 v[90:93], v[154:157], v[178:181], v[90:93]
	v_mfma_f32_16x16x32_bf16 v[78:81], v[140:143], v[186:189], v[78:81]
	v_mfma_f32_16x16x32_bf16 v[74:77], v[154:157], v[186:189], v[74:77]
	v_mfma_f32_16x16x32_bf16 v[126:129], v[150:153], v[166:169], v[126:129]
	v_mfma_f32_16x16x32_bf16 v[122:125], v[158:161], v[166:169], v[122:125]
	v_mfma_f32_16x16x32_bf16 v[110:113], v[150:153], v[174:177], v[110:113]
	v_mfma_f32_16x16x32_bf16 v[106:109], v[158:161], v[174:177], v[106:109]
	v_mfma_f32_16x16x32_bf16 v[94:97], v[150:153], v[182:185], v[94:97]
	v_mfma_f32_16x16x32_bf16 v[90:93], v[158:161], v[182:185], v[90:93]
	v_mfma_f32_16x16x32_bf16 v[78:81], v[150:153], v[202:205], v[78:81]
	v_mfma_f32_16x16x32_bf16 v[74:77], v[158:161], v[202:205], v[74:77]
	s_setprio 0
	s_barrier
	s_mov_b32 m0, s38
	v_add_u32_e32 v0, s8, v144
	v_lshl_add_u64 v[194:195], v[194:195], 0, s[88:89]
	ds_read_b128 v[206:209], v0
	ds_read_b128 v[210:213], v0 offset:1024
	ds_read_b128 v[214:217], v0 offset:2048
	ds_read_b128 v[218:221], v0 offset:3072
	global_load_lds_dwordx4 v[194:195], off
	v_lshl_add_u64 v[194:195], v[196:197], 0, s[88:89]
	s_mov_b32 m0, s58
	s_nop 0
	global_load_lds_dwordx4 v[194:195], off
	s_barrier
	s_waitcnt lgkmcnt(0)
	s_setprio 1
	s_waitcnt lgkmcnt(0)
	v_mfma_f32_16x16x32_bf16 v[118:121], v[206:209], v[162:165], v[118:121]
	v_mfma_f32_16x16x32_bf16 v[114:117], v[214:217], v[162:165], v[114:117]
	v_mfma_f32_16x16x32_bf16 v[102:105], v[206:209], v[170:173], v[102:105]
	v_mfma_f32_16x16x32_bf16 v[98:101], v[214:217], v[170:173], v[98:101]
	v_mfma_f32_16x16x32_bf16 v[86:89], v[206:209], v[178:181], v[86:89]
	v_mfma_f32_16x16x32_bf16 v[82:85], v[214:217], v[178:181], v[82:85]
	v_mfma_f32_16x16x32_bf16 v[70:73], v[206:209], v[186:189], v[70:73]
	v_mfma_f32_16x16x32_bf16 v[66:69], v[214:217], v[186:189], v[66:69]
	v_mfma_f32_16x16x32_bf16 v[118:121], v[210:213], v[166:169], v[118:121]
	v_mfma_f32_16x16x32_bf16 v[114:117], v[218:221], v[166:169], v[114:117]
	v_mfma_f32_16x16x32_bf16 v[102:105], v[210:213], v[174:177], v[102:105]
	v_mfma_f32_16x16x32_bf16 v[98:101], v[218:221], v[174:177], v[98:101]
	v_mfma_f32_16x16x32_bf16 v[86:89], v[210:213], v[182:185], v[86:89]
	v_mfma_f32_16x16x32_bf16 v[82:85], v[218:221], v[182:185], v[82:85]
	v_mfma_f32_16x16x32_bf16 v[70:73], v[210:213], v[202:205], v[70:73]
	v_mfma_f32_16x16x32_bf16 v[66:69], v[218:221], v[202:205], v[66:69]
	s_setprio 0
	s_mov_b32 m0, s76
	v_lshl_add_u64 v[194:195], v[222:223], 0, s[88:89]
	s_barrier
	ds_read_b128 v[162:165], v149 offset:49152
	ds_read_b128 v[166:169], v149 offset:50176
	ds_read_b128 v[170:173], v149 offset:51200
	ds_read_b128 v[174:177], v149 offset:52224
	ds_read_b128 v[178:181], v149 offset:53248
	ds_read_b128 v[182:185], v149 offset:54272
	ds_read_b128 v[186:189], v149 offset:55296
	ds_read_b128 v[202:205], v149 offset:56320
	global_load_lds_dwordx4 v[194:195], off
	v_lshl_add_u64 v[194:195], v[242:243], 0, s[88:89]
	s_mov_b32 m0, s4
	s_nop 0
	global_load_lds_dwordx4 v[194:195], off
	s_barrier
	s_waitcnt lgkmcnt(0)
	s_setprio 1
	s_waitcnt lgkmcnt(0)
	v_mfma_f32_16x16x32_bf16 v[62:65], v[140:143], v[162:165], v[62:65]
	v_mfma_f32_16x16x32_bf16 v[58:61], v[154:157], v[162:165], v[58:61]
	v_mfma_f32_16x16x32_bf16 v[46:49], v[140:143], v[170:173], v[46:49]
	v_mfma_f32_16x16x32_bf16 v[42:45], v[154:157], v[170:173], v[42:45]
	v_mfma_f32_16x16x32_bf16 v[30:33], v[140:143], v[178:181], v[30:33]
	v_mfma_f32_16x16x32_bf16 v[26:29], v[154:157], v[178:181], v[26:29]
	v_mfma_f32_16x16x32_bf16 v[14:17], v[140:143], v[186:189], v[14:17]
	v_mfma_f32_16x16x32_bf16 v[10:13], v[154:157], v[186:189], v[10:13]
	v_mfma_f32_16x16x32_bf16 v[62:65], v[150:153], v[166:169], v[62:65]
	v_mfma_f32_16x16x32_bf16 v[58:61], v[158:161], v[166:169], v[58:61]
	v_mfma_f32_16x16x32_bf16 v[46:49], v[150:153], v[174:177], v[46:49]
	v_mfma_f32_16x16x32_bf16 v[42:45], v[158:161], v[174:177], v[42:45]
	v_mfma_f32_16x16x32_bf16 v[30:33], v[150:153], v[182:185], v[30:33]
	v_mfma_f32_16x16x32_bf16 v[26:29], v[158:161], v[182:185], v[26:29]
	v_mfma_f32_16x16x32_bf16 v[14:17], v[150:153], v[202:205], v[14:17]
	v_mfma_f32_16x16x32_bf16 v[10:13], v[158:161], v[202:205], v[10:13]
	s_setprio 0
	s_barrier
	s_add_u32 s0, s34, 0x40080
	s_addc_u32 s1, s35, 0
	s_mov_b32 m0, s10
	v_lshl_add_u64 v[140:141], s[0:1], 0, v[130:131]
	global_load_lds_dwordx4 v[140:141], off
	v_lshl_add_u64 v[140:141], s[0:1], 0, v[132:133]
	s_mov_b32 m0, s11
	s_nop 0
	global_load_lds_dwordx4 v[140:141], off
	s_waitcnt vmcnt(6)
	s_barrier
	s_setprio 1
	v_mfma_f32_16x16x32_bf16 v[54:57], v[206:209], v[162:165], v[54:57]
	v_mfma_f32_16x16x32_bf16 v[50:53], v[214:217], v[162:165], v[50:53]
	v_mfma_f32_16x16x32_bf16 v[38:41], v[206:209], v[170:173], v[38:41]
	v_mfma_f32_16x16x32_bf16 v[34:37], v[214:217], v[170:173], v[34:37]
	v_mfma_f32_16x16x32_bf16 v[22:25], v[206:209], v[178:181], v[22:25]
	v_mfma_f32_16x16x32_bf16 v[18:21], v[214:217], v[178:181], v[18:21]
	v_mfma_f32_16x16x32_bf16 v[6:9], v[206:209], v[186:189], v[6:9]
	v_mfma_f32_16x16x32_bf16 v[2:5], v[214:217], v[186:189], v[2:5]
	v_mfma_f32_16x16x32_bf16 v[54:57], v[210:213], v[166:169], v[54:57]
	v_mfma_f32_16x16x32_bf16 v[50:53], v[218:221], v[166:169], v[50:53]
	v_mfma_f32_16x16x32_bf16 v[38:41], v[210:213], v[174:177], v[38:41]
	v_mfma_f32_16x16x32_bf16 v[34:37], v[218:221], v[174:177], v[34:37]
	v_mfma_f32_16x16x32_bf16 v[22:25], v[210:213], v[182:185], v[22:25]
	v_mfma_f32_16x16x32_bf16 v[18:21], v[218:221], v[182:185], v[18:21]
	v_mfma_f32_16x16x32_bf16 v[6:9], v[210:213], v[202:205], v[6:9]
	v_mfma_f32_16x16x32_bf16 v[2:5], v[218:221], v[202:205], v[2:5]
	s_setprio 0
	s_add_i32 s51, s51, 2
	s_add_u32 s20, s20, 0x100
	s_addc_u32 s21, s21, 0
	s_add_u32 s45, s45, 0x100
	s_addc_u32 s50, s50, 0
	s_cmp_gt_u32 s51, 13
	s_barrier
	s_cbranch_scc0 .LBB0_1241
	v_readfirstlane_b32 s98, v191
	s_cmpk_gt_u32 s98, 0xff
	s_cbranch_scc1 .Lrl_e0_1241
	s_barrier
.Lrl_e0_1241:
	s_lshl_b32 s15, s44, 8
	s_add_i32 s15, s15, s74
	s_cmp_gt_i32 s42, 5
	v_sub_co_u32_e64 v0, s[0:1], s42, 9
	s_cselect_b64 s[52:53], -1, 0
	s_xor_b64 s[54:55], s[0:1], -1
	v_readfirstlane_b32 s0, v0
	s_lshl_b32 s86, s0, 11
	s_lshl_b32 s48, s0, 8
	s_add_i32 s0, s15, 0xfffff000
	s_lshr_b32 s0, s0, 3
	s_and_b32 s0, s0, 0x1fffff00
	s_mov_b32 s1, s87
	s_lshl_b64 s[34:35], s[0:1], 13
	s_ashr_i32 s0, s15, 8
	s_ashr_i32 s1, s0, 31
	s_mov_b64 s[44:45], -1
	s_mov_b32 s49, s87
	s_lshl_b32 s7, s42, 8
	v_or_b32_e32 v150, s15, v135
	s_lshl_b64 s[20:21], s[0:1], 18
	s_and_b64 vcc, exec, s[52:53]
	s_movk_i32 s29, 0xfff
	s_cbranch_vccz .LBB0_1252
	s_and_b64 vcc, exec, s[54:55]
	s_cbranch_vccz .LBB0_1249
	v_cmp_lt_i32_e32 vcc, s29, v150
	s_and_saveexec_b64 s[0:1], vcc
	s_xor_b64 s[44:45], exec, s[0:1]
	s_add_u32 s18, s72, s34
	s_addc_u32 s29, s73, s35
	s_lshl_b64 s[0:1], s[86:87], 1
	s_add_u32 s50, s18, s0
	v_and_b32_e32 v0, 0x7cf, v150
	s_addc_u32 s51, s29, s1
	s_movk_i32 s29, 0xfff
	s_or_saveexec_b64 s[44:45], s[44:45]
	v_mov_b64_e32 v[140:141], 0x1000
	v_mov_b64_e32 v[142:143], s[50:51]
	s_xor_b64 exec, exec, s[44:45]
	s_add_u32 s18, s70, s20
	s_addc_u32 s29, s71, s21
	s_lshl_b64 s[0:1], s[48:49], 1
	s_add_u32 s0, s18, s0
	s_addc_u32 s1, s29, s1
	v_and_b32_e32 v0, 0xcf, v150
	s_movk_i32 s29, 0xfff
	v_mov_b64_e32 v[140:141], 0x200
	v_mov_b64_e32 v[142:143], s[0:1]
	s_or_b64 exec, exec, s[44:45]
	v_lshl_add_u64 v[142:143], v[0:1], 1, v[142:143]
	v_mul_u32_u24_e32 v0, v140, v145
	v_lshlrev_b32_e32 v0, 1, v0
	v_cvt_pk_bf16_f32 v141, v126, v127
	v_lshl_add_u64 v[152:153], v[142:143], 0, v[0:1]
	v_lshlrev_b32_e32 v0, 1, v140
	global_store_short v[152:153], v141, off
	v_lshl_add_u64 v[152:153], v[152:153], 0, v[0:1]
	v_cvt_pk_bf16_f32 v151, v128, v129
	global_store_short_d16_hi v[152:153], v141, off
	v_lshl_add_u64 v[152:153], v[152:153], 0, v[0:1]
	global_store_short v[152:153], v151, off
	v_lshl_add_u64 v[152:153], v[152:153], 0, v[0:1]
	global_store_short_d16_hi v[152:153], v151, off
	v_mul_u32_u24_e32 v152, v140, v146
	v_lshlrev_b32_e32 v152, 1, v152
	v_mov_b32_e32 v153, v1
	v_cvt_pk_bf16_f32 v141, v122, v123
	v_lshl_add_u64 v[152:153], v[142:143], 0, v[152:153]
	global_store_short v[152:153], v141, off
	v_lshl_add_u64 v[152:153], v[152:153], 0, v[0:1]
	v_cvt_pk_bf16_f32 v151, v124, v125
	global_store_short_d16_hi v[152:153], v141, off
	v_lshl_add_u64 v[152:153], v[152:153], 0, v[0:1]
	global_store_short v[152:153], v151, off
	v_lshl_add_u64 v[152:153], v[152:153], 0, v[0:1]
	global_store_short_d16_hi v[152:153], v151, off
	v_mul_u32_u24_e32 v152, v140, v147
	v_lshlrev_b32_e32 v152, 1, v152
	v_mov_b32_e32 v153, v1
	v_cvt_pk_bf16_f32 v141, v118, v119
	v_lshl_add_u64 v[152:153], v[142:143], 0, v[152:153]
	global_store_short v[152:153], v141, off
	v_lshl_add_u64 v[152:153], v[152:153], 0, v[0:1]
	v_cvt_pk_bf16_f32 v151, v120, v121
	global_store_short_d16_hi v[152:153], v141, off
	v_lshl_add_u64 v[152:153], v[152:153], 0, v[0:1]
	v_mul_u32_u24_e32 v140, v140, v148
	global_store_short v[152:153], v151, off
	v_lshl_add_u64 v[152:153], v[152:153], 0, v[0:1]
	v_lshlrev_b32_e32 v140, 1, v140
	v_mov_b32_e32 v141, v1
	global_store_short_d16_hi v[152:153], v151, off
	v_cvt_pk_bf16_f32 v151, v114, v115
	v_lshl_add_u64 v[140:141], v[142:143], 0, v[140:141]
	global_store_short v[140:141], v151, off
	v_lshl_add_u64 v[140:141], v[140:141], 0, v[0:1]
	v_cvt_pk_bf16_f32 v152, v116, v117
	global_store_short_d16_hi v[140:141], v151, off
	v_lshl_add_u64 v[140:141], v[140:141], 0, v[0:1]
	global_store_short v[140:141], v152, off
	v_lshl_add_u64 v[140:141], v[140:141], 0, v[0:1]
	global_store_short_d16_hi v[140:141], v152, off
	s_mov_b64 s[44:45], 0

.LBB0_1353:
	v_add_u32_e32 v0, s61, v187
	s_waitcnt vmcnt(0)
	ds_read_b128 v[130:133], v0
	ds_read_b128 v[134:137], v0 offset:1024
	ds_read_b128 v[138:141], v0 offset:2048
	ds_read_b128 v[142:145], v0 offset:3072
	s_add_u32 s0, s20, 0xfffc0080
	s_addc_u32 s1, s21, -1
	s_cmp_eq_u32 s26, 12
	s_cselect_b32 s43, s4, s1
	s_cselect_b32 s42, s8, s0
	s_cselect_b32 s35, s10, s25
	s_cselect_b32 s34, s11, s24
	v_lshl_add_u64 v[194:195], s[20:21], 0, v[174:175]
	s_add_i32 m0, s67, 0xc000
	ds_read_b128 v[146:149], v202
	ds_read_b128 v[150:153], v202 offset:1024
	ds_read_b128 v[154:157], v202 offset:2048
	ds_read_b128 v[158:161], v202 offset:3072
	ds_read_b128 v[178:181], v202 offset:4096
	ds_read_b128 v[182:185], v202 offset:5120
	ds_read_b128 v[204:207], v202 offset:6144
	ds_read_b128 v[208:211], v202 offset:7168
	global_load_lds_dwordx4 v[194:195], off
	v_lshl_add_u64 v[194:195], s[20:21], 0, v[176:177]
	s_add_i32 m0, s67, 0xe000
	s_nop 0
	global_load_lds_dwordx4 v[194:195], off
	s_waitcnt lgkmcnt(8)
	s_barrier
	s_waitcnt lgkmcnt(0)
	s_setprio 1
	s_waitcnt lgkmcnt(0)
	v_mfma_f32_16x16x32_bf16 v[126:129], v[130:133], v[146:149], v[126:129]
	v_mfma_f32_16x16x32_bf16 v[122:125], v[138:141], v[146:149], v[122:125]
	v_mfma_f32_16x16x32_bf16 v[118:121], v[130:133], v[154:157], v[118:121]
	v_mfma_f32_16x16x32_bf16 v[114:117], v[138:141], v[154:157], v[114:117]
	v_mfma_f32_16x16x32_bf16 v[102:105], v[130:133], v[178:181], v[102:105]
	v_mfma_f32_16x16x32_bf16 v[98:101], v[138:141], v[178:181], v[98:101]
	v_mfma_f32_16x16x32_bf16 v[86:89], v[130:133], v[204:207], v[86:89]
	v_mfma_f32_16x16x32_bf16 v[82:85], v[138:141], v[204:207], v[82:85]
	v_mfma_f32_16x16x32_bf16 v[126:129], v[134:137], v[150:153], v[126:129]
	v_mfma_f32_16x16x32_bf16 v[122:125], v[142:145], v[150:153], v[122:125]
	v_mfma_f32_16x16x32_bf16 v[118:121], v[134:137], v[158:161], v[118:121]
	v_mfma_f32_16x16x32_bf16 v[114:117], v[142:145], v[158:161], v[114:117]
	v_mfma_f32_16x16x32_bf16 v[102:105], v[134:137], v[182:185], v[102:105]
	v_mfma_f32_16x16x32_bf16 v[98:101], v[142:145], v[182:185], v[98:101]
	v_mfma_f32_16x16x32_bf16 v[86:89], v[134:137], v[208:211], v[86:89]
	v_mfma_f32_16x16x32_bf16 v[82:85], v[142:145], v[208:211], v[82:85]
	s_setprio 0
	s_barrier
	s_mov_b32 m0, s62
	v_add_u32_e32 v0, s78, v187
	v_lshl_add_u64 v[194:195], s[34:35], 0, v[162:163]
	ds_read_b128 v[212:215], v0
	ds_read_b128 v[216:219], v0 offset:1024
	ds_read_b128 v[220:223], v0 offset:2048
	ds_read_b128 v[242:245], v0 offset:3072
	global_load_lds_dwordx4 v[194:195], off
	v_lshl_add_u64 v[196:197], s[34:35], 0, v[164:165]
	s_mov_b32 m0, s63
	s_nop 0
	global_load_lds_dwordx4 v[196:197], off
	s_barrier
	s_waitcnt lgkmcnt(0)
	s_setprio 1
	s_waitcnt lgkmcnt(0)
	v_mfma_f32_16x16x32_bf16 v[110:113], v[212:215], v[146:149], v[110:113]
	v_mfma_f32_16x16x32_bf16 v[106:109], v[220:223], v[146:149], v[106:109]
	v_mfma_f32_16x16x32_bf16 v[94:97], v[212:215], v[154:157], v[94:97]
	v_mfma_f32_16x16x32_bf16 v[90:93], v[220:223], v[154:157], v[90:93]
	v_mfma_f32_16x16x32_bf16 v[78:81], v[212:215], v[178:181], v[78:81]
	v_mfma_f32_16x16x32_bf16 v[74:77], v[220:223], v[178:181], v[74:77]
	v_mfma_f32_16x16x32_bf16 v[70:73], v[212:215], v[204:207], v[70:73]
	v_mfma_f32_16x16x32_bf16 v[66:69], v[220:223], v[204:207], v[66:69]
	v_mfma_f32_16x16x32_bf16 v[110:113], v[216:219], v[150:153], v[110:113]
	v_mfma_f32_16x16x32_bf16 v[106:109], v[242:245], v[150:153], v[106:109]
	v_mfma_f32_16x16x32_bf16 v[94:97], v[216:219], v[158:161], v[94:97]
	v_mfma_f32_16x16x32_bf16 v[90:93], v[242:245], v[158:161], v[90:93]
	v_mfma_f32_16x16x32_bf16 v[78:81], v[216:219], v[182:185], v[78:81]
	v_mfma_f32_16x16x32_bf16 v[74:77], v[242:245], v[182:185], v[74:77]
	v_mfma_f32_16x16x32_bf16 v[70:73], v[216:219], v[208:211], v[70:73]
	v_mfma_f32_16x16x32_bf16 v[66:69], v[242:245], v[208:211], v[66:69]
	s_setprio 0
	s_mov_b32 m0, s67
	v_lshl_add_u64 v[246:247], s[42:43], 0, v[162:163]
	s_barrier
	ds_read_b128 v[146:149], v202 offset:16384
	ds_read_b128 v[150:153], v202 offset:17408
	ds_read_b128 v[154:157], v202 offset:18432
	ds_read_b128 v[158:161], v202 offset:19456
	ds_read_b128 v[178:181], v202 offset:20480
	ds_read_b128 v[182:185], v202 offset:21504
	ds_read_b128 v[204:207], v202 offset:22528
	ds_read_b128 v[208:211], v202 offset:23552
	global_load_lds_dwordx4 v[246:247], off
	v_lshl_add_u64 v[248:249], s[42:43], 0, v[164:165]
	s_mov_b32 m0, s75
	s_nop 0
	global_load_lds_dwordx4 v[248:249], off
	s_barrier
	s_waitcnt lgkmcnt(0)
	s_setprio 1
	s_waitcnt lgkmcnt(0)
	v_mfma_f32_16x16x32_bf16 v[62:65], v[130:133], v[146:149], v[62:65]
	v_mfma_f32_16x16x32_bf16 v[58:61], v[138:141], v[146:149], v[58:61]
	v_mfma_f32_16x16x32_bf16 v[54:57], v[130:133], v[154:157], v[54:57]
	v_mfma_f32_16x16x32_bf16 v[50:53], v[138:141], v[154:157], v[50:53]
	v_mfma_f32_16x16x32_bf16 v[38:41], v[130:133], v[178:181], v[38:41]
	v_mfma_f32_16x16x32_bf16 v[34:37], v[138:141], v[178:181], v[34:37]
	v_mfma_f32_16x16x32_bf16 v[22:25], v[130:133], v[204:207], v[22:25]
	v_mfma_f32_16x16x32_bf16 v[14:17], v[138:141], v[204:207], v[14:17]
	v_mfma_f32_16x16x32_bf16 v[62:65], v[134:137], v[150:153], v[62:65]
	v_mfma_f32_16x16x32_bf16 v[58:61], v[142:145], v[150:153], v[58:61]
	v_mfma_f32_16x16x32_bf16 v[54:57], v[134:137], v[158:161], v[54:57]
	v_mfma_f32_16x16x32_bf16 v[50:53], v[142:145], v[158:161], v[50:53]
	v_mfma_f32_16x16x32_bf16 v[38:41], v[134:137], v[182:185], v[38:41]
	v_mfma_f32_16x16x32_bf16 v[34:37], v[142:145], v[182:185], v[34:37]
	v_mfma_f32_16x16x32_bf16 v[22:25], v[134:137], v[208:211], v[22:25]
	v_mfma_f32_16x16x32_bf16 v[14:17], v[142:145], v[208:211], v[14:17]
	s_setprio 0
	s_barrier
	s_add_u32 s0, s34, 0x40000
	s_addc_u32 s1, s35, 0
	s_mov_b32 m0, s79
	v_lshl_add_u64 v[130:131], s[0:1], 0, v[162:163]
	global_load_lds_dwordx4 v[130:131], off
	v_lshl_add_u64 v[130:131], s[0:1], 0, v[164:165]
	s_mov_b32 m0, s92
	s_nop 0
	global_load_lds_dwordx4 v[130:131], off
	s_waitcnt vmcnt(6)
	s_barrier
	s_setprio 1
	v_mfma_f32_16x16x32_bf16 v[46:49], v[212:215], v[146:149], v[46:49]
	v_mfma_f32_16x16x32_bf16 v[42:45], v[220:223], v[146:149], v[42:45]
	v_mfma_f32_16x16x32_bf16 v[30:33], v[212:215], v[154:157], v[30:33]
	v_mfma_f32_16x16x32_bf16 v[26:29], v[220:223], v[154:157], v[26:29]
	v_mfma_f32_16x16x32_bf16 v[18:21], v[212:215], v[178:181], v[18:21]
	v_mfma_f32_16x16x32_bf16 v[10:13], v[220:223], v[178:181], v[10:13]
	v_mfma_f32_16x16x32_bf16 v[6:9], v[212:215], v[204:207], v[6:9]
	v_mfma_f32_16x16x32_bf16 v[2:5], v[220:223], v[204:207], v[2:5]
	v_mfma_f32_16x16x32_bf16 v[46:49], v[216:219], v[150:153], v[46:49]
	v_mfma_f32_16x16x32_bf16 v[42:45], v[242:245], v[150:153], v[42:45]
	v_mfma_f32_16x16x32_bf16 v[30:33], v[216:219], v[158:161], v[30:33]
	v_mfma_f32_16x16x32_bf16 v[26:29], v[242:245], v[158:161], v[26:29]
	v_mfma_f32_16x16x32_bf16 v[18:21], v[216:219], v[182:185], v[18:21]
	v_mfma_f32_16x16x32_bf16 v[10:13], v[242:245], v[182:185], v[10:13]
	v_mfma_f32_16x16x32_bf16 v[6:9], v[216:219], v[208:211], v[6:9]
	v_mfma_f32_16x16x32_bf16 v[2:5], v[242:245], v[208:211], v[2:5]
	s_setprio 0
	v_add_u32_e32 v0, s80, v187
	s_barrier
	ds_read_b128 v[130:133], v0
	ds_read_b128 v[134:137], v0 offset:1024
	ds_read_b128 v[138:141], v0 offset:2048
	ds_read_b128 v[142:145], v0 offset:3072
	s_add_u32 s0, s42, 0x40000
	s_addc_u32 s1, s43, 0
	s_mov_b32 m0, s93
	v_lshl_add_u64 v[212:213], s[0:1], 0, v[162:163]
	ds_read_b128 v[146:149], v202 offset:32768
	ds_read_b128 v[150:153], v202 offset:33792
	ds_read_b128 v[154:157], v202 offset:34816
	ds_read_b128 v[158:161], v202 offset:35840
	ds_read_b128 v[178:181], v202 offset:36864
	ds_read_b128 v[182:185], v202 offset:37888
	ds_read_b128 v[204:207], v202 offset:38912
	ds_read_b128 v[208:211], v202 offset:39936
	global_load_lds_dwordx4 v[212:213], off
	v_lshl_add_u64 v[212:213], s[0:1], 0, v[164:165]
	s_mov_b32 m0, s60
	s_nop 0
	global_load_lds_dwordx4 v[212:213], off
	s_waitcnt lgkmcnt(8)
	s_barrier
	s_waitcnt lgkmcnt(0)
	s_setprio 1
	s_waitcnt lgkmcnt(0)
	v_mfma_f32_16x16x32_bf16 v[126:129], v[130:133], v[146:149], v[126:129]
	v_mfma_f32_16x16x32_bf16 v[122:125], v[138:141], v[146:149], v[122:125]
	v_mfma_f32_16x16x32_bf16 v[118:121], v[130:133], v[154:157], v[118:121]
	v_mfma_f32_16x16x32_bf16 v[114:117], v[138:141], v[154:157], v[114:117]
	v_mfma_f32_16x16x32_bf16 v[102:105], v[130:133], v[178:181], v[102:105]
	v_mfma_f32_16x16x32_bf16 v[98:101], v[138:141], v[178:181], v[98:101]
	v_mfma_f32_16x16x32_bf16 v[86:89], v[130:133], v[204:207], v[86:89]
	v_mfma_f32_16x16x32_bf16 v[82:85], v[138:141], v[204:207], v[82:85]
	v_mfma_f32_16x16x32_bf16 v[126:129], v[134:137], v[150:153], v[126:129]
	v_mfma_f32_16x16x32_bf16 v[122:125], v[142:145], v[150:153], v[122:125]
	v_mfma_f32_16x16x32_bf16 v[118:121], v[134:137], v[158:161], v[118:121]
	v_mfma_f32_16x16x32_bf16 v[114:117], v[142:145], v[158:161], v[114:117]
	v_mfma_f32_16x16x32_bf16 v[102:105], v[134:137], v[182:185], v[102:105]
	v_mfma_f32_16x16x32_bf16 v[98:101], v[142:145], v[182:185], v[98:101]
	v_mfma_f32_16x16x32_bf16 v[86:89], v[134:137], v[208:211], v[86:89]
	v_mfma_f32_16x16x32_bf16 v[82:85], v[142:145], v[208:211], v[82:85]
	s_setprio 0
	s_barrier
	s_mov_b32 m0, s81
	v_add_u32_e32 v0, s14, v187
	v_lshl_add_u64 v[194:195], v[194:195], 0, s[88:89]
	ds_read_b128 v[212:215], v0
	ds_read_b128 v[216:219], v0 offset:1024
	ds_read_b128 v[220:223], v0 offset:2048
	ds_read_b128 v[242:245], v0 offset:3072
	global_load_lds_dwordx4 v[194:195], off
	v_lshl_add_u64 v[194:195], v[196:197], 0, s[88:89]
	s_mov_b32 m0, s68
	s_nop 0
	global_load_lds_dwordx4 v[194:195], off
	s_barrier
	s_waitcnt lgkmcnt(0)
	s_setprio 1
	s_waitcnt lgkmcnt(0)
	v_mfma_f32_16x16x32_bf16 v[110:113], v[212:215], v[146:149], v[110:113]
	v_mfma_f32_16x16x32_bf16 v[106:109], v[220:223], v[146:149], v[106:109]
	v_mfma_f32_16x16x32_bf16 v[94:97], v[212:215], v[154:157], v[94:97]
	v_mfma_f32_16x16x32_bf16 v[90:93], v[220:223], v[154:157], v[90:93]
	v_mfma_f32_16x16x32_bf16 v[78:81], v[212:215], v[178:181], v[78:81]
	v_mfma_f32_16x16x32_bf16 v[74:77], v[220:223], v[178:181], v[74:77]
	v_mfma_f32_16x16x32_bf16 v[70:73], v[212:215], v[204:207], v[70:73]
	v_mfma_f32_16x16x32_bf16 v[66:69], v[220:223], v[204:207], v[66:69]
	v_mfma_f32_16x16x32_bf16 v[110:113], v[216:219], v[150:153], v[110:113]
	v_mfma_f32_16x16x32_bf16 v[106:109], v[242:245], v[150:153], v[106:109]
	v_mfma_f32_16x16x32_bf16 v[94:97], v[216:219], v[158:161], v[94:97]
	v_mfma_f32_16x16x32_bf16 v[90:93], v[242:245], v[158:161], v[90:93]
	v_mfma_f32_16x16x32_bf16 v[78:81], v[216:219], v[182:185], v[78:81]
	v_mfma_f32_16x16x32_bf16 v[74:77], v[242:245], v[182:185], v[74:77]
	v_mfma_f32_16x16x32_bf16 v[70:73], v[216:219], v[208:211], v[70:73]
	v_mfma_f32_16x16x32_bf16 v[66:69], v[242:245], v[208:211], v[66:69]
	s_setprio 0
	s_mov_b32 m0, s69
	v_lshl_add_u64 v[194:195], v[246:247], 0, s[88:89]
	s_barrier
	ds_read_b128 v[146:149], v202 offset:49152
	ds_read_b128 v[150:153], v202 offset:50176
	ds_read_b128 v[154:157], v202 offset:51200
	ds_read_b128 v[158:161], v202 offset:52224
	ds_read_b128 v[178:181], v202 offset:53248
	ds_read_b128 v[182:185], v202 offset:54272
	ds_read_b128 v[204:207], v202 offset:55296
	ds_read_b128 v[208:211], v202 offset:56320
	global_load_lds_dwordx4 v[194:195], off
	v_lshl_add_u64 v[194:195], v[248:249], 0, s[88:89]
	s_mov_b32 m0, s19
	s_nop 0
	global_load_lds_dwordx4 v[194:195], off
	s_barrier
	s_waitcnt lgkmcnt(0)
	s_setprio 1
	s_waitcnt lgkmcnt(0)
	v_mfma_f32_16x16x32_bf16 v[62:65], v[130:133], v[146:149], v[62:65]
	v_mfma_f32_16x16x32_bf16 v[58:61], v[138:141], v[146:149], v[58:61]
	v_mfma_f32_16x16x32_bf16 v[54:57], v[130:133], v[154:157], v[54:57]
	v_mfma_f32_16x16x32_bf16 v[50:53], v[138:141], v[154:157], v[50:53]
	v_mfma_f32_16x16x32_bf16 v[38:41], v[130:133], v[178:181], v[38:41]
	v_mfma_f32_16x16x32_bf16 v[34:37], v[138:141], v[178:181], v[34:37]
	v_mfma_f32_16x16x32_bf16 v[22:25], v[130:133], v[204:207], v[22:25]
	v_mfma_f32_16x16x32_bf16 v[14:17], v[138:141], v[204:207], v[14:17]
	v_mfma_f32_16x16x32_bf16 v[62:65], v[134:137], v[150:153], v[62:65]
	v_mfma_f32_16x16x32_bf16 v[58:61], v[142:145], v[150:153], v[58:61]
	v_mfma_f32_16x16x32_bf16 v[54:57], v[134:137], v[158:161], v[54:57]
	v_mfma_f32_16x16x32_bf16 v[50:53], v[142:145], v[158:161], v[50:53]
	v_mfma_f32_16x16x32_bf16 v[38:41], v[134:137], v[182:185], v[38:41]
	v_mfma_f32_16x16x32_bf16 v[34:37], v[142:145], v[182:185], v[34:37]
	v_mfma_f32_16x16x32_bf16 v[22:25], v[134:137], v[208:211], v[22:25]
	v_mfma_f32_16x16x32_bf16 v[14:17], v[142:145], v[208:211], v[14:17]
	s_setprio 0
	s_barrier
	s_add_u32 s0, s34, 0x40080
	s_addc_u32 s1, s35, 0
	s_mov_b32 m0, s15
	v_lshl_add_u64 v[130:131], s[0:1], 0, v[162:163]
	global_load_lds_dwordx4 v[130:131], off
	v_lshl_add_u64 v[130:131], s[0:1], 0, v[164:165]
	s_mov_b32 m0, s16
	s_nop 0
	global_load_lds_dwordx4 v[130:131], off
	s_waitcnt vmcnt(6)
	s_barrier
	s_setprio 1
	v_mfma_f32_16x16x32_bf16 v[46:49], v[212:215], v[146:149], v[46:49]
	v_mfma_f32_16x16x32_bf16 v[42:45], v[220:223], v[146:149], v[42:45]
	v_mfma_f32_16x16x32_bf16 v[30:33], v[212:215], v[154:157], v[30:33]
	v_mfma_f32_16x16x32_bf16 v[26:29], v[220:223], v[154:157], v[26:29]
	v_mfma_f32_16x16x32_bf16 v[18:21], v[212:215], v[178:181], v[18:21]
	v_mfma_f32_16x16x32_bf16 v[10:13], v[220:223], v[178:181], v[10:13]
	v_mfma_f32_16x16x32_bf16 v[6:9], v[212:215], v[204:207], v[6:9]
	v_mfma_f32_16x16x32_bf16 v[2:5], v[220:223], v[204:207], v[2:5]
	v_mfma_f32_16x16x32_bf16 v[46:49], v[216:219], v[150:153], v[46:49]
	v_mfma_f32_16x16x32_bf16 v[42:45], v[242:245], v[150:153], v[42:45]
	v_mfma_f32_16x16x32_bf16 v[30:33], v[216:219], v[158:161], v[30:33]
	v_mfma_f32_16x16x32_bf16 v[26:29], v[242:245], v[158:161], v[26:29]
	v_mfma_f32_16x16x32_bf16 v[18:21], v[216:219], v[182:185], v[18:21]
	v_mfma_f32_16x16x32_bf16 v[10:13], v[242:245], v[182:185], v[10:13]
	v_mfma_f32_16x16x32_bf16 v[6:9], v[216:219], v[208:211], v[6:9]
	v_mfma_f32_16x16x32_bf16 v[2:5], v[242:245], v[208:211], v[2:5]
	s_setprio 0
	s_add_i32 s26, s26, 2
	s_add_u32 s20, s20, 0x100
	s_addc_u32 s21, s21, 0
	s_add_u32 s24, s24, 0x100
	s_addc_u32 s25, s25, 0
	s_cmp_gt_u32 s26, 13
	s_barrier
	s_cbranch_scc0 .LBB0_1353
	v_readfirstlane_b32 s98, v191
	s_cmpk_gt_u32 s98, 0xff
	s_cbranch_scc1 .Lrl_e0_1353
	s_barrier
.Lrl_e0_1353:
	s_cmp_lt_i32 s66, 3
	s_mov_b64 s[20:21], -1
	s_cbranch_scc0 .LBB0_1556
	s_cmp_lg_u32 s66, 2
	s_cselect_b64 s[34:35], -1, 0
	s_cmp_eq_u32 s66, 2
	s_mov_b32 s24, s45
	s_mov_b32 s18, s44
	s_cselect_b64 s[0:1], -1, 0
	v_readlane_b32 s44, v254, 5
	s_and_b64 s[10:11], s[0:1], exec
	v_readlane_b32 s46, v254, 7
	v_readlane_b32 s45, v254, 6
	v_readlane_b32 s47, v254, 8
	s_cselect_b32 s8, s46, s44
	s_cselect_b32 s4, s47, s45
	s_add_u32 s10, s8, s2
	s_addc_u32 s11, s4, s3
	v_lshlrev_b32_e32 v178, 2, v166
	global_load_dwordx4 v[138:141], v178, s[10:11] offset:16
	global_load_dwordx4 v[142:145], v178, s[10:11]
	global_load_dwordx4 v[130:133], v178, s[10:11] offset:144
	global_load_dwordx4 v[134:137], v178, s[10:11] offset:128
	v_readlane_b32 s10, v254, 26
	s_lshl_b32 s26, s74, 8
	v_readlane_b32 s11, v254, 27
	s_add_i32 s26, s26, s30
	s_and_b64 s[20:21], s[0:1], s[10:11]
	v_or_b32_e32 v180, s26, v167
	v_mov_b64_e32 v[148:149], v[128:129]
	v_mov_b64_e32 v[152:153], v[124:125]
	v_mov_b64_e32 v[156:157], v[112:113]
	v_cmp_lt_i32_e64 s[42:43], s29, v180
	v_cmp_gt_i32_e64 s[46:47], s33, v180
	v_bitop3_b32 v182, s26, v231, v167 bitop3:0xc8
	s_and_b64 vcc, exec, s[20:21]
	v_xor_b32_e32 v205, 16, v224
	v_add_u32_e32 v203, 64, v225
	v_xor_b32_e32 v204, 32, v224
	v_mov_b32_e32 v161, v109
	v_mov_b32_e32 v160, v108
	v_mov_b32_e32 v159, v107
	v_mov_b32_e32 v158, v106
	v_mov_b64_e32 v[146:147], v[126:127]
	v_mov_b64_e32 v[150:151], v[122:123]
	v_mov_b64_e32 v[154:155], v[110:111]
	s_cbranch_vccnz .LBB0_1365
	v_lshl_or_b32 v222, v182, 6, v166
	v_lshlrev_b32_e32 v222, 2, v222
	s_and_saveexec_b64 vcc, s[42:43]
	s_cbranch_execz .Lrope_skip_0
	global_load_dwordx4 v[214:217], v222, s[84:85]
	global_load_dwordx4 v[218:221], v222, s[84:85] offset:16
	global_load_dwordx4 v[242:245], v222, s[84:85] offset:128
	global_load_dwordx4 v[246:249], v222, s[84:85] offset:144
